# K-loops: fragment ds_reads reordered by first use; the last reads of each phase are waited for mid-cluster (counted lgkmcnt) so the MFMA cluster starts while they are in flight
# baseline (speedup 1.0000x reference)
.LBB0_122:
	v_mov_b64_e32 v[0:1], 0x180
	s_ashr_i32 s15, s14, 31
	v_cmp_lt_i64_e32 vcc, s[16:17], v[0:1]
	s_lshl_b64 s[16:17], s[14:15], 19
	s_add_u32 s16, s30, s16
	s_addc_u32 s17, s31, s17
	s_and_b64 s[18:19], vcc, exec
	s_cselect_b32 s7, s17, s21
	s_cselect_b32 s9, s16, s20
	s_ashr_i32 s13, s12, 31
	s_lshl_b64 s[18:19], s[12:13], 19
	s_add_u32 s18, s34, s18
	s_addc_u32 s19, s35, s19
	s_and_b64 s[22:23], vcc, exec
	s_cselect_b32 s13, s19, s3
	s_cselect_b32 s15, s18, s2
	s_add_u32 s20, s20, 0x40080
	s_addc_u32 s21, s21, 0
	s_add_u32 s50, s2, 0x100
	s_addc_u32 s51, s3, 0
	s_mov_b32 s52, -2
	s_add_u32 s2, s20, 0xfffc0080
	s_addc_u32 s3, s21, -1
	ds_read_b128 v[24:27], v164
	ds_read_b128 v[32:35], v164 offset:2048
	ds_read_b128 v[28:31], v164 offset:1024
	ds_read_b128 v[36:39], v164 offset:3072
	s_cmp_eq_u32 s52, 12
	s_cselect_b32 s23, s7, s3
	s_cselect_b32 s22, s9, s2
	s_cselect_b32 s3, s13, s51
	s_cselect_b32 s2, s15, s50
	s_add_i32 m0, s37, 0xc000
	ds_read_b128 v[154:157], v165
	ds_read_b128 v[180:183], v165 offset:2048
	ds_read_b128 v[188:191], v165 offset:4096
	ds_read_b128 v[196:199], v165 offset:6144
	ds_read_b128 v[158:161], v165 offset:1024
	ds_read_b128 v[184:187], v165 offset:3072
	ds_read_b128 v[192:195], v165 offset:5120
	global_load_lds_dwordx4 v150, s[20:21]
	s_add_i32 m0, s37, 0xe000
	ds_read_b128 v[200:203], v165 offset:7168
	global_load_lds_dwordx4 v152, s[20:21]
	s_waitcnt lgkmcnt(8)
	s_barrier
	s_waitcnt lgkmcnt(4)
	v_mfma_f32_16x16x32_bf16 v[140:143], v[24:27], v[154:157], 0
	v_mfma_f32_16x16x32_bf16 v[136:139], v[32:35], v[154:157], 0
	v_mfma_f32_16x16x32_bf16 v[124:127], v[24:27], v[180:183], 0
	v_mfma_f32_16x16x32_bf16 v[120:123], v[32:35], v[180:183], 0
	v_mfma_f32_16x16x32_bf16 v[108:111], v[24:27], v[188:191], 0
	v_mfma_f32_16x16x32_bf16 v[104:107], v[32:35], v[188:191], 0
	v_mfma_f32_16x16x32_bf16 v[92:95], v[24:27], v[196:199], 0
	v_mfma_f32_16x16x32_bf16 v[88:91], v[32:35], v[196:199], 0
	s_waitcnt lgkmcnt(0)
	v_mfma_f32_16x16x32_bf16 v[140:143], v[28:31], v[158:161], v[140:143]
	v_mfma_f32_16x16x32_bf16 v[136:139], v[36:39], v[158:161], v[136:139]
	v_mfma_f32_16x16x32_bf16 v[124:127], v[28:31], v[184:187], v[124:127]
	v_mfma_f32_16x16x32_bf16 v[120:123], v[36:39], v[184:187], v[120:123]
	v_mfma_f32_16x16x32_bf16 v[108:111], v[28:31], v[192:195], v[108:111]
	v_mfma_f32_16x16x32_bf16 v[104:107], v[36:39], v[192:195], v[104:107]
	v_mfma_f32_16x16x32_bf16 v[92:95], v[28:31], v[200:203], v[92:95]
	v_mfma_f32_16x16x32_bf16 v[88:91], v[36:39], v[200:203], v[88:91]
	s_barrier
	ds_read_b128 v[204:207], v164 offset:16384
	ds_read_b128 v[212:215], v164 offset:18432
	ds_read_b128 v[208:211], v164 offset:17408
	s_add_i32 m0, s36, 0x10000
	ds_read_b128 v[216:219], v164 offset:19456
	global_load_lds_dwordx4 v168, s[2:3]
	s_add_i32 m0, s36, 0x12000
	s_add_u32 s98, s2, 0x80
	s_addc_u32 s99, s3, 0
	global_load_lds_dwordx4 v148, s[2:3]
	s_barrier
	s_waitcnt lgkmcnt(2)
	v_mfma_f32_16x16x32_bf16 v[132:135], v[204:207], v[154:157], 0
	v_mfma_f32_16x16x32_bf16 v[128:131], v[212:215], v[154:157], 0
	v_mfma_f32_16x16x32_bf16 v[116:119], v[204:207], v[180:183], 0
	v_mfma_f32_16x16x32_bf16 v[112:115], v[212:215], v[180:183], 0
	v_mfma_f32_16x16x32_bf16 v[100:103], v[204:207], v[188:191], 0
	v_mfma_f32_16x16x32_bf16 v[96:99], v[212:215], v[188:191], 0
	v_mfma_f32_16x16x32_bf16 v[84:87], v[204:207], v[196:199], 0
	v_mfma_f32_16x16x32_bf16 v[80:83], v[212:215], v[196:199], 0
	s_waitcnt lgkmcnt(0)
	v_mfma_f32_16x16x32_bf16 v[132:135], v[208:211], v[158:161], v[132:135]
	v_mfma_f32_16x16x32_bf16 v[128:131], v[216:219], v[158:161], v[128:131]
	v_mfma_f32_16x16x32_bf16 v[116:119], v[208:211], v[184:187], v[116:119]
	v_mfma_f32_16x16x32_bf16 v[112:115], v[216:219], v[184:187], v[112:115]
	v_mfma_f32_16x16x32_bf16 v[100:103], v[208:211], v[192:195], v[100:103]
	v_mfma_f32_16x16x32_bf16 v[96:99], v[216:219], v[192:195], v[96:99]
	v_mfma_f32_16x16x32_bf16 v[84:87], v[208:211], v[200:203], v[84:87]
	v_mfma_f32_16x16x32_bf16 v[80:83], v[216:219], v[200:203], v[80:83]
	s_mov_b32 m0, s37
	s_add_u32 s100, s22, 0x80
	s_addc_u32 s101, s23, 0
	s_barrier
	ds_read_b128 v[154:157], v165 offset:16384
	ds_read_b128 v[180:183], v165 offset:18432
	ds_read_b128 v[188:191], v165 offset:20480
	ds_read_b128 v[196:199], v165 offset:22528
	ds_read_b128 v[158:161], v165 offset:17408
	ds_read_b128 v[184:187], v165 offset:19456
	ds_read_b128 v[192:195], v165 offset:21504
	global_load_lds_dwordx4 v144, s[22:23]
	s_mov_b32 m0, s38
	ds_read_b128 v[200:203], v165 offset:23552
	global_load_lds_dwordx4 v146, s[22:23]
	s_barrier
	s_waitcnt lgkmcnt(4)
	v_mfma_f32_16x16x32_bf16 v[76:79], v[24:27], v[154:157], 0
	v_mfma_f32_16x16x32_bf16 v[72:75], v[32:35], v[154:157], 0
	v_mfma_f32_16x16x32_bf16 v[60:63], v[24:27], v[180:183], 0
	v_mfma_f32_16x16x32_bf16 v[56:59], v[32:35], v[180:183], 0
	v_mfma_f32_16x16x32_bf16 v[44:47], v[24:27], v[188:191], 0
	v_mfma_f32_16x16x32_bf16 v[40:43], v[32:35], v[188:191], 0
	v_mfma_f32_16x16x32_bf16 v[12:15], v[24:27], v[196:199], 0
	v_mfma_f32_16x16x32_bf16 v[8:11], v[32:35], v[196:199], 0
	s_waitcnt lgkmcnt(0)
	v_mfma_f32_16x16x32_bf16 v[76:79], v[28:31], v[158:161], v[76:79]
	v_mfma_f32_16x16x32_bf16 v[72:75], v[36:39], v[158:161], v[72:75]
	v_mfma_f32_16x16x32_bf16 v[60:63], v[28:31], v[184:187], v[60:63]
	v_mfma_f32_16x16x32_bf16 v[56:59], v[36:39], v[184:187], v[56:59]
	v_mfma_f32_16x16x32_bf16 v[44:47], v[28:31], v[192:195], v[44:47]
	v_mfma_f32_16x16x32_bf16 v[40:43], v[36:39], v[192:195], v[40:43]
	v_mfma_f32_16x16x32_bf16 v[12:15], v[28:31], v[200:203], v[12:15]
	v_mfma_f32_16x16x32_bf16 v[8:11], v[36:39], v[200:203], v[8:11]
	s_barrier
	s_add_i32 m0, s36, 0x14000
	s_add_u32 s54, s2, 0x40000
	s_addc_u32 s55, s3, 0
	global_load_lds_dwordx4 v168, s[54:55]
	s_add_i32 m0, s36, 0x16000
	s_add_u32 s22, s22, 0x40000
	s_addc_u32 s23, s23, 0
	global_load_lds_dwordx4 v148, s[54:55]
	s_waitcnt vmcnt(6)
	s_barrier
	v_mfma_f32_16x16x32_bf16 v[20:23], v[204:207], v[188:191], 0
	v_mfma_f32_16x16x32_bf16 v[16:19], v[212:215], v[188:191], 0
	v_mfma_f32_16x16x32_bf16 v[4:7], v[204:207], v[196:199], 0
	v_mfma_f32_16x16x32_bf16 v[0:3], v[212:215], v[196:199], 0
	v_mfma_f32_16x16x32_bf16 v[24:27], v[204:207], v[154:157], 0
	v_mfma_f32_16x16x32_bf16 v[28:31], v[212:215], v[154:157], 0
	v_mfma_f32_16x16x32_bf16 v[32:35], v[204:207], v[180:183], 0
	v_mfma_f32_16x16x32_bf16 v[36:39], v[212:215], v[180:183], 0
	v_mfma_f32_16x16x32_bf16 v[20:23], v[208:211], v[192:195], v[20:23]
	v_mfma_f32_16x16x32_bf16 v[16:19], v[216:219], v[192:195], v[16:19]
	v_mfma_f32_16x16x32_bf16 v[4:7], v[208:211], v[200:203], v[4:7]
	v_mfma_f32_16x16x32_bf16 v[0:3], v[216:219], v[200:203], v[0:3]
	v_mfma_f32_16x16x32_bf16 v[24:27], v[208:211], v[158:161], v[24:27]
	v_mfma_f32_16x16x32_bf16 v[28:31], v[216:219], v[158:161], v[28:31]
	v_mfma_f32_16x16x32_bf16 v[32:35], v[208:211], v[184:187], v[32:35]
	v_mfma_f32_16x16x32_bf16 v[36:39], v[216:219], v[184:187], v[36:39]
	s_barrier
	ds_read_b128 v[48:51], v164 offset:32768
	ds_read_b128 v[64:67], v164 offset:34816
	ds_read_b128 v[52:55], v164 offset:33792
	ds_read_b128 v[68:71], v164 offset:35840
	s_mov_b32 m0, s39
	ds_read_b128 v[154:157], v165 offset:32768
	ds_read_b128 v[180:183], v165 offset:34816
	ds_read_b128 v[188:191], v165 offset:36864
	ds_read_b128 v[196:199], v165 offset:38912
	ds_read_b128 v[158:161], v165 offset:33792
	ds_read_b128 v[184:187], v165 offset:35840
	ds_read_b128 v[192:195], v165 offset:37888
	global_load_lds_dwordx4 v144, s[22:23]
	s_mov_b32 m0, s40
	ds_read_b128 v[200:203], v165 offset:39936
	global_load_lds_dwordx4 v146, s[22:23]
	s_waitcnt lgkmcnt(8)
	s_barrier
	s_waitcnt lgkmcnt(4)
	v_mfma_f32_16x16x32_bf16 v[140:143], v[48:51], v[154:157], v[140:143]
	v_mfma_f32_16x16x32_bf16 v[136:139], v[64:67], v[154:157], v[136:139]
	v_mfma_f32_16x16x32_bf16 v[124:127], v[48:51], v[180:183], v[124:127]
	v_mfma_f32_16x16x32_bf16 v[120:123], v[64:67], v[180:183], v[120:123]
	v_mfma_f32_16x16x32_bf16 v[108:111], v[48:51], v[188:191], v[108:111]
	v_mfma_f32_16x16x32_bf16 v[104:107], v[64:67], v[188:191], v[104:107]
	v_mfma_f32_16x16x32_bf16 v[92:95], v[48:51], v[196:199], v[92:95]
	v_mfma_f32_16x16x32_bf16 v[88:91], v[64:67], v[196:199], v[88:91]
	s_waitcnt lgkmcnt(0)
	v_mfma_f32_16x16x32_bf16 v[140:143], v[52:55], v[158:161], v[140:143]
	v_mfma_f32_16x16x32_bf16 v[136:139], v[68:71], v[158:161], v[136:139]
	v_mfma_f32_16x16x32_bf16 v[124:127], v[52:55], v[184:187], v[124:127]
	v_mfma_f32_16x16x32_bf16 v[120:123], v[68:71], v[184:187], v[120:123]
	v_mfma_f32_16x16x32_bf16 v[108:111], v[52:55], v[192:195], v[108:111]
	v_mfma_f32_16x16x32_bf16 v[104:107], v[68:71], v[192:195], v[104:107]
	v_mfma_f32_16x16x32_bf16 v[92:95], v[52:55], v[200:203], v[92:95]
	v_mfma_f32_16x16x32_bf16 v[88:91], v[68:71], v[200:203], v[88:91]
	s_barrier
	s_add_i32 m0, s36, 0x18000
	ds_read_b128 v[204:207], v164 offset:49152
	ds_read_b128 v[212:215], v164 offset:51200
	ds_read_b128 v[208:211], v164 offset:50176
	global_load_lds_dwordx4 v168, s[98:99]
	s_add_i32 m0, s36, 0x1a000
	ds_read_b128 v[216:219], v164 offset:52224
	global_load_lds_dwordx4 v148, s[98:99]
	s_barrier
	s_waitcnt lgkmcnt(2)
	v_mfma_f32_16x16x32_bf16 v[132:135], v[204:207], v[154:157], v[132:135]
	v_mfma_f32_16x16x32_bf16 v[128:131], v[212:215], v[154:157], v[128:131]
	v_mfma_f32_16x16x32_bf16 v[116:119], v[204:207], v[180:183], v[116:119]
	v_mfma_f32_16x16x32_bf16 v[112:115], v[212:215], v[180:183], v[112:115]
	v_mfma_f32_16x16x32_bf16 v[100:103], v[204:207], v[188:191], v[100:103]
	v_mfma_f32_16x16x32_bf16 v[96:99], v[212:215], v[188:191], v[96:99]
	v_mfma_f32_16x16x32_bf16 v[84:87], v[204:207], v[196:199], v[84:87]
	v_mfma_f32_16x16x32_bf16 v[80:83], v[212:215], v[196:199], v[80:83]
	s_waitcnt lgkmcnt(0)
	v_mfma_f32_16x16x32_bf16 v[132:135], v[208:211], v[158:161], v[132:135]
	v_mfma_f32_16x16x32_bf16 v[128:131], v[216:219], v[158:161], v[128:131]
	v_mfma_f32_16x16x32_bf16 v[116:119], v[208:211], v[184:187], v[116:119]
	v_mfma_f32_16x16x32_bf16 v[112:115], v[216:219], v[184:187], v[112:115]
	v_mfma_f32_16x16x32_bf16 v[100:103], v[208:211], v[192:195], v[100:103]
	v_mfma_f32_16x16x32_bf16 v[96:99], v[216:219], v[192:195], v[96:99]
	v_mfma_f32_16x16x32_bf16 v[84:87], v[208:211], v[200:203], v[84:87]
	v_mfma_f32_16x16x32_bf16 v[80:83], v[216:219], v[200:203], v[80:83]
	s_mov_b32 m0, s45
	s_barrier
	ds_read_b128 v[154:157], v165 offset:49152
	ds_read_b128 v[180:183], v165 offset:51200
	ds_read_b128 v[188:191], v165 offset:53248
	ds_read_b128 v[196:199], v165 offset:55296
	ds_read_b128 v[158:161], v165 offset:50176
	ds_read_b128 v[184:187], v165 offset:52224
	ds_read_b128 v[192:195], v165 offset:54272
	global_load_lds_dwordx4 v144, s[100:101]
	s_mov_b32 m0, s46
	ds_read_b128 v[200:203], v165 offset:56320
	global_load_lds_dwordx4 v146, s[100:101]
	s_barrier
	s_waitcnt lgkmcnt(4)
	v_mfma_f32_16x16x32_bf16 v[76:79], v[48:51], v[154:157], v[76:79]
	v_mfma_f32_16x16x32_bf16 v[72:75], v[64:67], v[154:157], v[72:75]
	v_mfma_f32_16x16x32_bf16 v[60:63], v[48:51], v[180:183], v[60:63]
	v_mfma_f32_16x16x32_bf16 v[56:59], v[64:67], v[180:183], v[56:59]
	v_mfma_f32_16x16x32_bf16 v[44:47], v[48:51], v[188:191], v[44:47]
	v_mfma_f32_16x16x32_bf16 v[40:43], v[64:67], v[188:191], v[40:43]
	v_mfma_f32_16x16x32_bf16 v[12:15], v[48:51], v[196:199], v[12:15]
	v_mfma_f32_16x16x32_bf16 v[8:11], v[64:67], v[196:199], v[8:11]
	s_waitcnt lgkmcnt(0)
	v_mfma_f32_16x16x32_bf16 v[76:79], v[52:55], v[158:161], v[76:79]
	v_mfma_f32_16x16x32_bf16 v[72:75], v[68:71], v[158:161], v[72:75]
	v_mfma_f32_16x16x32_bf16 v[60:63], v[52:55], v[184:187], v[60:63]
	v_mfma_f32_16x16x32_bf16 v[56:59], v[68:71], v[184:187], v[56:59]
	v_mfma_f32_16x16x32_bf16 v[44:47], v[52:55], v[192:195], v[44:47]
	v_mfma_f32_16x16x32_bf16 v[40:43], v[68:71], v[192:195], v[40:43]
	v_mfma_f32_16x16x32_bf16 v[12:15], v[52:55], v[200:203], v[12:15]
	v_mfma_f32_16x16x32_bf16 v[8:11], v[68:71], v[200:203], v[8:11]
	s_barrier
	s_add_i32 m0, s36, 0x1c000
	s_add_u32 s2, s2, 0x40080
	s_addc_u32 s3, s3, 0
	global_load_lds_dwordx4 v168, s[2:3]
	s_add_i32 m0, s36, 0x1e000
	s_add_i32 s52, s52, 2
	global_load_lds_dwordx4 v148, s[2:3]
	s_waitcnt vmcnt(6)
	s_barrier
	v_mfma_f32_16x16x32_bf16 v[24:27], v[204:207], v[154:157], v[24:27]
	v_mfma_f32_16x16x32_bf16 v[68:71], v[208:211], v[158:161], v[24:27]
	v_mfma_f32_16x16x32_bf16 v[24:27], v[212:215], v[154:157], v[28:31]
	v_mfma_f32_16x16x32_bf16 v[64:67], v[216:219], v[158:161], v[24:27]
	v_mfma_f32_16x16x32_bf16 v[24:27], v[204:207], v[180:183], v[32:35]
	v_mfma_f32_16x16x32_bf16 v[52:55], v[208:211], v[184:187], v[24:27]
	v_mfma_f32_16x16x32_bf16 v[24:27], v[212:215], v[180:183], v[36:39]
	v_mfma_f32_16x16x32_bf16 v[20:23], v[204:207], v[188:191], v[20:23]
	v_mfma_f32_16x16x32_bf16 v[16:19], v[212:215], v[188:191], v[16:19]
	v_mfma_f32_16x16x32_bf16 v[4:7], v[204:207], v[196:199], v[4:7]
	v_mfma_f32_16x16x32_bf16 v[0:3], v[212:215], v[196:199], v[0:3]
	v_mfma_f32_16x16x32_bf16 v[48:51], v[216:219], v[184:187], v[24:27]
	v_mfma_f32_16x16x32_bf16 v[20:23], v[208:211], v[192:195], v[20:23]
	v_mfma_f32_16x16x32_bf16 v[16:19], v[216:219], v[192:195], v[16:19]
	v_mfma_f32_16x16x32_bf16 v[4:7], v[208:211], v[200:203], v[4:7]
	v_mfma_f32_16x16x32_bf16 v[0:3], v[216:219], v[200:203], v[0:3]
	s_add_u32 s20, s20, 0x100
	s_addc_u32 s21, s21, 0
	s_add_u32 s50, s50, 0x100
	s_addc_u32 s51, s51, 0
	s_cmp_gt_u32 s52, 13
	s_barrier
.LBB0_123:
	s_add_u32 s2, s20, 0xfffc0080
	s_addc_u32 s3, s21, -1
	ds_read_b128 v[24:27], v164
	ds_read_b128 v[32:35], v164 offset:2048
	ds_read_b128 v[28:31], v164 offset:1024
	ds_read_b128 v[36:39], v164 offset:3072
	s_cmp_eq_u32 s52, 12
	s_cselect_b32 s23, s7, s3
	s_cselect_b32 s22, s9, s2
	s_cselect_b32 s3, s13, s51
	s_cselect_b32 s2, s15, s50
	s_add_i32 m0, s37, 0xc000
	ds_read_b128 v[154:157], v165
	ds_read_b128 v[180:183], v165 offset:2048
	ds_read_b128 v[188:191], v165 offset:4096
	ds_read_b128 v[196:199], v165 offset:6144
	ds_read_b128 v[158:161], v165 offset:1024
	ds_read_b128 v[184:187], v165 offset:3072
	ds_read_b128 v[192:195], v165 offset:5120
	global_load_lds_dwordx4 v150, s[20:21]
	s_add_i32 m0, s37, 0xe000
	ds_read_b128 v[200:203], v165 offset:7168
	global_load_lds_dwordx4 v152, s[20:21]
	s_waitcnt lgkmcnt(8)
	s_barrier
	s_waitcnt lgkmcnt(4)
	v_mfma_f32_16x16x32_bf16 v[140:143], v[24:27], v[154:157], v[140:143]
	v_mfma_f32_16x16x32_bf16 v[136:139], v[32:35], v[154:157], v[136:139]
	v_mfma_f32_16x16x32_bf16 v[124:127], v[24:27], v[180:183], v[124:127]
	v_mfma_f32_16x16x32_bf16 v[120:123], v[32:35], v[180:183], v[120:123]
	v_mfma_f32_16x16x32_bf16 v[108:111], v[24:27], v[188:191], v[108:111]
	v_mfma_f32_16x16x32_bf16 v[104:107], v[32:35], v[188:191], v[104:107]
	v_mfma_f32_16x16x32_bf16 v[92:95], v[24:27], v[196:199], v[92:95]
	v_mfma_f32_16x16x32_bf16 v[88:91], v[32:35], v[196:199], v[88:91]
	s_waitcnt lgkmcnt(0)
	v_mfma_f32_16x16x32_bf16 v[140:143], v[28:31], v[158:161], v[140:143]
	v_mfma_f32_16x16x32_bf16 v[136:139], v[36:39], v[158:161], v[136:139]
	v_mfma_f32_16x16x32_bf16 v[124:127], v[28:31], v[184:187], v[124:127]
	v_mfma_f32_16x16x32_bf16 v[120:123], v[36:39], v[184:187], v[120:123]
	v_mfma_f32_16x16x32_bf16 v[108:111], v[28:31], v[192:195], v[108:111]
	v_mfma_f32_16x16x32_bf16 v[104:107], v[36:39], v[192:195], v[104:107]
	v_mfma_f32_16x16x32_bf16 v[92:95], v[28:31], v[200:203], v[92:95]
	v_mfma_f32_16x16x32_bf16 v[88:91], v[36:39], v[200:203], v[88:91]
	s_barrier
	ds_read_b128 v[204:207], v164 offset:16384
	ds_read_b128 v[212:215], v164 offset:18432
	ds_read_b128 v[208:211], v164 offset:17408
	s_add_i32 m0, s36, 0x10000
	ds_read_b128 v[216:219], v164 offset:19456
	global_load_lds_dwordx4 v168, s[2:3]
	s_add_i32 m0, s36, 0x12000
	s_add_u32 s98, s2, 0x80
	s_addc_u32 s99, s3, 0
	global_load_lds_dwordx4 v148, s[2:3]
	s_barrier
	s_waitcnt lgkmcnt(2)
	v_mfma_f32_16x16x32_bf16 v[132:135], v[204:207], v[154:157], v[132:135]
	v_mfma_f32_16x16x32_bf16 v[128:131], v[212:215], v[154:157], v[128:131]
	v_mfma_f32_16x16x32_bf16 v[116:119], v[204:207], v[180:183], v[116:119]
	v_mfma_f32_16x16x32_bf16 v[112:115], v[212:215], v[180:183], v[112:115]
	v_mfma_f32_16x16x32_bf16 v[100:103], v[204:207], v[188:191], v[100:103]
	v_mfma_f32_16x16x32_bf16 v[96:99], v[212:215], v[188:191], v[96:99]
	v_mfma_f32_16x16x32_bf16 v[84:87], v[204:207], v[196:199], v[84:87]
	v_mfma_f32_16x16x32_bf16 v[80:83], v[212:215], v[196:199], v[80:83]
	s_waitcnt lgkmcnt(0)
	v_mfma_f32_16x16x32_bf16 v[132:135], v[208:211], v[158:161], v[132:135]
	v_mfma_f32_16x16x32_bf16 v[128:131], v[216:219], v[158:161], v[128:131]
	v_mfma_f32_16x16x32_bf16 v[116:119], v[208:211], v[184:187], v[116:119]
	v_mfma_f32_16x16x32_bf16 v[112:115], v[216:219], v[184:187], v[112:115]
	v_mfma_f32_16x16x32_bf16 v[100:103], v[208:211], v[192:195], v[100:103]
	v_mfma_f32_16x16x32_bf16 v[96:99], v[216:219], v[192:195], v[96:99]
	v_mfma_f32_16x16x32_bf16 v[84:87], v[208:211], v[200:203], v[84:87]
	v_mfma_f32_16x16x32_bf16 v[80:83], v[216:219], v[200:203], v[80:83]
	s_mov_b32 m0, s37
	s_add_u32 s100, s22, 0x80
	s_addc_u32 s101, s23, 0
	s_barrier
	ds_read_b128 v[154:157], v165 offset:16384
	ds_read_b128 v[180:183], v165 offset:18432
	ds_read_b128 v[188:191], v165 offset:20480
	ds_read_b128 v[196:199], v165 offset:22528
	ds_read_b128 v[158:161], v165 offset:17408
	ds_read_b128 v[184:187], v165 offset:19456
	ds_read_b128 v[192:195], v165 offset:21504
	global_load_lds_dwordx4 v144, s[22:23]
	s_mov_b32 m0, s38
	ds_read_b128 v[200:203], v165 offset:23552
	global_load_lds_dwordx4 v146, s[22:23]
	s_barrier
	s_waitcnt lgkmcnt(4)
	v_mfma_f32_16x16x32_bf16 v[76:79], v[24:27], v[154:157], v[76:79]
	v_mfma_f32_16x16x32_bf16 v[72:75], v[32:35], v[154:157], v[72:75]
	v_mfma_f32_16x16x32_bf16 v[60:63], v[24:27], v[180:183], v[60:63]
	v_mfma_f32_16x16x32_bf16 v[56:59], v[32:35], v[180:183], v[56:59]
	v_mfma_f32_16x16x32_bf16 v[44:47], v[24:27], v[188:191], v[44:47]
	v_mfma_f32_16x16x32_bf16 v[40:43], v[32:35], v[188:191], v[40:43]
	v_mfma_f32_16x16x32_bf16 v[12:15], v[24:27], v[196:199], v[12:15]
	v_mfma_f32_16x16x32_bf16 v[8:11], v[32:35], v[196:199], v[8:11]
	s_waitcnt lgkmcnt(0)
	v_mfma_f32_16x16x32_bf16 v[76:79], v[28:31], v[158:161], v[76:79]
	v_mfma_f32_16x16x32_bf16 v[72:75], v[36:39], v[158:161], v[72:75]
	v_mfma_f32_16x16x32_bf16 v[60:63], v[28:31], v[184:187], v[60:63]
	v_mfma_f32_16x16x32_bf16 v[56:59], v[36:39], v[184:187], v[56:59]
	v_mfma_f32_16x16x32_bf16 v[44:47], v[28:31], v[192:195], v[44:47]
	v_mfma_f32_16x16x32_bf16 v[40:43], v[36:39], v[192:195], v[40:43]
	v_mfma_f32_16x16x32_bf16 v[12:15], v[28:31], v[200:203], v[12:15]
	v_mfma_f32_16x16x32_bf16 v[8:11], v[36:39], v[200:203], v[8:11]
	s_barrier
	s_add_i32 m0, s36, 0x14000
	s_add_u32 s54, s2, 0x40000
	s_addc_u32 s55, s3, 0
	global_load_lds_dwordx4 v168, s[54:55]
	s_add_i32 m0, s36, 0x16000
	s_add_u32 s22, s22, 0x40000
	s_addc_u32 s23, s23, 0
	global_load_lds_dwordx4 v148, s[54:55]
	s_waitcnt vmcnt(6)
	s_barrier
	v_mfma_f32_16x16x32_bf16 v[20:23], v[204:207], v[188:191], v[20:23]
	v_mfma_f32_16x16x32_bf16 v[16:19], v[212:215], v[188:191], v[16:19]
	v_mfma_f32_16x16x32_bf16 v[4:7], v[204:207], v[196:199], v[4:7]
	v_mfma_f32_16x16x32_bf16 v[0:3], v[212:215], v[196:199], v[0:3]
	v_mfma_f32_16x16x32_bf16 v[24:27], v[204:207], v[154:157], v[68:71]
	v_mfma_f32_16x16x32_bf16 v[28:31], v[212:215], v[154:157], v[64:67]
	v_mfma_f32_16x16x32_bf16 v[32:35], v[204:207], v[180:183], v[52:55]
	v_mfma_f32_16x16x32_bf16 v[36:39], v[212:215], v[180:183], v[48:51]
	v_mfma_f32_16x16x32_bf16 v[20:23], v[208:211], v[192:195], v[20:23]
	v_mfma_f32_16x16x32_bf16 v[16:19], v[216:219], v[192:195], v[16:19]
	v_mfma_f32_16x16x32_bf16 v[4:7], v[208:211], v[200:203], v[4:7]
	v_mfma_f32_16x16x32_bf16 v[0:3], v[216:219], v[200:203], v[0:3]
	v_mfma_f32_16x16x32_bf16 v[24:27], v[208:211], v[158:161], v[24:27]
	v_mfma_f32_16x16x32_bf16 v[28:31], v[216:219], v[158:161], v[28:31]
	v_mfma_f32_16x16x32_bf16 v[32:35], v[208:211], v[184:187], v[32:35]
	v_mfma_f32_16x16x32_bf16 v[36:39], v[216:219], v[184:187], v[36:39]
	s_barrier
	ds_read_b128 v[48:51], v164 offset:32768
	ds_read_b128 v[64:67], v164 offset:34816
	ds_read_b128 v[52:55], v164 offset:33792
	ds_read_b128 v[68:71], v164 offset:35840
	s_mov_b32 m0, s39
	ds_read_b128 v[154:157], v165 offset:32768
	ds_read_b128 v[180:183], v165 offset:34816
	ds_read_b128 v[188:191], v165 offset:36864
	ds_read_b128 v[196:199], v165 offset:38912
	ds_read_b128 v[158:161], v165 offset:33792
	ds_read_b128 v[184:187], v165 offset:35840
	ds_read_b128 v[192:195], v165 offset:37888
	global_load_lds_dwordx4 v144, s[22:23]
	s_mov_b32 m0, s40
	ds_read_b128 v[200:203], v165 offset:39936
	global_load_lds_dwordx4 v146, s[22:23]
	s_waitcnt lgkmcnt(8)
	s_barrier
	s_waitcnt lgkmcnt(4)
	v_mfma_f32_16x16x32_bf16 v[140:143], v[48:51], v[154:157], v[140:143]
	v_mfma_f32_16x16x32_bf16 v[136:139], v[64:67], v[154:157], v[136:139]
	v_mfma_f32_16x16x32_bf16 v[124:127], v[48:51], v[180:183], v[124:127]
	v_mfma_f32_16x16x32_bf16 v[120:123], v[64:67], v[180:183], v[120:123]
	v_mfma_f32_16x16x32_bf16 v[108:111], v[48:51], v[188:191], v[108:111]
	v_mfma_f32_16x16x32_bf16 v[104:107], v[64:67], v[188:191], v[104:107]
	v_mfma_f32_16x16x32_bf16 v[92:95], v[48:51], v[196:199], v[92:95]
	v_mfma_f32_16x16x32_bf16 v[88:91], v[64:67], v[196:199], v[88:91]
	s_waitcnt lgkmcnt(0)
	v_mfma_f32_16x16x32_bf16 v[140:143], v[52:55], v[158:161], v[140:143]
	v_mfma_f32_16x16x32_bf16 v[136:139], v[68:71], v[158:161], v[136:139]
	v_mfma_f32_16x16x32_bf16 v[124:127], v[52:55], v[184:187], v[124:127]
	v_mfma_f32_16x16x32_bf16 v[120:123], v[68:71], v[184:187], v[120:123]
	v_mfma_f32_16x16x32_bf16 v[108:111], v[52:55], v[192:195], v[108:111]
	v_mfma_f32_16x16x32_bf16 v[104:107], v[68:71], v[192:195], v[104:107]
	v_mfma_f32_16x16x32_bf16 v[92:95], v[52:55], v[200:203], v[92:95]
	v_mfma_f32_16x16x32_bf16 v[88:91], v[68:71], v[200:203], v[88:91]
	s_barrier
	s_add_i32 m0, s36, 0x18000
	ds_read_b128 v[204:207], v164 offset:49152
	ds_read_b128 v[212:215], v164 offset:51200
	ds_read_b128 v[208:211], v164 offset:50176
	global_load_lds_dwordx4 v168, s[98:99]
	s_add_i32 m0, s36, 0x1a000
	ds_read_b128 v[216:219], v164 offset:52224
	global_load_lds_dwordx4 v148, s[98:99]
	s_barrier
	s_waitcnt lgkmcnt(2)
	v_mfma_f32_16x16x32_bf16 v[132:135], v[204:207], v[154:157], v[132:135]
	v_mfma_f32_16x16x32_bf16 v[128:131], v[212:215], v[154:157], v[128:131]
	v_mfma_f32_16x16x32_bf16 v[116:119], v[204:207], v[180:183], v[116:119]
	v_mfma_f32_16x16x32_bf16 v[112:115], v[212:215], v[180:183], v[112:115]
	v_mfma_f32_16x16x32_bf16 v[100:103], v[204:207], v[188:191], v[100:103]
	v_mfma_f32_16x16x32_bf16 v[96:99], v[212:215], v[188:191], v[96:99]
	v_mfma_f32_16x16x32_bf16 v[84:87], v[204:207], v[196:199], v[84:87]
	v_mfma_f32_16x16x32_bf16 v[80:83], v[212:215], v[196:199], v[80:83]
	s_waitcnt lgkmcnt(0)
	v_mfma_f32_16x16x32_bf16 v[132:135], v[208:211], v[158:161], v[132:135]
	v_mfma_f32_16x16x32_bf16 v[128:131], v[216:219], v[158:161], v[128:131]
	v_mfma_f32_16x16x32_bf16 v[116:119], v[208:211], v[184:187], v[116:119]
	v_mfma_f32_16x16x32_bf16 v[112:115], v[216:219], v[184:187], v[112:115]
	v_mfma_f32_16x16x32_bf16 v[100:103], v[208:211], v[192:195], v[100:103]
	v_mfma_f32_16x16x32_bf16 v[96:99], v[216:219], v[192:195], v[96:99]
	v_mfma_f32_16x16x32_bf16 v[84:87], v[208:211], v[200:203], v[84:87]
	v_mfma_f32_16x16x32_bf16 v[80:83], v[216:219], v[200:203], v[80:83]
	s_mov_b32 m0, s45
	s_barrier
	ds_read_b128 v[154:157], v165 offset:49152
	ds_read_b128 v[180:183], v165 offset:51200
	ds_read_b128 v[188:191], v165 offset:53248
	ds_read_b128 v[196:199], v165 offset:55296
	ds_read_b128 v[158:161], v165 offset:50176
	ds_read_b128 v[184:187], v165 offset:52224
	ds_read_b128 v[192:195], v165 offset:54272
	global_load_lds_dwordx4 v144, s[100:101]
	s_mov_b32 m0, s46
	ds_read_b128 v[200:203], v165 offset:56320
	global_load_lds_dwordx4 v146, s[100:101]
	s_barrier
	s_waitcnt lgkmcnt(4)
	v_mfma_f32_16x16x32_bf16 v[76:79], v[48:51], v[154:157], v[76:79]
	v_mfma_f32_16x16x32_bf16 v[72:75], v[64:67], v[154:157], v[72:75]
	v_mfma_f32_16x16x32_bf16 v[60:63], v[48:51], v[180:183], v[60:63]
	v_mfma_f32_16x16x32_bf16 v[56:59], v[64:67], v[180:183], v[56:59]
	v_mfma_f32_16x16x32_bf16 v[44:47], v[48:51], v[188:191], v[44:47]
	v_mfma_f32_16x16x32_bf16 v[40:43], v[64:67], v[188:191], v[40:43]
	v_mfma_f32_16x16x32_bf16 v[12:15], v[48:51], v[196:199], v[12:15]
	v_mfma_f32_16x16x32_bf16 v[8:11], v[64:67], v[196:199], v[8:11]
	s_waitcnt lgkmcnt(0)
	v_mfma_f32_16x16x32_bf16 v[76:79], v[52:55], v[158:161], v[76:79]
	v_mfma_f32_16x16x32_bf16 v[72:75], v[68:71], v[158:161], v[72:75]
	v_mfma_f32_16x16x32_bf16 v[60:63], v[52:55], v[184:187], v[60:63]
	v_mfma_f32_16x16x32_bf16 v[56:59], v[68:71], v[184:187], v[56:59]
	v_mfma_f32_16x16x32_bf16 v[44:47], v[52:55], v[192:195], v[44:47]
	v_mfma_f32_16x16x32_bf16 v[40:43], v[68:71], v[192:195], v[40:43]
	v_mfma_f32_16x16x32_bf16 v[12:15], v[52:55], v[200:203], v[12:15]
	v_mfma_f32_16x16x32_bf16 v[8:11], v[68:71], v[200:203], v[8:11]
	s_barrier
	s_add_i32 m0, s36, 0x1c000
	s_add_u32 s2, s2, 0x40080
	s_addc_u32 s3, s3, 0
	global_load_lds_dwordx4 v168, s[2:3]
	s_add_i32 m0, s36, 0x1e000
	s_add_i32 s52, s52, 2
	global_load_lds_dwordx4 v148, s[2:3]
	s_waitcnt vmcnt(6)
	s_barrier
	v_mfma_f32_16x16x32_bf16 v[24:27], v[204:207], v[154:157], v[24:27]
	v_mfma_f32_16x16x32_bf16 v[68:71], v[208:211], v[158:161], v[24:27]
	v_mfma_f32_16x16x32_bf16 v[24:27], v[212:215], v[154:157], v[28:31]
	v_mfma_f32_16x16x32_bf16 v[64:67], v[216:219], v[158:161], v[24:27]
	v_mfma_f32_16x16x32_bf16 v[24:27], v[204:207], v[180:183], v[32:35]
	v_mfma_f32_16x16x32_bf16 v[52:55], v[208:211], v[184:187], v[24:27]
	v_mfma_f32_16x16x32_bf16 v[24:27], v[212:215], v[180:183], v[36:39]
	v_mfma_f32_16x16x32_bf16 v[20:23], v[204:207], v[188:191], v[20:23]
	v_mfma_f32_16x16x32_bf16 v[16:19], v[212:215], v[188:191], v[16:19]
	v_mfma_f32_16x16x32_bf16 v[4:7], v[204:207], v[196:199], v[4:7]
	v_mfma_f32_16x16x32_bf16 v[0:3], v[212:215], v[196:199], v[0:3]
	v_mfma_f32_16x16x32_bf16 v[48:51], v[216:219], v[184:187], v[24:27]
	v_mfma_f32_16x16x32_bf16 v[20:23], v[208:211], v[192:195], v[20:23]
	v_mfma_f32_16x16x32_bf16 v[16:19], v[216:219], v[192:195], v[16:19]
	v_mfma_f32_16x16x32_bf16 v[4:7], v[208:211], v[200:203], v[4:7]
	v_mfma_f32_16x16x32_bf16 v[0:3], v[216:219], v[200:203], v[0:3]
	s_add_u32 s20, s20, 0x100
	s_addc_u32 s21, s21, 0
	s_add_u32 s50, s50, 0x100
	s_addc_u32 s51, s51, 0
	s_cmp_gt_u32 s52, 13
	s_barrier
	s_cbranch_scc0 .LBB0_123
	s_lshl_b32 s2, s6, 8
	s_add_i32 s3, s2, s43
	s_lshl_b32 s2, s8, 8
	s_cmp_gt_i32 s8, 3
	s_cselect_b64 s[20:21], -1, 0
	s_and_b64 s[22:23], s[20:21], exec
	s_mov_b32 s7, 0x8982000
	s_cselect_b32 s7, s7, 0x7182000
	s_add_u32 s22, s26, s7
	s_addc_u32 s23, s25, 0
	s_add_i32 s7, s6, -16
	v_mov_b32_e32 v160, v163
	v_mov_b32_e32 v24, v162
	s_lshr_b32 s7, s7, 3
	s_add_i32 s96, s7, 1
	v_add_u32_e32 v154, s3, v24
	s_lshl_b64 s[50:51], s[96:97], 11
	v_ashrrev_i32_e32 v155, 31, v154
	s_cmp_gt_i32 s6, 15
	v_lshl_add_u64 v[156:157], v[154:155], 2, s[10:11]
	s_cselect_b32 s7, s51, 0
	s_cselect_b32 s6, s50, 0
	global_load_dword v166, v[156:157], off
	global_load_dword v191, v[156:157], off offset:64
	global_load_dword v192, v[156:157], off offset:128
	global_load_dword v193, v[156:157], off offset:192
	global_load_dword v194, v[156:157], off offset:512
	global_load_dword v195, v[156:157], off offset:576
	global_load_dword v196, v[156:157], off offset:640
	global_load_dword v197, v[156:157], off offset:704
	s_lshl_b64 s[6:7], s[6:7], 2
	s_add_u32 s9, s41, s6
	s_addc_u32 s13, s42, s7
	s_ashr_i32 s3, s2, 31
	s_lshl_b64 s[6:7], s[2:3], 2
	s_add_u32 s3, s9, s6
	s_addc_u32 s7, s13, s7
	v_lshlrev_b32_e32 v158, 3, v160
	s_add_u32 s6, s3, s49
	s_addc_u32 s7, s7, 0
	v_ashrrev_i32_e32 v159, 31, v158
	v_lshl_add_u64 v[24:25], v[158:159], 2, s[6:7]
	global_load_dwordx4 v[36:39], v[24:25], off
	global_load_dwordx4 v[32:35], v[24:25], off offset:16
	global_load_dwordx4 v[28:31], v[24:25], off offset:512
	s_nop 0
	global_load_dwordx4 v[24:27], v[24:25], off offset:528
	s_and_b32 s2, s2, 0x300
	s_or_b32 s2, s2, s44
	v_add_u32_e32 v158, s2, v158
	v_cmp_eq_u32_e64 s[6:7], 0, v160
	v_lshlrev_b64 v[160:161], 11, v[154:155]
	s_cmp_lt_i32 s8, 4
	s_waitcnt vmcnt(0)
	v_ashrrev_i32_e32 v159, 31, v158
	v_lshl_add_u64 v[158:159], v[158:159], 1, s[22:23]
	v_lshl_add_u64 v[160:161], v[158:159], 0, v[160:161]
	v_lshl_add_u64 v[156:157], v[154:155], 2, s[0:1]
	s_and_b64 s[6:7], s[6:7], s[20:21]
	s_mov_b64 s[2:3], 0x8000
	s_mov_b64 s[50:51], 0x28000
	v_mov_b32_e32 v180, 0xc0135761
	v_mov_b32_e32 v181, 0xc0135761
	v_mov_b32_e32 v182, 0xbdd2d3e7
	v_mov_b32_e32 v183, 0xbdd2d3e7
	v_fmamk_f32 v166, v166, 0x3a800000, v225
	v_fmamk_f32 v190, v191, 0x3a800000, v225
	v_fmamk_f32 v192, v192, 0x3a800000, v225
	v_fmamk_f32 v188, v193, 0x3a800000, v225
	v_fmamk_f32 v194, v194, 0x3a800000, v225
	v_fmamk_f32 v186, v195, 0x3a800000, v225
	v_fmamk_f32 v196, v196, 0x3a800000, v225
	v_fmamk_f32 v184, v197, 0x3a800000, v225
	v_rsq_f32_e32 v166, v166
	v_rsq_f32_e32 v190, v190
	v_rsq_f32_e32 v192, v192
	v_rsq_f32_e32 v188, v188
	v_rsq_f32_e32 v194, v194
	v_rsq_f32_e32 v186, v186
	v_rsq_f32_e32 v196, v196
	v_rsq_f32_e32 v184, v184
	v_pk_fma_f32 v[140:141], v[140:141], v[166:167], v[36:37] op_sel_hi:[1,0,1]
	v_pk_fma_f32 v[142:143], v[142:143], v[166:167], v[38:39] op_sel_hi:[1,0,1]
	v_pk_fma_f32 v[136:137], v[136:137], v[166:167], v[32:33] op_sel_hi:[1,0,1]
	v_pk_fma_f32 v[138:139], v[138:139], v[166:167], v[34:35] op_sel_hi:[1,0,1]
	v_pk_fma_f32 v[132:133], v[132:133], v[166:167], v[28:29] op_sel_hi:[1,0,1]
	v_pk_fma_f32 v[134:135], v[134:135], v[166:167], v[30:31] op_sel_hi:[1,0,1]
	v_pk_fma_f32 v[128:129], v[128:129], v[166:167], v[24:25] op_sel_hi:[1,0,1]
	v_pk_fma_f32 v[130:131], v[130:131], v[166:167], v[26:27] op_sel_hi:[1,0,1]
	v_pk_fma_f32 v[124:125], v[124:125], v[190:191], v[36:37] op_sel_hi:[1,0,1]
	v_pk_fma_f32 v[126:127], v[126:127], v[190:191], v[38:39] op_sel_hi:[1,0,1]
	v_pk_fma_f32 v[120:121], v[120:121], v[190:191], v[32:33] op_sel_hi:[1,0,1]
	v_pk_fma_f32 v[122:123], v[122:123], v[190:191], v[34:35] op_sel_hi:[1,0,1]
	v_pk_fma_f32 v[116:117], v[116:117], v[190:191], v[28:29] op_sel_hi:[1,0,1]
	v_pk_fma_f32 v[118:119], v[118:119], v[190:191], v[30:31] op_sel_hi:[1,0,1]
	v_pk_fma_f32 v[112:113], v[112:113], v[190:191], v[24:25] op_sel_hi:[1,0,1]
	v_pk_fma_f32 v[114:115], v[114:115], v[190:191], v[26:27] op_sel_hi:[1,0,1]
	v_pk_fma_f32 v[108:109], v[108:109], v[192:193], v[36:37] op_sel_hi:[1,0,1]
	v_pk_fma_f32 v[110:111], v[110:111], v[192:193], v[38:39] op_sel_hi:[1,0,1]
	v_pk_fma_f32 v[104:105], v[104:105], v[192:193], v[32:33] op_sel_hi:[1,0,1]
	v_pk_fma_f32 v[106:107], v[106:107], v[192:193], v[34:35] op_sel_hi:[1,0,1]
	v_pk_fma_f32 v[100:101], v[100:101], v[192:193], v[28:29] op_sel_hi:[1,0,1]
	v_pk_fma_f32 v[102:103], v[102:103], v[192:193], v[30:31] op_sel_hi:[1,0,1]
	v_pk_fma_f32 v[96:97], v[96:97], v[192:193], v[24:25] op_sel_hi:[1,0,1]
	v_pk_fma_f32 v[98:99], v[98:99], v[192:193], v[26:27] op_sel_hi:[1,0,1]
	v_pk_fma_f32 v[92:93], v[92:93], v[188:189], v[36:37] op_sel_hi:[1,0,1]
	v_pk_fma_f32 v[94:95], v[94:95], v[188:189], v[38:39] op_sel_hi:[1,0,1]
	v_pk_fma_f32 v[88:89], v[88:89], v[188:189], v[32:33] op_sel_hi:[1,0,1]
	v_pk_fma_f32 v[90:91], v[90:91], v[188:189], v[34:35] op_sel_hi:[1,0,1]
	v_pk_fma_f32 v[84:85], v[84:85], v[188:189], v[28:29] op_sel_hi:[1,0,1]
	v_pk_fma_f32 v[86:87], v[86:87], v[188:189], v[30:31] op_sel_hi:[1,0,1]
	v_pk_fma_f32 v[80:81], v[80:81], v[188:189], v[24:25] op_sel_hi:[1,0,1]
	v_pk_fma_f32 v[82:83], v[82:83], v[188:189], v[26:27] op_sel_hi:[1,0,1]
	v_pk_fma_f32 v[76:77], v[76:77], v[194:195], v[36:37] op_sel_hi:[1,0,1]
	v_pk_fma_f32 v[78:79], v[78:79], v[194:195], v[38:39] op_sel_hi:[1,0,1]
	v_pk_fma_f32 v[72:73], v[72:73], v[194:195], v[32:33] op_sel_hi:[1,0,1]
	v_pk_fma_f32 v[74:75], v[74:75], v[194:195], v[34:35] op_sel_hi:[1,0,1]
	v_pk_fma_f32 v[68:69], v[68:69], v[194:195], v[28:29] op_sel_hi:[1,0,1]
	v_pk_fma_f32 v[70:71], v[70:71], v[194:195], v[30:31] op_sel_hi:[1,0,1]
	v_pk_fma_f32 v[64:65], v[64:65], v[194:195], v[24:25] op_sel_hi:[1,0,1]
	v_pk_fma_f32 v[66:67], v[66:67], v[194:195], v[26:27] op_sel_hi:[1,0,1]
	v_pk_fma_f32 v[60:61], v[60:61], v[186:187], v[36:37] op_sel_hi:[1,0,1]
	v_pk_fma_f32 v[62:63], v[62:63], v[186:187], v[38:39] op_sel_hi:[1,0,1]
	v_pk_fma_f32 v[56:57], v[56:57], v[186:187], v[32:33] op_sel_hi:[1,0,1]
	v_pk_fma_f32 v[58:59], v[58:59], v[186:187], v[34:35] op_sel_hi:[1,0,1]
	v_pk_fma_f32 v[52:53], v[52:53], v[186:187], v[28:29] op_sel_hi:[1,0,1]
	v_pk_fma_f32 v[54:55], v[54:55], v[186:187], v[30:31] op_sel_hi:[1,0,1]
	v_pk_fma_f32 v[48:49], v[48:49], v[186:187], v[24:25] op_sel_hi:[1,0,1]
	v_pk_fma_f32 v[50:51], v[50:51], v[186:187], v[26:27] op_sel_hi:[1,0,1]
	v_pk_fma_f32 v[44:45], v[44:45], v[196:197], v[36:37] op_sel_hi:[1,0,1]
	v_pk_fma_f32 v[46:47], v[46:47], v[196:197], v[38:39] op_sel_hi:[1,0,1]
	v_pk_fma_f32 v[40:41], v[40:41], v[196:197], v[32:33] op_sel_hi:[1,0,1]
	v_pk_fma_f32 v[42:43], v[42:43], v[196:197], v[34:35] op_sel_hi:[1,0,1]
	v_pk_fma_f32 v[20:21], v[20:21], v[196:197], v[28:29] op_sel_hi:[1,0,1]
	v_pk_fma_f32 v[22:23], v[22:23], v[196:197], v[30:31] op_sel_hi:[1,0,1]
	v_pk_fma_f32 v[16:17], v[16:17], v[196:197], v[24:25] op_sel_hi:[1,0,1]
	v_pk_fma_f32 v[18:19], v[18:19], v[196:197], v[26:27] op_sel_hi:[1,0,1]
	v_pk_fma_f32 v[12:13], v[12:13], v[184:185], v[36:37] op_sel_hi:[1,0,1]
	v_pk_fma_f32 v[14:15], v[14:15], v[184:185], v[38:39] op_sel_hi:[1,0,1]
	v_pk_fma_f32 v[8:9], v[8:9], v[184:185], v[32:33] op_sel_hi:[1,0,1]
	v_pk_fma_f32 v[10:11], v[10:11], v[184:185], v[34:35] op_sel_hi:[1,0,1]
	v_pk_fma_f32 v[4:5], v[4:5], v[184:185], v[28:29] op_sel_hi:[1,0,1]
	v_pk_fma_f32 v[6:7], v[6:7], v[184:185], v[30:31] op_sel_hi:[1,0,1]
	v_pk_fma_f32 v[0:1], v[0:1], v[184:185], v[24:25] op_sel_hi:[1,0,1]
	v_pk_fma_f32 v[2:3], v[2:3], v[184:185], v[26:27] op_sel_hi:[1,0,1]
	v_pk_mul_f32 v[24:25], v[140:141], v[140:141]
	v_pk_mul_f32 v[26:27], v[142:143], v[142:143]
	v_pk_mul_f32 v[28:29], v[136:137], v[136:137]
	v_pk_mul_f32 v[30:31], v[138:139], v[138:139]
	v_pk_mul_f32 v[32:33], v[132:133], v[132:133]
	v_pk_mul_f32 v[34:35], v[134:135], v[134:135]
	v_pk_mul_f32 v[36:37], v[128:129], v[128:129]
	v_pk_mul_f32 v[38:39], v[130:131], v[130:131]
	v_pk_fma_f32 v[24:25], v[24:25], v[182:183], v[180:181]
	v_pk_fma_f32 v[26:27], v[26:27], v[182:183], v[180:181]
	v_pk_fma_f32 v[28:29], v[28:29], v[182:183], v[180:181]
	v_pk_fma_f32 v[30:31], v[30:31], v[182:183], v[180:181]
	v_pk_fma_f32 v[32:33], v[32:33], v[182:183], v[180:181]
	v_pk_fma_f32 v[34:35], v[34:35], v[182:183], v[180:181]
	v_pk_fma_f32 v[36:37], v[36:37], v[182:183], v[180:181]
	v_pk_fma_f32 v[38:39], v[38:39], v[182:183], v[180:181]
	v_pk_mul_f32 v[24:25], v[24:25], v[140:141]
	v_pk_mul_f32 v[26:27], v[26:27], v[142:143]
	v_pk_mul_f32 v[28:29], v[28:29], v[136:137]
	v_pk_mul_f32 v[30:31], v[30:31], v[138:139]
	v_pk_mul_f32 v[32:33], v[32:33], v[132:133]
	v_pk_mul_f32 v[34:35], v[34:35], v[134:135]
	v_pk_mul_f32 v[36:37], v[36:37], v[128:129]
	v_pk_mul_f32 v[38:39], v[38:39], v[130:131]
	v_exp_f32_e32 v24, v24
	v_exp_f32_e32 v25, v25
	v_exp_f32_e32 v26, v26
	v_exp_f32_e32 v27, v27
	v_exp_f32_e32 v28, v28
	v_exp_f32_e32 v29, v29
	v_exp_f32_e32 v30, v30
	v_exp_f32_e32 v31, v31
	v_exp_f32_e32 v32, v32
	v_exp_f32_e32 v33, v33
	v_exp_f32_e32 v34, v34
	v_exp_f32_e32 v35, v35
	v_exp_f32_e32 v36, v36
	v_exp_f32_e32 v37, v37
	v_exp_f32_e32 v38, v38
	v_exp_f32_e32 v39, v39
	v_pk_add_f32 v[24:25], v[24:25], 1.0 op_sel_hi:[1,0]
	v_pk_add_f32 v[26:27], v[26:27], 1.0 op_sel_hi:[1,0]
	v_pk_add_f32 v[28:29], v[28:29], 1.0 op_sel_hi:[1,0]
	v_pk_add_f32 v[30:31], v[30:31], 1.0 op_sel_hi:[1,0]
	v_pk_add_f32 v[32:33], v[32:33], 1.0 op_sel_hi:[1,0]
	v_pk_add_f32 v[34:35], v[34:35], 1.0 op_sel_hi:[1,0]
	v_pk_add_f32 v[36:37], v[36:37], 1.0 op_sel_hi:[1,0]
	v_pk_add_f32 v[38:39], v[38:39], 1.0 op_sel_hi:[1,0]
	v_rcp_f32_e32 v24, v24
	v_rcp_f32_e32 v25, v25
	v_rcp_f32_e32 v26, v26
	v_rcp_f32_e32 v27, v27
	v_rcp_f32_e32 v28, v28
	v_rcp_f32_e32 v29, v29
	v_rcp_f32_e32 v30, v30
	v_rcp_f32_e32 v31, v31
	v_rcp_f32_e32 v32, v32
	v_rcp_f32_e32 v33, v33
	v_rcp_f32_e32 v34, v34
	v_rcp_f32_e32 v35, v35
	v_rcp_f32_e32 v36, v36
	v_rcp_f32_e32 v37, v37
	v_rcp_f32_e32 v38, v38
	v_rcp_f32_e32 v39, v39
	v_pk_mul_f32 v[140:141], v[140:141], v[24:25]
	v_pk_mul_f32 v[142:143], v[142:143], v[26:27]
	v_pk_mul_f32 v[136:137], v[136:137], v[28:29]
	v_pk_mul_f32 v[138:139], v[138:139], v[30:31]
	v_pk_mul_f32 v[132:133], v[132:133], v[32:33]
	v_pk_mul_f32 v[134:135], v[134:135], v[34:35]
	v_pk_mul_f32 v[128:129], v[128:129], v[36:37]
	v_pk_mul_f32 v[130:131], v[130:131], v[38:39]
	v_cvt_pk_bf16_f32 v24, v140, v141
	v_cvt_pk_bf16_f32 v25, v142, v143
	v_cvt_pk_bf16_f32 v26, v136, v137
	v_cvt_pk_bf16_f32 v27, v138, v139
	v_cvt_pk_bf16_f32 v28, v132, v133
	v_cvt_pk_bf16_f32 v29, v134, v135
	v_cvt_pk_bf16_f32 v30, v128, v129
	v_cvt_pk_bf16_f32 v31, v130, v131
	global_store_dwordx4 v[160:161], v[24:27], off
	global_store_dwordx4 v[160:161], v[28:31], off offset:256
	s_and_b64 vcc, exec, s[20:21]
	s_cbranch_vccz .Lio_skip_0
	v_pk_mul_f32 v[32:33], v[140:141], v[140:141]
	v_pk_fma_f32 v[32:33], v[142:143], v[142:143], v[32:33]
	v_pk_fma_f32 v[32:33], v[136:137], v[136:137], v[32:33]
	v_pk_fma_f32 v[32:33], v[138:139], v[138:139], v[32:33]
	v_pk_fma_f32 v[32:33], v[132:133], v[132:133], v[32:33]
	v_pk_fma_f32 v[32:33], v[134:135], v[134:135], v[32:33]
	v_pk_fma_f32 v[32:33], v[128:129], v[128:129], v[32:33]
	v_pk_fma_f32 v[32:33], v[130:131], v[130:131], v[32:33]
	s_nop 0
	v_add_f32_e32 v32, v32, v33
	v_mov_b32_e32 v33, v32
	s_nop 1
	v_permlane16_swap_b32_e32 v32, v33
	v_add_f32_e32 v32, v32, v33
	v_mov_b32_e32 v33, v32
	s_nop 1
	v_permlane32_swap_b32_e32 v32, v33
	s_and_saveexec_b64 vcc, s[6:7]
	v_add_f32_e32 v32, v32, v33
	global_atomic_add_f32 v[156:157], v32, off
	s_mov_b64 exec, vcc

.Lie_done_b:
.LBB0_354:
	s_ashr_i32 s31, s30, 31
	v_cmp_lt_i64_e32 vcc, s[8:9], v[170:171]
	s_lshl_b64 s[8:9], s[30:31], 19
	s_add_u32 s34, s52, s8
	s_addc_u32 s35, s53, s9
	s_and_b64 s[8:9], vcc, exec
	s_cselect_b32 s1, s35, s7
	s_cselect_b32 s31, s34, s6
	s_ashr_i32 s29, s28, 31
	s_lshl_b64 s[8:9], s[28:29], 19
	s_add_u32 s36, s43, s8
	s_addc_u32 s37, s42, s9
	s_and_b64 s[8:9], vcc, exec
	s_cselect_b32 s29, s37, s3
	s_cselect_b32 s38, s36, s2
	s_add_u32 s6, s6, 0x40080
	s_addc_u32 s7, s7, 0
	s_add_u32 s39, s2, 0x100
	s_addc_u32 s40, s3, 0
	s_mov_b32 s41, -2
	s_add_u32 s2, s6, 0xfffc0080
	s_addc_u32 s3, s7, -1
	ds_read_b128 v[128:131], v208
	ds_read_b128 v[136:139], v208 offset:2048
	ds_read_b128 v[132:135], v208 offset:1024
	ds_read_b128 v[140:143], v208 offset:3072
	s_cmp_eq_u32 s41, 12
	s_cselect_b32 s9, s1, s3
	s_cselect_b32 s8, s31, s2
	s_cselect_b32 s3, s29, s40
	s_cselect_b32 s2, s38, s39
	s_add_i32 m0, s21, 0xc000
	ds_read_b128 v[144:147], v209
	ds_read_b128 v[152:155], v209 offset:2048
	ds_read_b128 v[180:183], v209 offset:4096
	ds_read_b128 v[188:191], v209 offset:6144
	ds_read_b128 v[148:151], v209 offset:1024
	ds_read_b128 v[156:159], v209 offset:3072
	ds_read_b128 v[184:187], v209 offset:5120
	global_load_lds_dwordx4 v164, s[6:7]
	s_add_i32 m0, s21, 0xe000
	ds_read_b128 v[192:195], v209 offset:7168
	global_load_lds_dwordx4 v166, s[6:7]
	s_waitcnt lgkmcnt(8)
	s_barrier
	s_waitcnt lgkmcnt(4)
	v_mfma_f32_16x16x32_bf16 v[124:127], v[128:131], v[144:147], 0
	v_mfma_f32_16x16x32_bf16 v[120:123], v[136:139], v[144:147], 0
	v_mfma_f32_16x16x32_bf16 v[116:119], v[128:131], v[152:155], 0
	v_mfma_f32_16x16x32_bf16 v[112:115], v[136:139], v[152:155], 0
	v_mfma_f32_16x16x32_bf16 v[100:103], v[128:131], v[180:183], 0
	v_mfma_f32_16x16x32_bf16 v[96:99], v[136:139], v[180:183], 0
	v_mfma_f32_16x16x32_bf16 v[84:87], v[128:131], v[188:191], 0
	v_mfma_f32_16x16x32_bf16 v[80:83], v[136:139], v[188:191], 0
	s_waitcnt lgkmcnt(0)
	v_mfma_f32_16x16x32_bf16 v[124:127], v[132:135], v[148:151], v[124:127]
	v_mfma_f32_16x16x32_bf16 v[120:123], v[140:143], v[148:151], v[120:123]
	v_mfma_f32_16x16x32_bf16 v[116:119], v[132:135], v[156:159], v[116:119]
	v_mfma_f32_16x16x32_bf16 v[112:115], v[140:143], v[156:159], v[112:115]
	v_mfma_f32_16x16x32_bf16 v[100:103], v[132:135], v[184:187], v[100:103]
	v_mfma_f32_16x16x32_bf16 v[96:99], v[140:143], v[184:187], v[96:99]
	v_mfma_f32_16x16x32_bf16 v[84:87], v[132:135], v[192:195], v[84:87]
	v_mfma_f32_16x16x32_bf16 v[80:83], v[140:143], v[192:195], v[80:83]
	s_barrier
	s_add_u32 s98, s2, 0x80
	s_addc_u32 s99, s3, 0
	s_add_i32 m0, s54, 0x10000
	ds_read_b128 v[196:199], v208 offset:16384
	ds_read_b128 v[210:213], v208 offset:18432
	ds_read_b128 v[200:203], v208 offset:17408
	global_load_lds_dwordx4 v160, s[2:3]
	s_add_i32 m0, s54, 0x12000
	ds_read_b128 v[214:217], v208 offset:19456
	global_load_lds_dwordx4 v162, s[2:3]
	s_barrier
	s_waitcnt lgkmcnt(2)
	v_mfma_f32_16x16x32_bf16 v[108:111], v[196:199], v[144:147], 0
	v_mfma_f32_16x16x32_bf16 v[104:107], v[210:213], v[144:147], 0
	v_mfma_f32_16x16x32_bf16 v[92:95], v[196:199], v[152:155], 0
	v_mfma_f32_16x16x32_bf16 v[88:91], v[210:213], v[152:155], 0
	v_mfma_f32_16x16x32_bf16 v[76:79], v[196:199], v[180:183], 0
	v_mfma_f32_16x16x32_bf16 v[72:75], v[210:213], v[180:183], 0
	v_mfma_f32_16x16x32_bf16 v[68:71], v[196:199], v[188:191], 0
	v_mfma_f32_16x16x32_bf16 v[64:67], v[210:213], v[188:191], 0
	s_waitcnt lgkmcnt(0)
	v_mfma_f32_16x16x32_bf16 v[108:111], v[200:203], v[148:151], v[108:111]
	v_mfma_f32_16x16x32_bf16 v[104:107], v[214:217], v[148:151], v[104:107]
	v_mfma_f32_16x16x32_bf16 v[92:95], v[200:203], v[156:159], v[92:95]
	v_mfma_f32_16x16x32_bf16 v[88:91], v[214:217], v[156:159], v[88:91]
	v_mfma_f32_16x16x32_bf16 v[76:79], v[200:203], v[184:187], v[76:79]
	v_mfma_f32_16x16x32_bf16 v[72:75], v[214:217], v[184:187], v[72:75]
	v_mfma_f32_16x16x32_bf16 v[68:71], v[200:203], v[192:195], v[68:71]
	v_mfma_f32_16x16x32_bf16 v[64:67], v[214:217], v[192:195], v[64:67]
	s_mov_b32 m0, s21
	s_add_u32 s100, s8, 0x80
	s_addc_u32 s101, s9, 0
	s_barrier
	ds_read_b128 v[144:147], v209 offset:16384
	ds_read_b128 v[152:155], v209 offset:18432
	ds_read_b128 v[180:183], v209 offset:20480
	ds_read_b128 v[188:191], v209 offset:22528
	ds_read_b128 v[148:151], v209 offset:17408
	ds_read_b128 v[156:159], v209 offset:19456
	ds_read_b128 v[184:187], v209 offset:21504
	global_load_lds_dwordx4 v160, s[8:9]
	s_mov_b32 m0, s55
	ds_read_b128 v[192:195], v209 offset:23552
	global_load_lds_dwordx4 v162, s[8:9]
	s_barrier
	s_waitcnt lgkmcnt(4)
	v_mfma_f32_16x16x32_bf16 v[60:63], v[128:131], v[144:147], 0
	v_mfma_f32_16x16x32_bf16 v[56:59], v[136:139], v[144:147], 0
	v_mfma_f32_16x16x32_bf16 v[52:55], v[128:131], v[152:155], 0
	v_mfma_f32_16x16x32_bf16 v[48:51], v[136:139], v[152:155], 0
	v_mfma_f32_16x16x32_bf16 v[36:39], v[128:131], v[180:183], 0
	v_mfma_f32_16x16x32_bf16 v[32:35], v[136:139], v[180:183], 0
	v_mfma_f32_16x16x32_bf16 v[20:23], v[128:131], v[188:191], 0
	v_mfma_f32_16x16x32_bf16 v[16:19], v[136:139], v[188:191], 0
	s_waitcnt lgkmcnt(0)
	v_mfma_f32_16x16x32_bf16 v[60:63], v[132:135], v[148:151], v[60:63]
	v_mfma_f32_16x16x32_bf16 v[56:59], v[140:143], v[148:151], v[56:59]
	v_mfma_f32_16x16x32_bf16 v[52:55], v[132:135], v[156:159], v[52:55]
	v_mfma_f32_16x16x32_bf16 v[48:51], v[140:143], v[156:159], v[48:51]
	v_mfma_f32_16x16x32_bf16 v[36:39], v[132:135], v[184:187], v[36:39]
	v_mfma_f32_16x16x32_bf16 v[32:35], v[140:143], v[184:187], v[32:35]
	v_mfma_f32_16x16x32_bf16 v[20:23], v[132:135], v[192:195], v[20:23]
	v_mfma_f32_16x16x32_bf16 v[16:19], v[140:143], v[192:195], v[16:19]
	s_barrier
	s_add_i32 m0, s54, 0x14000
	s_add_u32 s64, s2, 0x40000
	s_addc_u32 s65, s3, 0
	global_load_lds_dwordx4 v160, s[64:65]
	s_add_i32 m0, s54, 0x16000
	s_add_u32 s8, s8, 0x40000
	s_addc_u32 s9, s9, 0
	global_load_lds_dwordx4 v162, s[64:65]
	s_waitcnt vmcnt(6)
	s_barrier
	v_mfma_f32_16x16x32_bf16 v[44:47], v[196:199], v[144:147], 0
	v_mfma_f32_16x16x32_bf16 v[40:43], v[210:213], v[144:147], 0
	v_mfma_f32_16x16x32_bf16 v[28:31], v[196:199], v[152:155], 0
	v_mfma_f32_16x16x32_bf16 v[24:27], v[210:213], v[152:155], 0
	v_mfma_f32_16x16x32_bf16 v[12:15], v[196:199], v[180:183], 0
	v_mfma_f32_16x16x32_bf16 v[8:11], v[210:213], v[180:183], 0
	v_mfma_f32_16x16x32_bf16 v[4:7], v[196:199], v[188:191], 0
	v_mfma_f32_16x16x32_bf16 v[0:3], v[210:213], v[188:191], 0
	v_mfma_f32_16x16x32_bf16 v[44:47], v[200:203], v[148:151], v[44:47]
	v_mfma_f32_16x16x32_bf16 v[40:43], v[214:217], v[148:151], v[40:43]
	v_mfma_f32_16x16x32_bf16 v[28:31], v[200:203], v[156:159], v[28:31]
	v_mfma_f32_16x16x32_bf16 v[24:27], v[214:217], v[156:159], v[24:27]
	v_mfma_f32_16x16x32_bf16 v[12:15], v[200:203], v[184:187], v[12:15]
	v_mfma_f32_16x16x32_bf16 v[8:11], v[214:217], v[184:187], v[8:11]
	v_mfma_f32_16x16x32_bf16 v[4:7], v[200:203], v[192:195], v[4:7]
	v_mfma_f32_16x16x32_bf16 v[0:3], v[214:217], v[192:195], v[0:3]
	s_barrier
	ds_read_b128 v[128:131], v208 offset:32768
	ds_read_b128 v[136:139], v208 offset:34816
	ds_read_b128 v[132:135], v208 offset:33792
	ds_read_b128 v[140:143], v208 offset:35840
	s_mov_b32 m0, s56
	ds_read_b128 v[144:147], v209 offset:32768
	ds_read_b128 v[152:155], v209 offset:34816
	ds_read_b128 v[180:183], v209 offset:36864
	ds_read_b128 v[188:191], v209 offset:38912
	ds_read_b128 v[148:151], v209 offset:33792
	ds_read_b128 v[156:159], v209 offset:35840
	ds_read_b128 v[184:187], v209 offset:37888
	global_load_lds_dwordx4 v160, s[8:9]
	s_mov_b32 m0, s57
	ds_read_b128 v[192:195], v209 offset:39936
	global_load_lds_dwordx4 v162, s[8:9]
	s_waitcnt lgkmcnt(8)
	s_barrier
	s_waitcnt lgkmcnt(4)
	v_mfma_f32_16x16x32_bf16 v[124:127], v[128:131], v[144:147], v[124:127]
	v_mfma_f32_16x16x32_bf16 v[120:123], v[136:139], v[144:147], v[120:123]
	v_mfma_f32_16x16x32_bf16 v[116:119], v[128:131], v[152:155], v[116:119]
	v_mfma_f32_16x16x32_bf16 v[112:115], v[136:139], v[152:155], v[112:115]
	v_mfma_f32_16x16x32_bf16 v[100:103], v[128:131], v[180:183], v[100:103]
	v_mfma_f32_16x16x32_bf16 v[96:99], v[136:139], v[180:183], v[96:99]
	v_mfma_f32_16x16x32_bf16 v[84:87], v[128:131], v[188:191], v[84:87]
	v_mfma_f32_16x16x32_bf16 v[80:83], v[136:139], v[188:191], v[80:83]
	s_waitcnt lgkmcnt(0)
	v_mfma_f32_16x16x32_bf16 v[124:127], v[132:135], v[148:151], v[124:127]
	v_mfma_f32_16x16x32_bf16 v[120:123], v[140:143], v[148:151], v[120:123]
	v_mfma_f32_16x16x32_bf16 v[116:119], v[132:135], v[156:159], v[116:119]
	v_mfma_f32_16x16x32_bf16 v[112:115], v[140:143], v[156:159], v[112:115]
	v_mfma_f32_16x16x32_bf16 v[100:103], v[132:135], v[184:187], v[100:103]
	v_mfma_f32_16x16x32_bf16 v[96:99], v[140:143], v[184:187], v[96:99]
	v_mfma_f32_16x16x32_bf16 v[84:87], v[132:135], v[192:195], v[84:87]
	v_mfma_f32_16x16x32_bf16 v[80:83], v[140:143], v[192:195], v[80:83]
	s_barrier
	s_add_i32 m0, s54, 0x18000
	ds_read_b128 v[196:199], v208 offset:49152
	ds_read_b128 v[210:213], v208 offset:51200
	ds_read_b128 v[200:203], v208 offset:50176
	global_load_lds_dwordx4 v160, s[98:99]
	s_add_i32 m0, s54, 0x1a000
	ds_read_b128 v[214:217], v208 offset:52224
	global_load_lds_dwordx4 v162, s[98:99]
	s_barrier
	s_waitcnt lgkmcnt(2)
	v_mfma_f32_16x16x32_bf16 v[108:111], v[196:199], v[144:147], v[108:111]
	v_mfma_f32_16x16x32_bf16 v[104:107], v[210:213], v[144:147], v[104:107]
	v_mfma_f32_16x16x32_bf16 v[92:95], v[196:199], v[152:155], v[92:95]
	v_mfma_f32_16x16x32_bf16 v[88:91], v[210:213], v[152:155], v[88:91]
	v_mfma_f32_16x16x32_bf16 v[76:79], v[196:199], v[180:183], v[76:79]
	v_mfma_f32_16x16x32_bf16 v[72:75], v[210:213], v[180:183], v[72:75]
	v_mfma_f32_16x16x32_bf16 v[68:71], v[196:199], v[188:191], v[68:71]
	v_mfma_f32_16x16x32_bf16 v[64:67], v[210:213], v[188:191], v[64:67]
	s_waitcnt lgkmcnt(0)
	v_mfma_f32_16x16x32_bf16 v[108:111], v[200:203], v[148:151], v[108:111]
	v_mfma_f32_16x16x32_bf16 v[104:107], v[214:217], v[148:151], v[104:107]
	v_mfma_f32_16x16x32_bf16 v[92:95], v[200:203], v[156:159], v[92:95]
	v_mfma_f32_16x16x32_bf16 v[88:91], v[214:217], v[156:159], v[88:91]
	v_mfma_f32_16x16x32_bf16 v[76:79], v[200:203], v[184:187], v[76:79]
	v_mfma_f32_16x16x32_bf16 v[72:75], v[214:217], v[184:187], v[72:75]
	v_mfma_f32_16x16x32_bf16 v[68:71], v[200:203], v[192:195], v[68:71]
	v_mfma_f32_16x16x32_bf16 v[64:67], v[214:217], v[192:195], v[64:67]
	s_mov_b32 m0, s60
	s_barrier
	ds_read_b128 v[144:147], v209 offset:49152
	ds_read_b128 v[152:155], v209 offset:51200
	ds_read_b128 v[180:183], v209 offset:53248
	ds_read_b128 v[188:191], v209 offset:55296
	ds_read_b128 v[148:151], v209 offset:50176
	ds_read_b128 v[156:159], v209 offset:52224
	ds_read_b128 v[184:187], v209 offset:54272
	global_load_lds_dwordx4 v160, s[100:101]
	s_mov_b32 m0, s61
	ds_read_b128 v[192:195], v209 offset:56320
	global_load_lds_dwordx4 v162, s[100:101]
	s_barrier
	s_waitcnt lgkmcnt(4)
	v_mfma_f32_16x16x32_bf16 v[60:63], v[128:131], v[144:147], v[60:63]
	v_mfma_f32_16x16x32_bf16 v[56:59], v[136:139], v[144:147], v[56:59]
	v_mfma_f32_16x16x32_bf16 v[52:55], v[128:131], v[152:155], v[52:55]
	v_mfma_f32_16x16x32_bf16 v[48:51], v[136:139], v[152:155], v[48:51]
	v_mfma_f32_16x16x32_bf16 v[36:39], v[128:131], v[180:183], v[36:39]
	v_mfma_f32_16x16x32_bf16 v[32:35], v[136:139], v[180:183], v[32:35]
	v_mfma_f32_16x16x32_bf16 v[20:23], v[128:131], v[188:191], v[20:23]
	v_mfma_f32_16x16x32_bf16 v[16:19], v[136:139], v[188:191], v[16:19]
	s_waitcnt lgkmcnt(0)
	v_mfma_f32_16x16x32_bf16 v[60:63], v[132:135], v[148:151], v[60:63]
	v_mfma_f32_16x16x32_bf16 v[56:59], v[140:143], v[148:151], v[56:59]
	v_mfma_f32_16x16x32_bf16 v[52:55], v[132:135], v[156:159], v[52:55]
	v_mfma_f32_16x16x32_bf16 v[48:51], v[140:143], v[156:159], v[48:51]
	v_mfma_f32_16x16x32_bf16 v[36:39], v[132:135], v[184:187], v[36:39]
	v_mfma_f32_16x16x32_bf16 v[32:35], v[140:143], v[184:187], v[32:35]
	v_mfma_f32_16x16x32_bf16 v[20:23], v[132:135], v[192:195], v[20:23]
	v_mfma_f32_16x16x32_bf16 v[16:19], v[140:143], v[192:195], v[16:19]
	s_barrier
	s_add_i32 m0, s54, 0x1c000
	s_add_u32 s2, s2, 0x40080
	s_addc_u32 s3, s3, 0
	global_load_lds_dwordx4 v160, s[2:3]
	s_add_i32 m0, s54, 0x1e000
	s_add_i32 s41, s41, 2
	global_load_lds_dwordx4 v162, s[2:3]
	s_waitcnt vmcnt(6)
	s_barrier
	v_mfma_f32_16x16x32_bf16 v[44:47], v[196:199], v[144:147], v[44:47]
	v_mfma_f32_16x16x32_bf16 v[40:43], v[210:213], v[144:147], v[40:43]
	v_mfma_f32_16x16x32_bf16 v[28:31], v[196:199], v[152:155], v[28:31]
	v_mfma_f32_16x16x32_bf16 v[24:27], v[210:213], v[152:155], v[24:27]
	v_mfma_f32_16x16x32_bf16 v[12:15], v[196:199], v[180:183], v[12:15]
	v_mfma_f32_16x16x32_bf16 v[8:11], v[210:213], v[180:183], v[8:11]
	v_mfma_f32_16x16x32_bf16 v[4:7], v[196:199], v[188:191], v[4:7]
	v_mfma_f32_16x16x32_bf16 v[0:3], v[210:213], v[188:191], v[0:3]
	v_mfma_f32_16x16x32_bf16 v[44:47], v[200:203], v[148:151], v[44:47]
	v_mfma_f32_16x16x32_bf16 v[40:43], v[214:217], v[148:151], v[40:43]
	v_mfma_f32_16x16x32_bf16 v[28:31], v[200:203], v[156:159], v[28:31]
	v_mfma_f32_16x16x32_bf16 v[24:27], v[214:217], v[156:159], v[24:27]
	v_mfma_f32_16x16x32_bf16 v[12:15], v[200:203], v[184:187], v[12:15]
	v_mfma_f32_16x16x32_bf16 v[8:11], v[214:217], v[184:187], v[8:11]
	v_mfma_f32_16x16x32_bf16 v[4:7], v[200:203], v[192:195], v[4:7]
	v_mfma_f32_16x16x32_bf16 v[0:3], v[214:217], v[192:195], v[0:3]
	s_add_u32 s6, s6, 0x100
	s_addc_u32 s7, s7, 0
	s_add_u32 s39, s39, 0x100
	s_addc_u32 s40, s40, 0
	s_cmp_gt_u32 s41, 13
	s_barrier
.LBB0_355:
	s_add_u32 s2, s6, 0xfffc0080
	s_addc_u32 s3, s7, -1
	ds_read_b128 v[128:131], v208
	ds_read_b128 v[136:139], v208 offset:2048
	ds_read_b128 v[132:135], v208 offset:1024
	ds_read_b128 v[140:143], v208 offset:3072
	s_cmp_eq_u32 s41, 12
	s_cselect_b32 s9, s1, s3
	s_cselect_b32 s8, s31, s2
	s_cselect_b32 s3, s29, s40
	s_cselect_b32 s2, s38, s39
	s_add_i32 m0, s21, 0xc000
	ds_read_b128 v[144:147], v209
	ds_read_b128 v[152:155], v209 offset:2048
	ds_read_b128 v[180:183], v209 offset:4096
	ds_read_b128 v[188:191], v209 offset:6144
	ds_read_b128 v[148:151], v209 offset:1024
	ds_read_b128 v[156:159], v209 offset:3072
	ds_read_b128 v[184:187], v209 offset:5120
	global_load_lds_dwordx4 v164, s[6:7]
	s_add_i32 m0, s21, 0xe000
	ds_read_b128 v[192:195], v209 offset:7168
	global_load_lds_dwordx4 v166, s[6:7]
	s_waitcnt lgkmcnt(8)
	s_barrier
	s_waitcnt lgkmcnt(4)
	v_mfma_f32_16x16x32_bf16 v[124:127], v[128:131], v[144:147], v[124:127]
	v_mfma_f32_16x16x32_bf16 v[120:123], v[136:139], v[144:147], v[120:123]
	v_mfma_f32_16x16x32_bf16 v[116:119], v[128:131], v[152:155], v[116:119]
	v_mfma_f32_16x16x32_bf16 v[112:115], v[136:139], v[152:155], v[112:115]
	v_mfma_f32_16x16x32_bf16 v[100:103], v[128:131], v[180:183], v[100:103]
	v_mfma_f32_16x16x32_bf16 v[96:99], v[136:139], v[180:183], v[96:99]
	v_mfma_f32_16x16x32_bf16 v[84:87], v[128:131], v[188:191], v[84:87]
	v_mfma_f32_16x16x32_bf16 v[80:83], v[136:139], v[188:191], v[80:83]
	s_waitcnt lgkmcnt(0)
	v_mfma_f32_16x16x32_bf16 v[124:127], v[132:135], v[148:151], v[124:127]
	v_mfma_f32_16x16x32_bf16 v[120:123], v[140:143], v[148:151], v[120:123]
	v_mfma_f32_16x16x32_bf16 v[116:119], v[132:135], v[156:159], v[116:119]
	v_mfma_f32_16x16x32_bf16 v[112:115], v[140:143], v[156:159], v[112:115]
	v_mfma_f32_16x16x32_bf16 v[100:103], v[132:135], v[184:187], v[100:103]
	v_mfma_f32_16x16x32_bf16 v[96:99], v[140:143], v[184:187], v[96:99]
	v_mfma_f32_16x16x32_bf16 v[84:87], v[132:135], v[192:195], v[84:87]
	v_mfma_f32_16x16x32_bf16 v[80:83], v[140:143], v[192:195], v[80:83]
	s_barrier
	s_add_u32 s98, s2, 0x80
	s_addc_u32 s99, s3, 0
	s_add_i32 m0, s54, 0x10000
	ds_read_b128 v[196:199], v208 offset:16384
	ds_read_b128 v[210:213], v208 offset:18432
	ds_read_b128 v[200:203], v208 offset:17408
	global_load_lds_dwordx4 v160, s[2:3]
	s_add_i32 m0, s54, 0x12000
	ds_read_b128 v[214:217], v208 offset:19456
	global_load_lds_dwordx4 v162, s[2:3]
	s_barrier
	s_waitcnt lgkmcnt(2)
	v_mfma_f32_16x16x32_bf16 v[108:111], v[196:199], v[144:147], v[108:111]
	v_mfma_f32_16x16x32_bf16 v[104:107], v[210:213], v[144:147], v[104:107]
	v_mfma_f32_16x16x32_bf16 v[92:95], v[196:199], v[152:155], v[92:95]
	v_mfma_f32_16x16x32_bf16 v[88:91], v[210:213], v[152:155], v[88:91]
	v_mfma_f32_16x16x32_bf16 v[76:79], v[196:199], v[180:183], v[76:79]
	v_mfma_f32_16x16x32_bf16 v[72:75], v[210:213], v[180:183], v[72:75]
	v_mfma_f32_16x16x32_bf16 v[68:71], v[196:199], v[188:191], v[68:71]
	v_mfma_f32_16x16x32_bf16 v[64:67], v[210:213], v[188:191], v[64:67]
	s_waitcnt lgkmcnt(0)
	v_mfma_f32_16x16x32_bf16 v[108:111], v[200:203], v[148:151], v[108:111]
	v_mfma_f32_16x16x32_bf16 v[104:107], v[214:217], v[148:151], v[104:107]
	v_mfma_f32_16x16x32_bf16 v[92:95], v[200:203], v[156:159], v[92:95]
	v_mfma_f32_16x16x32_bf16 v[88:91], v[214:217], v[156:159], v[88:91]
	v_mfma_f32_16x16x32_bf16 v[76:79], v[200:203], v[184:187], v[76:79]
	v_mfma_f32_16x16x32_bf16 v[72:75], v[214:217], v[184:187], v[72:75]
	v_mfma_f32_16x16x32_bf16 v[68:71], v[200:203], v[192:195], v[68:71]
	v_mfma_f32_16x16x32_bf16 v[64:67], v[214:217], v[192:195], v[64:67]
	s_mov_b32 m0, s21
	s_add_u32 s100, s8, 0x80
	s_addc_u32 s101, s9, 0
	s_barrier
	ds_read_b128 v[144:147], v209 offset:16384
	ds_read_b128 v[152:155], v209 offset:18432
	ds_read_b128 v[180:183], v209 offset:20480
	ds_read_b128 v[188:191], v209 offset:22528
	ds_read_b128 v[148:151], v209 offset:17408
	ds_read_b128 v[156:159], v209 offset:19456
	ds_read_b128 v[184:187], v209 offset:21504
	global_load_lds_dwordx4 v160, s[8:9]
	s_mov_b32 m0, s55
	ds_read_b128 v[192:195], v209 offset:23552
	global_load_lds_dwordx4 v162, s[8:9]
	s_barrier
	s_waitcnt lgkmcnt(4)
	v_mfma_f32_16x16x32_bf16 v[60:63], v[128:131], v[144:147], v[60:63]
	v_mfma_f32_16x16x32_bf16 v[56:59], v[136:139], v[144:147], v[56:59]
	v_mfma_f32_16x16x32_bf16 v[52:55], v[128:131], v[152:155], v[52:55]
	v_mfma_f32_16x16x32_bf16 v[48:51], v[136:139], v[152:155], v[48:51]
	v_mfma_f32_16x16x32_bf16 v[36:39], v[128:131], v[180:183], v[36:39]
	v_mfma_f32_16x16x32_bf16 v[32:35], v[136:139], v[180:183], v[32:35]
	v_mfma_f32_16x16x32_bf16 v[20:23], v[128:131], v[188:191], v[20:23]
	v_mfma_f32_16x16x32_bf16 v[16:19], v[136:139], v[188:191], v[16:19]
	s_waitcnt lgkmcnt(0)
	v_mfma_f32_16x16x32_bf16 v[60:63], v[132:135], v[148:151], v[60:63]
	v_mfma_f32_16x16x32_bf16 v[56:59], v[140:143], v[148:151], v[56:59]
	v_mfma_f32_16x16x32_bf16 v[52:55], v[132:135], v[156:159], v[52:55]
	v_mfma_f32_16x16x32_bf16 v[48:51], v[140:143], v[156:159], v[48:51]
	v_mfma_f32_16x16x32_bf16 v[36:39], v[132:135], v[184:187], v[36:39]
	v_mfma_f32_16x16x32_bf16 v[32:35], v[140:143], v[184:187], v[32:35]
	v_mfma_f32_16x16x32_bf16 v[20:23], v[132:135], v[192:195], v[20:23]
	v_mfma_f32_16x16x32_bf16 v[16:19], v[140:143], v[192:195], v[16:19]
	s_barrier
	s_add_i32 m0, s54, 0x14000
	s_add_u32 s64, s2, 0x40000
	s_addc_u32 s65, s3, 0
	global_load_lds_dwordx4 v160, s[64:65]
	s_add_i32 m0, s54, 0x16000
	s_add_u32 s8, s8, 0x40000
	s_addc_u32 s9, s9, 0
	global_load_lds_dwordx4 v162, s[64:65]
	s_waitcnt vmcnt(6)
	s_barrier
	v_mfma_f32_16x16x32_bf16 v[44:47], v[196:199], v[144:147], v[44:47]
	v_mfma_f32_16x16x32_bf16 v[40:43], v[210:213], v[144:147], v[40:43]
	v_mfma_f32_16x16x32_bf16 v[28:31], v[196:199], v[152:155], v[28:31]
	v_mfma_f32_16x16x32_bf16 v[24:27], v[210:213], v[152:155], v[24:27]
	v_mfma_f32_16x16x32_bf16 v[12:15], v[196:199], v[180:183], v[12:15]
	v_mfma_f32_16x16x32_bf16 v[8:11], v[210:213], v[180:183], v[8:11]
	v_mfma_f32_16x16x32_bf16 v[4:7], v[196:199], v[188:191], v[4:7]
	v_mfma_f32_16x16x32_bf16 v[0:3], v[210:213], v[188:191], v[0:3]
	v_mfma_f32_16x16x32_bf16 v[44:47], v[200:203], v[148:151], v[44:47]
	v_mfma_f32_16x16x32_bf16 v[40:43], v[214:217], v[148:151], v[40:43]
	v_mfma_f32_16x16x32_bf16 v[28:31], v[200:203], v[156:159], v[28:31]
	v_mfma_f32_16x16x32_bf16 v[24:27], v[214:217], v[156:159], v[24:27]
	v_mfma_f32_16x16x32_bf16 v[12:15], v[200:203], v[184:187], v[12:15]
	v_mfma_f32_16x16x32_bf16 v[8:11], v[214:217], v[184:187], v[8:11]
	v_mfma_f32_16x16x32_bf16 v[4:7], v[200:203], v[192:195], v[4:7]
	v_mfma_f32_16x16x32_bf16 v[0:3], v[214:217], v[192:195], v[0:3]
	s_barrier
	ds_read_b128 v[128:131], v208 offset:32768
	ds_read_b128 v[136:139], v208 offset:34816
	ds_read_b128 v[132:135], v208 offset:33792
	ds_read_b128 v[140:143], v208 offset:35840
	s_mov_b32 m0, s56
	ds_read_b128 v[144:147], v209 offset:32768
	ds_read_b128 v[152:155], v209 offset:34816
	ds_read_b128 v[180:183], v209 offset:36864
	ds_read_b128 v[188:191], v209 offset:38912
	ds_read_b128 v[148:151], v209 offset:33792
	ds_read_b128 v[156:159], v209 offset:35840
	ds_read_b128 v[184:187], v209 offset:37888
	global_load_lds_dwordx4 v160, s[8:9]
	s_mov_b32 m0, s57
	ds_read_b128 v[192:195], v209 offset:39936
	global_load_lds_dwordx4 v162, s[8:9]
	s_waitcnt lgkmcnt(8)
	s_barrier
	s_waitcnt lgkmcnt(4)
	v_mfma_f32_16x16x32_bf16 v[124:127], v[128:131], v[144:147], v[124:127]
	v_mfma_f32_16x16x32_bf16 v[120:123], v[136:139], v[144:147], v[120:123]
	v_mfma_f32_16x16x32_bf16 v[116:119], v[128:131], v[152:155], v[116:119]
	v_mfma_f32_16x16x32_bf16 v[112:115], v[136:139], v[152:155], v[112:115]
	v_mfma_f32_16x16x32_bf16 v[100:103], v[128:131], v[180:183], v[100:103]
	v_mfma_f32_16x16x32_bf16 v[96:99], v[136:139], v[180:183], v[96:99]
	v_mfma_f32_16x16x32_bf16 v[84:87], v[128:131], v[188:191], v[84:87]
	v_mfma_f32_16x16x32_bf16 v[80:83], v[136:139], v[188:191], v[80:83]
	s_waitcnt lgkmcnt(0)
	v_mfma_f32_16x16x32_bf16 v[124:127], v[132:135], v[148:151], v[124:127]
	v_mfma_f32_16x16x32_bf16 v[120:123], v[140:143], v[148:151], v[120:123]
	v_mfma_f32_16x16x32_bf16 v[116:119], v[132:135], v[156:159], v[116:119]
	v_mfma_f32_16x16x32_bf16 v[112:115], v[140:143], v[156:159], v[112:115]
	v_mfma_f32_16x16x32_bf16 v[100:103], v[132:135], v[184:187], v[100:103]
	v_mfma_f32_16x16x32_bf16 v[96:99], v[140:143], v[184:187], v[96:99]
	v_mfma_f32_16x16x32_bf16 v[84:87], v[132:135], v[192:195], v[84:87]
	v_mfma_f32_16x16x32_bf16 v[80:83], v[140:143], v[192:195], v[80:83]
	s_barrier
	s_add_i32 m0, s54, 0x18000
	ds_read_b128 v[196:199], v208 offset:49152
	ds_read_b128 v[210:213], v208 offset:51200
	ds_read_b128 v[200:203], v208 offset:50176
	global_load_lds_dwordx4 v160, s[98:99]
	s_add_i32 m0, s54, 0x1a000
	ds_read_b128 v[214:217], v208 offset:52224
	global_load_lds_dwordx4 v162, s[98:99]
	s_barrier
	s_waitcnt lgkmcnt(2)
	v_mfma_f32_16x16x32_bf16 v[108:111], v[196:199], v[144:147], v[108:111]
	v_mfma_f32_16x16x32_bf16 v[104:107], v[210:213], v[144:147], v[104:107]
	v_mfma_f32_16x16x32_bf16 v[92:95], v[196:199], v[152:155], v[92:95]
	v_mfma_f32_16x16x32_bf16 v[88:91], v[210:213], v[152:155], v[88:91]
	v_mfma_f32_16x16x32_bf16 v[76:79], v[196:199], v[180:183], v[76:79]
	v_mfma_f32_16x16x32_bf16 v[72:75], v[210:213], v[180:183], v[72:75]
	v_mfma_f32_16x16x32_bf16 v[68:71], v[196:199], v[188:191], v[68:71]
	v_mfma_f32_16x16x32_bf16 v[64:67], v[210:213], v[188:191], v[64:67]
	s_waitcnt lgkmcnt(0)
	v_mfma_f32_16x16x32_bf16 v[108:111], v[200:203], v[148:151], v[108:111]
	v_mfma_f32_16x16x32_bf16 v[104:107], v[214:217], v[148:151], v[104:107]
	v_mfma_f32_16x16x32_bf16 v[92:95], v[200:203], v[156:159], v[92:95]
	v_mfma_f32_16x16x32_bf16 v[88:91], v[214:217], v[156:159], v[88:91]
	v_mfma_f32_16x16x32_bf16 v[76:79], v[200:203], v[184:187], v[76:79]
	v_mfma_f32_16x16x32_bf16 v[72:75], v[214:217], v[184:187], v[72:75]
	v_mfma_f32_16x16x32_bf16 v[68:71], v[200:203], v[192:195], v[68:71]
	v_mfma_f32_16x16x32_bf16 v[64:67], v[214:217], v[192:195], v[64:67]
	s_mov_b32 m0, s60
	s_barrier
	ds_read_b128 v[144:147], v209 offset:49152
	ds_read_b128 v[152:155], v209 offset:51200
	ds_read_b128 v[180:183], v209 offset:53248
	ds_read_b128 v[188:191], v209 offset:55296
	ds_read_b128 v[148:151], v209 offset:50176
	ds_read_b128 v[156:159], v209 offset:52224
	ds_read_b128 v[184:187], v209 offset:54272
	global_load_lds_dwordx4 v160, s[100:101]
	s_mov_b32 m0, s61
	ds_read_b128 v[192:195], v209 offset:56320
	global_load_lds_dwordx4 v162, s[100:101]
	s_barrier
	s_waitcnt lgkmcnt(4)
	v_mfma_f32_16x16x32_bf16 v[60:63], v[128:131], v[144:147], v[60:63]
	v_mfma_f32_16x16x32_bf16 v[56:59], v[136:139], v[144:147], v[56:59]
	v_mfma_f32_16x16x32_bf16 v[52:55], v[128:131], v[152:155], v[52:55]
	v_mfma_f32_16x16x32_bf16 v[48:51], v[136:139], v[152:155], v[48:51]
	v_mfma_f32_16x16x32_bf16 v[36:39], v[128:131], v[180:183], v[36:39]
	v_mfma_f32_16x16x32_bf16 v[32:35], v[136:139], v[180:183], v[32:35]
	v_mfma_f32_16x16x32_bf16 v[20:23], v[128:131], v[188:191], v[20:23]
	v_mfma_f32_16x16x32_bf16 v[16:19], v[136:139], v[188:191], v[16:19]
	s_waitcnt lgkmcnt(0)
	v_mfma_f32_16x16x32_bf16 v[60:63], v[132:135], v[148:151], v[60:63]
	v_mfma_f32_16x16x32_bf16 v[56:59], v[140:143], v[148:151], v[56:59]
	v_mfma_f32_16x16x32_bf16 v[52:55], v[132:135], v[156:159], v[52:55]
	v_mfma_f32_16x16x32_bf16 v[48:51], v[140:143], v[156:159], v[48:51]
	v_mfma_f32_16x16x32_bf16 v[36:39], v[132:135], v[184:187], v[36:39]
	v_mfma_f32_16x16x32_bf16 v[32:35], v[140:143], v[184:187], v[32:35]
	v_mfma_f32_16x16x32_bf16 v[20:23], v[132:135], v[192:195], v[20:23]
	v_mfma_f32_16x16x32_bf16 v[16:19], v[140:143], v[192:195], v[16:19]
	s_barrier
	s_add_i32 m0, s54, 0x1c000
	s_add_u32 s2, s2, 0x40080
	s_addc_u32 s3, s3, 0
	global_load_lds_dwordx4 v160, s[2:3]
	s_add_i32 m0, s54, 0x1e000
	s_add_i32 s41, s41, 2
	global_load_lds_dwordx4 v162, s[2:3]
	s_waitcnt vmcnt(6)
	s_barrier
	v_mfma_f32_16x16x32_bf16 v[44:47], v[196:199], v[144:147], v[44:47]
	v_mfma_f32_16x16x32_bf16 v[40:43], v[210:213], v[144:147], v[40:43]
	v_mfma_f32_16x16x32_bf16 v[28:31], v[196:199], v[152:155], v[28:31]
	v_mfma_f32_16x16x32_bf16 v[24:27], v[210:213], v[152:155], v[24:27]
	v_mfma_f32_16x16x32_bf16 v[12:15], v[196:199], v[180:183], v[12:15]
	v_mfma_f32_16x16x32_bf16 v[8:11], v[210:213], v[180:183], v[8:11]
	v_mfma_f32_16x16x32_bf16 v[4:7], v[196:199], v[188:191], v[4:7]
	v_mfma_f32_16x16x32_bf16 v[0:3], v[210:213], v[188:191], v[0:3]
	v_mfma_f32_16x16x32_bf16 v[44:47], v[200:203], v[148:151], v[44:47]
	v_mfma_f32_16x16x32_bf16 v[40:43], v[214:217], v[148:151], v[40:43]
	v_mfma_f32_16x16x32_bf16 v[28:31], v[200:203], v[156:159], v[28:31]
	v_mfma_f32_16x16x32_bf16 v[24:27], v[214:217], v[156:159], v[24:27]
	v_mfma_f32_16x16x32_bf16 v[12:15], v[200:203], v[184:187], v[12:15]
	v_mfma_f32_16x16x32_bf16 v[8:11], v[214:217], v[184:187], v[8:11]
	v_mfma_f32_16x16x32_bf16 v[4:7], v[200:203], v[192:195], v[4:7]
	v_mfma_f32_16x16x32_bf16 v[0:3], v[214:217], v[192:195], v[0:3]
	s_add_u32 s6, s6, 0x100
	s_addc_u32 s7, s7, 0
	s_add_u32 s39, s39, 0x100
	s_addc_u32 s40, s40, 0
	s_cmp_gt_u32 s41, 13
	s_barrier
	s_cbranch_scc0 .LBB0_355
	s_lshl_b32 s1, s0, 8
	v_mov_b32_e32 v211, v206
	v_mov_b32_e32 v210, v207
	s_add_i32 s1, s1, s59
	s_cmp_lt_i32 s20, 3
	v_add_u32_e32 v180, s1, v211
	s_mov_b64 s[2:3], -1
	s_cbranch_scc0 .LBB0_490
	s_cmp_gt_i32 s0, 15
	s_cselect_b64 s[2:3], -1, 0
	s_cmp_lt_i32 s0, 16
	s_cselect_b64 s[38:39], -1, 0
	s_cmp_eq_u32 s20, 2
	s_cselect_b64 s[8:9], -1, 0
	s_cmp_lg_u32 s20, 2
	s_cselect_b64 s[0:1], -1, 0
	s_and_b64 s[40:41], s[8:9], s[22:23]
	v_lshlrev_b32_e32 v182, 2, v210
	s_mov_b64 s[6:7], -1
	s_and_b64 vcc, exec, s[40:41]
	v_ashrrev_i32_e32 v183, 31, v182
	s_cbranch_vccnz .LBB0_447
	s_and_b64 s[6:7], s[8:9], exec
	s_cselect_b32 s6, s46, s44
	s_cselect_b32 s7, s47, s45
	v_mov_b32_e32 v128, s7
	v_mov_b32_e32 v129, s6
	v_lshl_add_u64 v[128:129], v[182:183], 2, v[128:129]
	global_load_dwordx4 v[140:143], v[128:129], off
	global_load_dwordx4 v[136:139], v[128:129], off offset:64
	global_load_dwordx4 v[132:135], v[128:129], off offset:128
	s_nop 0
	global_load_dwordx4 v[128:131], v[128:129], off offset:192
	v_mul_f32_e32 v144, v125, v125
	v_mul_f32_e32 v145, v127, v127
	v_fmac_f32_e32 v144, v124, v124
	v_fmac_f32_e32 v145, v126, v126
	v_add_f32_e32 v144, v144, v145
	v_mul_f32_e32 v145, v121, v121
	v_mul_f32_e32 v146, v123, v123
	v_fmac_f32_e32 v145, v120, v120
	v_fmac_f32_e32 v146, v122, v122
	v_add_f32_e32 v145, v145, v146
	v_add_f32_e32 v144, v144, v145
	v_mul_f32_e32 v145, v109, v109
	v_mul_f32_e32 v146, v111, v111
	v_fmac_f32_e32 v145, v108, v108
	v_fmac_f32_e32 v146, v110, v110
	v_add_f32_e32 v145, v145, v146
	v_add_f32_e32 v144, v144, v145
	v_mul_f32_e32 v145, v105, v105
	v_mul_f32_e32 v146, v107, v107
	v_fmac_f32_e32 v145, v104, v104
	v_fmac_f32_e32 v146, v106, v106
	v_add_f32_e32 v145, v145, v146
	v_add_f32_e32 v144, v144, v145
	v_mov_b32_e32 v145, v144
	s_nop 1
	v_permlane16_swap_b32_e32 v144, v145
	v_add_f32_e32 v144, v144, v145
	v_mov_b32_e32 v145, v144
	s_nop 1
	v_permlane32_swap_b32_e32 v144, v145
	v_add_f32_e32 v144, v144, v145
	v_fmamk_f32 v144, v144, 0x3c800000, v225
	v_cmp_gt_f32_e32 vcc, s93, v144
	v_mul_f32_e32 v145, 0x4b800000, v144
	v_and_b32_e32 v202, 63, v211
	v_cndmask_b32_e32 v144, v144, v145, vcc
	v_rsq_f32_e32 v144, v144
	v_cndmask_b32_e64 v168, 0, 1, s[2:3]
	v_cmp_ne_u32_e64 s[6:7], 1, v168
	v_lshlrev_b32_e32 v186, 7, v202
	v_mul_f32_e32 v145, 0x45800000, v144
	v_cndmask_b32_e32 v152, v144, v145, vcc
	v_pk_mul_f32 v[144:145], v[124:125], v[152:153] op_sel_hi:[1,0]
	v_pk_mul_f32 v[146:147], v[126:127], v[152:153] op_sel_hi:[1,0]
	v_pk_mul_f32 v[148:149], v[108:109], v[152:153] op_sel_hi:[1,0]
	v_pk_mul_f32 v[150:151], v[110:111], v[152:153] op_sel_hi:[1,0]
	v_pk_mul_f32 v[184:185], v[104:105], v[152:153] op_sel_hi:[1,0]
	s_andn2_b64 vcc, exec, s[2:3]
	s_waitcnt vmcnt(0)
	v_pk_mul_f32 v[158:159], v[142:143], v[146:147]
	v_pk_mul_f32 v[156:157], v[140:141], v[144:145]
	v_pk_mul_f32 v[144:145], v[120:121], v[152:153] op_sel_hi:[1,0]
	v_pk_mul_f32 v[146:147], v[122:123], v[152:153] op_sel_hi:[1,0]
	v_pk_mul_f32 v[152:153], v[106:107], v[152:153] op_sel_hi:[1,0]
	v_pk_mul_f32 v[146:147], v[138:139], v[146:147]
	v_pk_mul_f32 v[144:145], v[136:137], v[144:145]
	v_pk_mul_f32 v[150:151], v[134:135], v[150:151]
	v_pk_mul_f32 v[148:149], v[132:133], v[148:149]
	v_pk_mul_f32 v[154:155], v[130:131], v[152:153]
	v_pk_mul_f32 v[152:153], v[128:129], v[184:185]
	v_lshl_add_u64 v[184:185], v[182:183], 3, s[18:19]
	s_cbranch_vccnz .LBB0_360
	v_lshlrev_b32_e32 v168, 1, v180
	v_and_b32_e32 v168, 0xf80, v168
	v_lshl_add_u64 v[188:189], v[184:185], 0, v[168:169]
	global_load_dwordx4 v[190:193], v[188:189], off offset:16
	global_load_dwordx4 v[194:197], v[188:189], off
	v_mov_b32_e32 v187, v169
	s_waitcnt vmcnt(0)
	v_mul_f32_e32 v198, v158, v190
	v_mov_b32_e32 v188, v194
	v_mov_b32_e32 v189, v196
	v_mov_b32_e32 v196, v195
	v_mul_f32_e32 v200, v146, v191
	v_mul_f32_e32 v204, v146, v190
	v_mul_f32_e32 v212, v158, v191
	v_mov_b32_e32 v146, v159
	v_mov_b32_e32 v158, v147
	v_pk_mul_f32 v[194:195], v[144:145], v[196:197]
	v_pk_mul_f32 v[144:145], v[144:145], v[188:189]
	v_pk_mul_f32 v[190:191], v[146:147], v[192:193]
	v_pk_mul_f32 v[146:147], v[158:159], v[192:193]
	v_lshl_add_u64 v[192:193], v[184:185], 0, v[186:187]
	v_mov_b32_e32 v199, v190
	v_mov_b32_e32 v201, v191
	v_pk_fma_f32 v[190:191], v[156:157], v[188:189], v[194:195] neg_lo:[0,0,1] neg_hi:[0,0,1]
	v_pk_fma_f32 v[144:145], v[156:157], v[196:197], v[144:145]
	global_load_dwordx4 v[156:159], v[192:193], off offset:16
	s_nop 0
	global_load_dwordx4 v[192:195], v[192:193], off
	v_pk_add_f32 v[188:189], v[198:199], v[200:201] neg_lo:[0,1] neg_hi:[0,1]
	v_mov_b32_e32 v213, v147
	v_mov_b32_e32 v205, v146
	v_pk_add_f32 v[146:147], v[212:213], v[204:205]
	s_waitcnt vmcnt(0)
	v_mul_f32_e32 v198, v150, v156
	v_mul_f32_e32 v200, v154, v157
	v_mul_f32_e32 v156, v154, v156
	v_mov_b32_e32 v154, v151
	v_mov_b32_e32 v197, v194
	v_mov_b32_e32 v194, v193
	v_mul_f32_e32 v204, v150, v157
	v_pk_mul_f32 v[212:213], v[154:155], v[158:159]
	v_mov_b32_e32 v150, v155
	v_mov_b32_e32 v196, v192
	v_pk_mul_f32 v[192:193], v[152:153], v[194:195]
	v_mov_b32_e32 v199, v212
	v_mov_b32_e32 v201, v213
	v_pk_mul_f32 v[150:151], v[150:151], v[158:159]
	v_pk_mul_f32 v[152:153], v[152:153], v[196:197]
	v_pk_fma_f32 v[192:193], v[148:149], v[196:197], v[192:193] neg_lo:[0,0,1] neg_hi:[0,0,1]
	v_pk_add_f32 v[196:197], v[198:199], v[200:201] neg_lo:[0,1] neg_hi:[0,1]
	v_mov_b32_e32 v205, v151
	v_mov_b32_e32 v157, v150
	v_pk_fma_f32 v[152:153], v[148:149], v[194:195], v[152:153]
	v_pk_add_f32 v[154:155], v[204:205], v[156:157]
	v_mov_b32_e32 v148, v192
	v_mov_b32_e32 v149, v193
	v_mov_b32_e32 v150, v196
	v_mov_b32_e32 v151, v197
	v_mov_b32_e32 v156, v190
	v_mov_b32_e32 v157, v191
	v_mov_b32_e32 v158, v188
	v_mov_b32_e32 v159, v189

.LBB0_677:
	s_ashr_i32 s23, s22, 31
	v_cmp_lt_i64_e32 vcc, s[24:25], v[174:175]
	s_lshl_b64 s[24:25], s[22:23], 19
	s_add_u32 s24, s36, s24
	s_addc_u32 s25, s37, s25
	s_and_b64 s[26:27], vcc, exec
	s_cselect_b32 s1, s25, s9
	s_cselect_b32 s7, s24, s8
	s_ashr_i32 s21, s20, 31
	s_lshl_b64 s[26:27], s[20:21], 19
	s_add_u32 s26, s38, s26
	s_addc_u32 s27, s39, s27
	s_and_b64 s[28:29], vcc, exec
	s_cselect_b32 s21, s27, s3
	s_cselect_b32 s23, s26, s2
	s_add_u32 s8, s8, 0x40080
	s_addc_u32 s9, s9, 0
	s_add_u32 s56, s2, 0x100
	s_addc_u32 s57, s3, 0
	s_mov_b32 s58, -2
	s_add_u32 s2, s8, 0xfffc0080
	s_addc_u32 s3, s9, -1
	ds_read_b128 v[48:51], v206
	ds_read_b128 v[60:63], v206 offset:2048
	ds_read_b128 v[52:55], v206 offset:1024
	ds_read_b128 v[68:71], v206 offset:3072
	s_cmp_eq_u32 s58, 12
	s_cselect_b32 s29, s1, s3
	s_cselect_b32 s28, s7, s2
	s_cselect_b32 s3, s21, s57
	s_cselect_b32 s2, s23, s56
	s_add_i32 m0, s41, 0xc000
	ds_read_b128 v[72:75], v207
	ds_read_b128 v[80:83], v207 offset:2048
	ds_read_b128 v[160:163], v207 offset:4096
	ds_read_b128 v[192:195], v207 offset:6144
	ds_read_b128 v[76:79], v207 offset:1024
	ds_read_b128 v[84:87], v207 offset:3072
	ds_read_b128 v[164:167], v207 offset:5120
	global_load_lds_dwordx4 v188, s[8:9]
	s_add_i32 m0, s41, 0xe000
	ds_read_b128 v[196:199], v207 offset:7168
	global_load_lds_dwordx4 v190, s[8:9]
	s_waitcnt lgkmcnt(8)
	s_barrier
	s_waitcnt lgkmcnt(4)
	v_mfma_f32_16x16x32_bf16 v[156:159], v[48:51], v[72:75], 0
	v_mfma_f32_16x16x32_bf16 v[152:155], v[60:63], v[72:75], 0
	v_mfma_f32_16x16x32_bf16 v[140:143], v[48:51], v[80:83], 0
	v_mfma_f32_16x16x32_bf16 v[136:139], v[60:63], v[80:83], 0
	v_mfma_f32_16x16x32_bf16 v[124:127], v[48:51], v[160:163], 0
	v_mfma_f32_16x16x32_bf16 v[120:123], v[60:63], v[160:163], 0
	v_mfma_f32_16x16x32_bf16 v[108:111], v[48:51], v[192:195], 0
	v_mfma_f32_16x16x32_bf16 v[104:107], v[60:63], v[192:195], 0
	s_waitcnt lgkmcnt(0)
	v_mfma_f32_16x16x32_bf16 v[156:159], v[52:55], v[76:79], v[156:159]
	v_mfma_f32_16x16x32_bf16 v[152:155], v[68:71], v[76:79], v[152:155]
	v_mfma_f32_16x16x32_bf16 v[140:143], v[52:55], v[84:87], v[140:143]
	v_mfma_f32_16x16x32_bf16 v[136:139], v[68:71], v[84:87], v[136:139]
	v_mfma_f32_16x16x32_bf16 v[124:127], v[52:55], v[164:167], v[124:127]
	v_mfma_f32_16x16x32_bf16 v[120:123], v[68:71], v[164:167], v[120:123]
	v_mfma_f32_16x16x32_bf16 v[108:111], v[52:55], v[196:199], v[108:111]
	v_mfma_f32_16x16x32_bf16 v[104:107], v[68:71], v[196:199], v[104:107]
	s_barrier
	s_add_u32 s98, s2, 0x80
	s_addc_u32 s99, s3, 0
	s_add_i32 m0, s40, 0x10000
	ds_read_b128 v[200:203], v206 offset:16384
	ds_read_b128 v[212:215], v206 offset:18432
	ds_read_b128 v[208:211], v206 offset:17408
	global_load_lds_dwordx4 v182, s[2:3]
	s_add_i32 m0, s40, 0x12000
	ds_read_b128 v[216:219], v206 offset:19456
	global_load_lds_dwordx4 v186, s[2:3]
	s_barrier
	s_waitcnt lgkmcnt(2)
	v_mfma_f32_16x16x32_bf16 v[148:151], v[200:203], v[72:75], 0
	v_mfma_f32_16x16x32_bf16 v[72:75], v[212:215], v[72:75], 0
	s_waitcnt lgkmcnt(0)
	v_mfma_f32_16x16x32_bf16 v[148:151], v[208:211], v[76:79], v[148:151]
	v_mfma_f32_16x16x32_bf16 v[72:75], v[216:219], v[76:79], v[72:75]
	v_mfma_f32_16x16x32_bf16 v[76:79], v[200:203], v[80:83], 0
	v_mfma_f32_16x16x32_bf16 v[80:83], v[212:215], v[80:83], 0
	v_mfma_f32_16x16x32_bf16 v[112:115], v[212:215], v[160:163], 0
	v_mfma_f32_16x16x32_bf16 v[100:103], v[200:203], v[192:195], 0
	v_mfma_f32_16x16x32_bf16 v[96:99], v[212:215], v[192:195], 0
	v_mfma_f32_16x16x32_bf16 v[76:79], v[208:211], v[84:87], v[76:79]
	v_mfma_f32_16x16x32_bf16 v[80:83], v[216:219], v[84:87], v[80:83]
	v_mfma_f32_16x16x32_bf16 v[84:87], v[200:203], v[160:163], 0
	v_mfma_f32_16x16x32_bf16 v[112:115], v[216:219], v[164:167], v[112:115]
	v_mfma_f32_16x16x32_bf16 v[100:103], v[208:211], v[196:199], v[100:103]
	v_mfma_f32_16x16x32_bf16 v[96:99], v[216:219], v[196:199], v[96:99]
	v_mfma_f32_16x16x32_bf16 v[84:87], v[208:211], v[164:167], v[84:87]
	s_mov_b32 m0, s41
	s_add_u32 s100, s28, 0x80
	s_addc_u32 s101, s29, 0
	s_barrier
	ds_read_b128 v[116:119], v207 offset:16384
	ds_read_b128 v[132:135], v207 offset:18432
	ds_read_b128 v[160:163], v207 offset:20480
	ds_read_b128 v[192:195], v207 offset:22528
	ds_read_b128 v[128:131], v207 offset:17408
	ds_read_b128 v[144:147], v207 offset:19456
	ds_read_b128 v[164:167], v207 offset:21504
	global_load_lds_dwordx4 v180, s[28:29]
	s_mov_b32 m0, s42
	ds_read_b128 v[196:199], v207 offset:23552
	global_load_lds_dwordx4 v184, s[28:29]
	s_barrier
	s_waitcnt lgkmcnt(4)
	v_mfma_f32_16x16x32_bf16 v[92:95], v[48:51], v[116:119], 0
	v_mfma_f32_16x16x32_bf16 v[88:91], v[60:63], v[116:119], 0
	v_mfma_f32_16x16x32_bf16 v[44:47], v[48:51], v[132:135], 0
	v_mfma_f32_16x16x32_bf16 v[40:43], v[60:63], v[132:135], 0
	v_mfma_f32_16x16x32_bf16 v[28:31], v[48:51], v[160:163], 0
	v_mfma_f32_16x16x32_bf16 v[24:27], v[60:63], v[160:163], 0
	v_mfma_f32_16x16x32_bf16 v[12:15], v[48:51], v[192:195], 0
	v_mfma_f32_16x16x32_bf16 v[8:11], v[60:63], v[192:195], 0
	s_waitcnt lgkmcnt(0)
	v_mfma_f32_16x16x32_bf16 v[92:95], v[52:55], v[128:131], v[92:95]
	v_mfma_f32_16x16x32_bf16 v[88:91], v[68:71], v[128:131], v[88:91]
	v_mfma_f32_16x16x32_bf16 v[44:47], v[52:55], v[144:147], v[44:47]
	v_mfma_f32_16x16x32_bf16 v[40:43], v[68:71], v[144:147], v[40:43]
	v_mfma_f32_16x16x32_bf16 v[28:31], v[52:55], v[164:167], v[28:31]
	v_mfma_f32_16x16x32_bf16 v[24:27], v[68:71], v[164:167], v[24:27]
	v_mfma_f32_16x16x32_bf16 v[12:15], v[52:55], v[196:199], v[12:15]
	v_mfma_f32_16x16x32_bf16 v[8:11], v[68:71], v[196:199], v[8:11]
	s_barrier
	s_add_i32 m0, s40, 0x14000
	s_add_u32 s60, s2, 0x40000
	s_addc_u32 s61, s3, 0
	global_load_lds_dwordx4 v182, s[60:61]
	s_add_i32 m0, s40, 0x16000
	s_add_u32 s28, s28, 0x40000
	s_addc_u32 s29, s29, 0
	global_load_lds_dwordx4 v186, s[60:61]
	s_waitcnt vmcnt(6)
	s_barrier
	v_mfma_f32_16x16x32_bf16 v[36:39], v[200:203], v[132:135], 0
	v_mfma_f32_16x16x32_bf16 v[32:35], v[212:215], v[132:135], 0
	v_mfma_f32_16x16x32_bf16 v[20:23], v[200:203], v[160:163], 0
	v_mfma_f32_16x16x32_bf16 v[16:19], v[212:215], v[160:163], 0
	v_mfma_f32_16x16x32_bf16 v[4:7], v[200:203], v[192:195], 0
	v_mfma_f32_16x16x32_bf16 v[0:3], v[212:215], v[192:195], 0
	v_mfma_f32_16x16x32_bf16 v[48:51], v[200:203], v[116:119], 0
	v_mfma_f32_16x16x32_bf16 v[52:55], v[212:215], v[116:119], 0
	v_mfma_f32_16x16x32_bf16 v[36:39], v[208:211], v[144:147], v[36:39]
	v_mfma_f32_16x16x32_bf16 v[32:35], v[216:219], v[144:147], v[32:35]
	v_mfma_f32_16x16x32_bf16 v[20:23], v[208:211], v[164:167], v[20:23]
	v_mfma_f32_16x16x32_bf16 v[16:19], v[216:219], v[164:167], v[16:19]
	v_mfma_f32_16x16x32_bf16 v[4:7], v[208:211], v[196:199], v[4:7]
	v_mfma_f32_16x16x32_bf16 v[0:3], v[216:219], v[196:199], v[0:3]
	v_mfma_f32_16x16x32_bf16 v[48:51], v[208:211], v[128:131], v[48:51]
	v_mfma_f32_16x16x32_bf16 v[52:55], v[216:219], v[128:131], v[52:55]
	s_barrier
	ds_read_b128 v[56:59], v206 offset:32768
	ds_read_b128 v[60:63], v206 offset:33792
	ds_read_b128 v[64:67], v206 offset:34816
	ds_read_b128 v[68:71], v206 offset:35840
	s_mov_b32 m0, s43
	ds_read_b128 v[116:119], v207 offset:32768
	ds_read_b128 v[128:131], v207 offset:33792
	ds_read_b128 v[160:163], v207 offset:34816
	ds_read_b128 v[164:167], v207 offset:35840
	ds_read_b128 v[192:195], v207 offset:36864
	ds_read_b128 v[200:203], v207 offset:38912
	ds_read_b128 v[196:199], v207 offset:37888
	global_load_lds_dwordx4 v180, s[28:29]
	s_mov_b32 m0, s44
	ds_read_b128 v[208:211], v207 offset:39936
	global_load_lds_dwordx4 v184, s[28:29]
	s_waitcnt lgkmcnt(8)
	s_barrier
	s_waitcnt lgkmcnt(4)
	v_mfma_f32_16x16x32_bf16 v[132:135], v[56:59], v[116:119], v[156:159]
	v_mfma_f32_16x16x32_bf16 v[156:159], v[60:63], v[128:131], v[132:135]
	v_mfma_f32_16x16x32_bf16 v[132:135], v[64:67], v[116:119], v[152:155]
	v_mfma_f32_16x16x32_bf16 v[152:155], v[68:71], v[128:131], v[132:135]
	v_mfma_f32_16x16x32_bf16 v[132:135], v[56:59], v[160:163], v[140:143]
	v_mfma_f32_16x16x32_bf16 v[140:143], v[60:63], v[164:167], v[132:135]
	v_mfma_f32_16x16x32_bf16 v[132:135], v[64:67], v[160:163], v[136:139]
	s_waitcnt lgkmcnt(0)
	v_mfma_f32_16x16x32_bf16 v[124:127], v[56:59], v[192:195], v[124:127]
	v_mfma_f32_16x16x32_bf16 v[120:123], v[64:67], v[192:195], v[120:123]
	v_mfma_f32_16x16x32_bf16 v[108:111], v[56:59], v[200:203], v[108:111]
	v_mfma_f32_16x16x32_bf16 v[104:107], v[64:67], v[200:203], v[104:107]
	v_mfma_f32_16x16x32_bf16 v[136:139], v[68:71], v[164:167], v[132:135]
	v_mfma_f32_16x16x32_bf16 v[124:127], v[60:63], v[196:199], v[124:127]
	v_mfma_f32_16x16x32_bf16 v[120:123], v[68:71], v[196:199], v[120:123]
	v_mfma_f32_16x16x32_bf16 v[108:111], v[60:63], v[208:211], v[108:111]
	v_mfma_f32_16x16x32_bf16 v[104:107], v[68:71], v[208:211], v[104:107]
	s_barrier
	ds_read_b128 v[220:223], v206 offset:51200
	ds_read_b128 v[212:215], v206 offset:49152
	s_add_i32 m0, s40, 0x18000
	ds_read_b128 v[236:239], v206 offset:52224
	global_load_lds_dwordx4 v182, s[98:99]
	s_add_i32 m0, s40, 0x1a000
	ds_read_b128 v[216:219], v206 offset:50176
	global_load_lds_dwordx4 v186, s[98:99]
	s_barrier
	s_waitcnt lgkmcnt(2)
	v_mfma_f32_16x16x32_bf16 v[72:75], v[220:223], v[116:119], v[72:75]
	v_mfma_f32_16x16x32_bf16 v[132:135], v[212:215], v[116:119], v[148:151]
	s_waitcnt lgkmcnt(0)
	v_mfma_f32_16x16x32_bf16 v[144:147], v[236:239], v[128:131], v[72:75]
	v_mfma_f32_16x16x32_bf16 v[72:75], v[212:215], v[160:163], v[76:79]
	v_mfma_f32_16x16x32_bf16 v[148:151], v[216:219], v[128:131], v[132:135]
	v_mfma_f32_16x16x32_bf16 v[132:135], v[216:219], v[164:167], v[72:75]
	v_mfma_f32_16x16x32_bf16 v[72:75], v[220:223], v[160:163], v[80:83]
	v_mfma_f32_16x16x32_bf16 v[128:131], v[236:239], v[164:167], v[72:75]
	v_mfma_f32_16x16x32_bf16 v[72:75], v[212:215], v[192:195], v[84:87]
	v_mfma_f32_16x16x32_bf16 v[116:119], v[216:219], v[196:199], v[72:75]
	v_mfma_f32_16x16x32_bf16 v[72:75], v[220:223], v[192:195], v[112:115]
	v_mfma_f32_16x16x32_bf16 v[112:115], v[236:239], v[196:199], v[72:75]
	v_mfma_f32_16x16x32_bf16 v[72:75], v[212:215], v[200:203], v[100:103]
	v_mfma_f32_16x16x32_bf16 v[100:103], v[216:219], v[208:211], v[72:75]
	v_mfma_f32_16x16x32_bf16 v[72:75], v[220:223], v[200:203], v[96:99]
	v_mfma_f32_16x16x32_bf16 v[96:99], v[236:239], v[208:211], v[72:75]
	s_mov_b32 m0, s53
	s_barrier
	s_nop 2
	ds_read_b128 v[72:75], v207 offset:49152
	ds_read_b128 v[80:83], v207 offset:51200
	ds_read_b128 v[160:163], v207 offset:53248
	ds_read_b128 v[192:195], v207 offset:55296
	ds_read_b128 v[76:79], v207 offset:50176
	ds_read_b128 v[84:87], v207 offset:52224
	ds_read_b128 v[164:167], v207 offset:54272
	global_load_lds_dwordx4 v180, s[100:101]
	s_mov_b32 m0, s54
	ds_read_b128 v[196:199], v207 offset:56320
	global_load_lds_dwordx4 v184, s[100:101]
	s_barrier
	s_waitcnt lgkmcnt(4)
	v_mfma_f32_16x16x32_bf16 v[92:95], v[56:59], v[72:75], v[92:95]
	v_mfma_f32_16x16x32_bf16 v[88:91], v[64:67], v[72:75], v[88:91]
	v_mfma_f32_16x16x32_bf16 v[44:47], v[56:59], v[80:83], v[44:47]
	v_mfma_f32_16x16x32_bf16 v[40:43], v[64:67], v[80:83], v[40:43]
	v_mfma_f32_16x16x32_bf16 v[28:31], v[56:59], v[160:163], v[28:31]
	v_mfma_f32_16x16x32_bf16 v[24:27], v[64:67], v[160:163], v[24:27]
	v_mfma_f32_16x16x32_bf16 v[12:15], v[56:59], v[192:195], v[12:15]
	v_mfma_f32_16x16x32_bf16 v[8:11], v[64:67], v[192:195], v[8:11]
	s_waitcnt lgkmcnt(0)
	v_mfma_f32_16x16x32_bf16 v[92:95], v[60:63], v[76:79], v[92:95]
	v_mfma_f32_16x16x32_bf16 v[88:91], v[68:71], v[76:79], v[88:91]
	v_mfma_f32_16x16x32_bf16 v[44:47], v[60:63], v[84:87], v[44:47]
	v_mfma_f32_16x16x32_bf16 v[40:43], v[68:71], v[84:87], v[40:43]
	v_mfma_f32_16x16x32_bf16 v[28:31], v[60:63], v[164:167], v[28:31]
	v_mfma_f32_16x16x32_bf16 v[24:27], v[68:71], v[164:167], v[24:27]
	v_mfma_f32_16x16x32_bf16 v[12:15], v[60:63], v[196:199], v[12:15]
	v_mfma_f32_16x16x32_bf16 v[8:11], v[68:71], v[196:199], v[8:11]
	s_barrier
	s_add_i32 m0, s40, 0x1c000
	s_add_u32 s2, s2, 0x40080
	s_addc_u32 s3, s3, 0
	global_load_lds_dwordx4 v182, s[2:3]
	s_add_i32 m0, s40, 0x1e000
	s_add_i32 s58, s58, 2
	global_load_lds_dwordx4 v186, s[2:3]
	s_waitcnt vmcnt(6)
	s_barrier
	v_mfma_f32_16x16x32_bf16 v[48:51], v[212:215], v[72:75], v[48:51]
	v_mfma_f32_16x16x32_bf16 v[64:67], v[216:219], v[76:79], v[48:51]
	v_mfma_f32_16x16x32_bf16 v[48:51], v[220:223], v[72:75], v[52:55]
	v_mfma_f32_16x16x32_bf16 v[36:39], v[212:215], v[80:83], v[36:39]
	v_mfma_f32_16x16x32_bf16 v[32:35], v[220:223], v[80:83], v[32:35]
	v_mfma_f32_16x16x32_bf16 v[20:23], v[212:215], v[160:163], v[20:23]
	v_mfma_f32_16x16x32_bf16 v[16:19], v[220:223], v[160:163], v[16:19]
	v_mfma_f32_16x16x32_bf16 v[4:7], v[212:215], v[192:195], v[4:7]
	v_mfma_f32_16x16x32_bf16 v[0:3], v[220:223], v[192:195], v[0:3]
	v_mfma_f32_16x16x32_bf16 v[56:59], v[236:239], v[76:79], v[48:51]
	v_mfma_f32_16x16x32_bf16 v[36:39], v[216:219], v[84:87], v[36:39]
	v_mfma_f32_16x16x32_bf16 v[32:35], v[236:239], v[84:87], v[32:35]
	v_mfma_f32_16x16x32_bf16 v[20:23], v[216:219], v[164:167], v[20:23]
	v_mfma_f32_16x16x32_bf16 v[16:19], v[236:239], v[164:167], v[16:19]
	v_mfma_f32_16x16x32_bf16 v[4:7], v[216:219], v[196:199], v[4:7]
	v_mfma_f32_16x16x32_bf16 v[0:3], v[236:239], v[196:199], v[0:3]
	s_add_u32 s8, s8, 0x100
	s_addc_u32 s9, s9, 0
	s_add_u32 s56, s56, 0x100
	s_addc_u32 s57, s57, 0
	s_cmp_gt_u32 s58, 13
	s_barrier
.LBB0_678:
	s_add_u32 s2, s8, 0xfffc0080
	s_addc_u32 s3, s9, -1
	ds_read_b128 v[48:51], v206
	ds_read_b128 v[60:63], v206 offset:2048
	ds_read_b128 v[52:55], v206 offset:1024
	ds_read_b128 v[68:71], v206 offset:3072
	s_cmp_eq_u32 s58, 12
	s_cselect_b32 s29, s1, s3
	s_cselect_b32 s28, s7, s2
	s_cselect_b32 s3, s21, s57
	s_cselect_b32 s2, s23, s56
	s_add_i32 m0, s41, 0xc000
	ds_read_b128 v[72:75], v207
	ds_read_b128 v[80:83], v207 offset:2048
	ds_read_b128 v[160:163], v207 offset:4096
	ds_read_b128 v[192:195], v207 offset:6144
	ds_read_b128 v[76:79], v207 offset:1024
	ds_read_b128 v[84:87], v207 offset:3072
	ds_read_b128 v[164:167], v207 offset:5120
	global_load_lds_dwordx4 v188, s[8:9]
	s_add_i32 m0, s41, 0xe000
	ds_read_b128 v[196:199], v207 offset:7168
	global_load_lds_dwordx4 v190, s[8:9]
	s_waitcnt lgkmcnt(8)
	s_barrier
	s_waitcnt lgkmcnt(4)
	v_mfma_f32_16x16x32_bf16 v[156:159], v[48:51], v[72:75], v[156:159]
	v_mfma_f32_16x16x32_bf16 v[152:155], v[60:63], v[72:75], v[152:155]
	v_mfma_f32_16x16x32_bf16 v[140:143], v[48:51], v[80:83], v[140:143]
	v_mfma_f32_16x16x32_bf16 v[136:139], v[60:63], v[80:83], v[136:139]
	v_mfma_f32_16x16x32_bf16 v[124:127], v[48:51], v[160:163], v[124:127]
	v_mfma_f32_16x16x32_bf16 v[120:123], v[60:63], v[160:163], v[120:123]
	v_mfma_f32_16x16x32_bf16 v[108:111], v[48:51], v[192:195], v[108:111]
	v_mfma_f32_16x16x32_bf16 v[104:107], v[60:63], v[192:195], v[104:107]
	s_waitcnt lgkmcnt(0)
	v_mfma_f32_16x16x32_bf16 v[156:159], v[52:55], v[76:79], v[156:159]
	v_mfma_f32_16x16x32_bf16 v[152:155], v[68:71], v[76:79], v[152:155]
	v_mfma_f32_16x16x32_bf16 v[140:143], v[52:55], v[84:87], v[140:143]
	v_mfma_f32_16x16x32_bf16 v[136:139], v[68:71], v[84:87], v[136:139]
	v_mfma_f32_16x16x32_bf16 v[124:127], v[52:55], v[164:167], v[124:127]
	v_mfma_f32_16x16x32_bf16 v[120:123], v[68:71], v[164:167], v[120:123]
	v_mfma_f32_16x16x32_bf16 v[108:111], v[52:55], v[196:199], v[108:111]
	v_mfma_f32_16x16x32_bf16 v[104:107], v[68:71], v[196:199], v[104:107]
	s_barrier
	s_add_u32 s98, s2, 0x80
	s_addc_u32 s99, s3, 0
	s_add_i32 m0, s40, 0x10000
	ds_read_b128 v[200:203], v206 offset:16384
	ds_read_b128 v[212:215], v206 offset:18432
	ds_read_b128 v[208:211], v206 offset:17408
	global_load_lds_dwordx4 v182, s[2:3]
	s_add_i32 m0, s40, 0x12000
	ds_read_b128 v[216:219], v206 offset:19456
	global_load_lds_dwordx4 v186, s[2:3]
	s_barrier
	s_waitcnt lgkmcnt(2)
	v_mfma_f32_16x16x32_bf16 v[148:151], v[200:203], v[72:75], v[148:151]
	v_mfma_f32_16x16x32_bf16 v[72:75], v[212:215], v[72:75], v[144:147]
	s_waitcnt lgkmcnt(0)
	v_mfma_f32_16x16x32_bf16 v[148:151], v[208:211], v[76:79], v[148:151]
	v_mfma_f32_16x16x32_bf16 v[72:75], v[216:219], v[76:79], v[72:75]
	v_mfma_f32_16x16x32_bf16 v[76:79], v[200:203], v[80:83], v[132:135]
	v_mfma_f32_16x16x32_bf16 v[80:83], v[212:215], v[80:83], v[128:131]
	v_mfma_f32_16x16x32_bf16 v[112:115], v[212:215], v[160:163], v[112:115]
	v_mfma_f32_16x16x32_bf16 v[100:103], v[200:203], v[192:195], v[100:103]
	v_mfma_f32_16x16x32_bf16 v[96:99], v[212:215], v[192:195], v[96:99]
	v_mfma_f32_16x16x32_bf16 v[76:79], v[208:211], v[84:87], v[76:79]
	v_mfma_f32_16x16x32_bf16 v[80:83], v[216:219], v[84:87], v[80:83]
	v_mfma_f32_16x16x32_bf16 v[84:87], v[200:203], v[160:163], v[116:119]
	v_mfma_f32_16x16x32_bf16 v[112:115], v[216:219], v[164:167], v[112:115]
	v_mfma_f32_16x16x32_bf16 v[100:103], v[208:211], v[196:199], v[100:103]
	v_mfma_f32_16x16x32_bf16 v[96:99], v[216:219], v[196:199], v[96:99]
	v_mfma_f32_16x16x32_bf16 v[84:87], v[208:211], v[164:167], v[84:87]
	s_mov_b32 m0, s41
	s_add_u32 s100, s28, 0x80
	s_addc_u32 s101, s29, 0
	s_barrier
	ds_read_b128 v[116:119], v207 offset:16384
	ds_read_b128 v[132:135], v207 offset:18432
	ds_read_b128 v[160:163], v207 offset:20480
	ds_read_b128 v[192:195], v207 offset:22528
	ds_read_b128 v[128:131], v207 offset:17408
	ds_read_b128 v[144:147], v207 offset:19456
	ds_read_b128 v[164:167], v207 offset:21504
	global_load_lds_dwordx4 v180, s[28:29]
	s_mov_b32 m0, s42
	ds_read_b128 v[196:199], v207 offset:23552
	global_load_lds_dwordx4 v184, s[28:29]
	s_barrier
	s_waitcnt lgkmcnt(4)
	v_mfma_f32_16x16x32_bf16 v[92:95], v[48:51], v[116:119], v[92:95]
	v_mfma_f32_16x16x32_bf16 v[88:91], v[60:63], v[116:119], v[88:91]
	v_mfma_f32_16x16x32_bf16 v[44:47], v[48:51], v[132:135], v[44:47]
	v_mfma_f32_16x16x32_bf16 v[40:43], v[60:63], v[132:135], v[40:43]
	v_mfma_f32_16x16x32_bf16 v[28:31], v[48:51], v[160:163], v[28:31]
	v_mfma_f32_16x16x32_bf16 v[24:27], v[60:63], v[160:163], v[24:27]
	v_mfma_f32_16x16x32_bf16 v[12:15], v[48:51], v[192:195], v[12:15]
	v_mfma_f32_16x16x32_bf16 v[8:11], v[60:63], v[192:195], v[8:11]
	s_waitcnt lgkmcnt(0)
	v_mfma_f32_16x16x32_bf16 v[92:95], v[52:55], v[128:131], v[92:95]
	v_mfma_f32_16x16x32_bf16 v[88:91], v[68:71], v[128:131], v[88:91]
	v_mfma_f32_16x16x32_bf16 v[44:47], v[52:55], v[144:147], v[44:47]
	v_mfma_f32_16x16x32_bf16 v[40:43], v[68:71], v[144:147], v[40:43]
	v_mfma_f32_16x16x32_bf16 v[28:31], v[52:55], v[164:167], v[28:31]
	v_mfma_f32_16x16x32_bf16 v[24:27], v[68:71], v[164:167], v[24:27]
	v_mfma_f32_16x16x32_bf16 v[12:15], v[52:55], v[196:199], v[12:15]
	v_mfma_f32_16x16x32_bf16 v[8:11], v[68:71], v[196:199], v[8:11]
	s_barrier
	s_add_i32 m0, s40, 0x14000
	s_add_u32 s60, s2, 0x40000
	s_addc_u32 s61, s3, 0
	global_load_lds_dwordx4 v182, s[60:61]
	s_add_i32 m0, s40, 0x16000
	s_add_u32 s28, s28, 0x40000
	s_addc_u32 s29, s29, 0
	global_load_lds_dwordx4 v186, s[60:61]
	s_waitcnt vmcnt(6)
	s_barrier
	v_mfma_f32_16x16x32_bf16 v[36:39], v[200:203], v[132:135], v[36:39]
	v_mfma_f32_16x16x32_bf16 v[32:35], v[212:215], v[132:135], v[32:35]
	v_mfma_f32_16x16x32_bf16 v[20:23], v[200:203], v[160:163], v[20:23]
	v_mfma_f32_16x16x32_bf16 v[16:19], v[212:215], v[160:163], v[16:19]
	v_mfma_f32_16x16x32_bf16 v[4:7], v[200:203], v[192:195], v[4:7]
	v_mfma_f32_16x16x32_bf16 v[0:3], v[212:215], v[192:195], v[0:3]
	v_mfma_f32_16x16x32_bf16 v[48:51], v[200:203], v[116:119], v[64:67]
	v_mfma_f32_16x16x32_bf16 v[52:55], v[212:215], v[116:119], v[56:59]
	v_mfma_f32_16x16x32_bf16 v[36:39], v[208:211], v[144:147], v[36:39]
	v_mfma_f32_16x16x32_bf16 v[32:35], v[216:219], v[144:147], v[32:35]
	v_mfma_f32_16x16x32_bf16 v[20:23], v[208:211], v[164:167], v[20:23]
	v_mfma_f32_16x16x32_bf16 v[16:19], v[216:219], v[164:167], v[16:19]
	v_mfma_f32_16x16x32_bf16 v[4:7], v[208:211], v[196:199], v[4:7]
	v_mfma_f32_16x16x32_bf16 v[0:3], v[216:219], v[196:199], v[0:3]
	v_mfma_f32_16x16x32_bf16 v[48:51], v[208:211], v[128:131], v[48:51]
	v_mfma_f32_16x16x32_bf16 v[52:55], v[216:219], v[128:131], v[52:55]
	s_barrier
	ds_read_b128 v[56:59], v206 offset:32768
	ds_read_b128 v[60:63], v206 offset:33792
	ds_read_b128 v[64:67], v206 offset:34816
	ds_read_b128 v[68:71], v206 offset:35840
	s_mov_b32 m0, s43
	ds_read_b128 v[116:119], v207 offset:32768
	ds_read_b128 v[128:131], v207 offset:33792
	ds_read_b128 v[160:163], v207 offset:34816
	ds_read_b128 v[164:167], v207 offset:35840
	ds_read_b128 v[192:195], v207 offset:36864
	ds_read_b128 v[200:203], v207 offset:38912
	ds_read_b128 v[196:199], v207 offset:37888
	global_load_lds_dwordx4 v180, s[28:29]
	s_mov_b32 m0, s44
	ds_read_b128 v[208:211], v207 offset:39936
	global_load_lds_dwordx4 v184, s[28:29]
	s_waitcnt lgkmcnt(8)
	s_barrier
	s_waitcnt lgkmcnt(4)
	v_mfma_f32_16x16x32_bf16 v[132:135], v[56:59], v[116:119], v[156:159]
	v_mfma_f32_16x16x32_bf16 v[156:159], v[60:63], v[128:131], v[132:135]
	v_mfma_f32_16x16x32_bf16 v[132:135], v[64:67], v[116:119], v[152:155]
	v_mfma_f32_16x16x32_bf16 v[152:155], v[68:71], v[128:131], v[132:135]
	v_mfma_f32_16x16x32_bf16 v[132:135], v[56:59], v[160:163], v[140:143]
	v_mfma_f32_16x16x32_bf16 v[140:143], v[60:63], v[164:167], v[132:135]
	v_mfma_f32_16x16x32_bf16 v[132:135], v[64:67], v[160:163], v[136:139]
	s_waitcnt lgkmcnt(0)
	v_mfma_f32_16x16x32_bf16 v[124:127], v[56:59], v[192:195], v[124:127]
	v_mfma_f32_16x16x32_bf16 v[120:123], v[64:67], v[192:195], v[120:123]
	v_mfma_f32_16x16x32_bf16 v[108:111], v[56:59], v[200:203], v[108:111]
	v_mfma_f32_16x16x32_bf16 v[104:107], v[64:67], v[200:203], v[104:107]
	v_mfma_f32_16x16x32_bf16 v[136:139], v[68:71], v[164:167], v[132:135]
	v_mfma_f32_16x16x32_bf16 v[124:127], v[60:63], v[196:199], v[124:127]
	v_mfma_f32_16x16x32_bf16 v[120:123], v[68:71], v[196:199], v[120:123]
	v_mfma_f32_16x16x32_bf16 v[108:111], v[60:63], v[208:211], v[108:111]
	v_mfma_f32_16x16x32_bf16 v[104:107], v[68:71], v[208:211], v[104:107]
	s_barrier
	ds_read_b128 v[220:223], v206 offset:51200
	ds_read_b128 v[212:215], v206 offset:49152
	s_add_i32 m0, s40, 0x18000
	ds_read_b128 v[236:239], v206 offset:52224
	global_load_lds_dwordx4 v182, s[98:99]
	s_add_i32 m0, s40, 0x1a000
	ds_read_b128 v[216:219], v206 offset:50176
	global_load_lds_dwordx4 v186, s[98:99]
	s_barrier
	s_waitcnt lgkmcnt(2)
	v_mfma_f32_16x16x32_bf16 v[72:75], v[220:223], v[116:119], v[72:75]
	v_mfma_f32_16x16x32_bf16 v[132:135], v[212:215], v[116:119], v[148:151]
	s_waitcnt lgkmcnt(0)
	v_mfma_f32_16x16x32_bf16 v[144:147], v[236:239], v[128:131], v[72:75]
	v_mfma_f32_16x16x32_bf16 v[72:75], v[212:215], v[160:163], v[76:79]
	v_mfma_f32_16x16x32_bf16 v[148:151], v[216:219], v[128:131], v[132:135]
	v_mfma_f32_16x16x32_bf16 v[132:135], v[216:219], v[164:167], v[72:75]
	v_mfma_f32_16x16x32_bf16 v[72:75], v[220:223], v[160:163], v[80:83]
	v_mfma_f32_16x16x32_bf16 v[128:131], v[236:239], v[164:167], v[72:75]
	v_mfma_f32_16x16x32_bf16 v[72:75], v[212:215], v[192:195], v[84:87]
	v_mfma_f32_16x16x32_bf16 v[116:119], v[216:219], v[196:199], v[72:75]
	v_mfma_f32_16x16x32_bf16 v[72:75], v[220:223], v[192:195], v[112:115]
	v_mfma_f32_16x16x32_bf16 v[112:115], v[236:239], v[196:199], v[72:75]
	v_mfma_f32_16x16x32_bf16 v[72:75], v[212:215], v[200:203], v[100:103]
	v_mfma_f32_16x16x32_bf16 v[100:103], v[216:219], v[208:211], v[72:75]
	v_mfma_f32_16x16x32_bf16 v[72:75], v[220:223], v[200:203], v[96:99]
	v_mfma_f32_16x16x32_bf16 v[96:99], v[236:239], v[208:211], v[72:75]
	s_mov_b32 m0, s53
	s_barrier
	s_nop 2
	ds_read_b128 v[72:75], v207 offset:49152
	ds_read_b128 v[80:83], v207 offset:51200
	ds_read_b128 v[160:163], v207 offset:53248
	ds_read_b128 v[192:195], v207 offset:55296
	ds_read_b128 v[76:79], v207 offset:50176
	ds_read_b128 v[84:87], v207 offset:52224
	ds_read_b128 v[164:167], v207 offset:54272
	global_load_lds_dwordx4 v180, s[100:101]
	s_mov_b32 m0, s54
	ds_read_b128 v[196:199], v207 offset:56320
	global_load_lds_dwordx4 v184, s[100:101]
	s_barrier
	s_waitcnt lgkmcnt(4)
	v_mfma_f32_16x16x32_bf16 v[92:95], v[56:59], v[72:75], v[92:95]
	v_mfma_f32_16x16x32_bf16 v[88:91], v[64:67], v[72:75], v[88:91]
	v_mfma_f32_16x16x32_bf16 v[44:47], v[56:59], v[80:83], v[44:47]
	v_mfma_f32_16x16x32_bf16 v[40:43], v[64:67], v[80:83], v[40:43]
	v_mfma_f32_16x16x32_bf16 v[28:31], v[56:59], v[160:163], v[28:31]
	v_mfma_f32_16x16x32_bf16 v[24:27], v[64:67], v[160:163], v[24:27]
	v_mfma_f32_16x16x32_bf16 v[12:15], v[56:59], v[192:195], v[12:15]
	v_mfma_f32_16x16x32_bf16 v[8:11], v[64:67], v[192:195], v[8:11]
	s_waitcnt lgkmcnt(0)
	v_mfma_f32_16x16x32_bf16 v[92:95], v[60:63], v[76:79], v[92:95]
	v_mfma_f32_16x16x32_bf16 v[88:91], v[68:71], v[76:79], v[88:91]
	v_mfma_f32_16x16x32_bf16 v[44:47], v[60:63], v[84:87], v[44:47]
	v_mfma_f32_16x16x32_bf16 v[40:43], v[68:71], v[84:87], v[40:43]
	v_mfma_f32_16x16x32_bf16 v[28:31], v[60:63], v[164:167], v[28:31]
	v_mfma_f32_16x16x32_bf16 v[24:27], v[68:71], v[164:167], v[24:27]
	v_mfma_f32_16x16x32_bf16 v[12:15], v[60:63], v[196:199], v[12:15]
	v_mfma_f32_16x16x32_bf16 v[8:11], v[68:71], v[196:199], v[8:11]
	s_barrier
	s_add_i32 m0, s40, 0x1c000
	s_add_u32 s2, s2, 0x40080
	s_addc_u32 s3, s3, 0
	global_load_lds_dwordx4 v182, s[2:3]
	s_add_i32 m0, s40, 0x1e000
	s_add_i32 s58, s58, 2
	global_load_lds_dwordx4 v186, s[2:3]
	s_waitcnt vmcnt(6)
	s_barrier
	v_mfma_f32_16x16x32_bf16 v[48:51], v[212:215], v[72:75], v[48:51]
	v_mfma_f32_16x16x32_bf16 v[64:67], v[216:219], v[76:79], v[48:51]
	v_mfma_f32_16x16x32_bf16 v[48:51], v[220:223], v[72:75], v[52:55]
	v_mfma_f32_16x16x32_bf16 v[36:39], v[212:215], v[80:83], v[36:39]
	v_mfma_f32_16x16x32_bf16 v[32:35], v[220:223], v[80:83], v[32:35]
	v_mfma_f32_16x16x32_bf16 v[20:23], v[212:215], v[160:163], v[20:23]
	v_mfma_f32_16x16x32_bf16 v[16:19], v[220:223], v[160:163], v[16:19]
	v_mfma_f32_16x16x32_bf16 v[4:7], v[212:215], v[192:195], v[4:7]
	v_mfma_f32_16x16x32_bf16 v[0:3], v[220:223], v[192:195], v[0:3]
	v_mfma_f32_16x16x32_bf16 v[56:59], v[236:239], v[76:79], v[48:51]
	v_mfma_f32_16x16x32_bf16 v[36:39], v[216:219], v[84:87], v[36:39]
	v_mfma_f32_16x16x32_bf16 v[32:35], v[236:239], v[84:87], v[32:35]
	v_mfma_f32_16x16x32_bf16 v[20:23], v[216:219], v[164:167], v[20:23]
	v_mfma_f32_16x16x32_bf16 v[16:19], v[236:239], v[164:167], v[16:19]
	v_mfma_f32_16x16x32_bf16 v[4:7], v[216:219], v[196:199], v[4:7]
	v_mfma_f32_16x16x32_bf16 v[0:3], v[236:239], v[196:199], v[0:3]
	s_add_u32 s8, s8, 0x100
	s_addc_u32 s9, s9, 0
	s_add_u32 s56, s56, 0x100
	s_addc_u32 s57, s57, 0
	s_cmp_gt_u32 s58, 13
	s_barrier
	s_cbranch_scc0 .LBB0_678
	s_lshl_b32 s1, s0, 8
	s_add_i32 s2, s1, s51
	s_lshl_b32 s1, s6, 8
	v_mov_b32_e32 v160, v205
	v_mov_b32_e32 v208, v204
	s_or_b32 s1, s1, s52
	s_nop 0
	v_lshl_add_u32 v192, v208, 3, s1
	s_add_i32 s1, s0, -16
	s_lshr_b32 s1, s1, 3
	s_add_i32 s1, s1, 1
	s_cmp_gt_i32 s0, 15
	s_cselect_b32 s3, s1, 0
	s_mul_i32 s96, s3, 0x1800
	s_lshl_b64 s[0:1], s[96:97], 2
	s_add_u32 s0, s45, s0
	v_ashrrev_i32_e32 v193, 31, v192
	s_addc_u32 s1, s46, s1
	v_lshlrev_b64 v[196:197], 2, v[192:193]
	s_lshl_b32 s96, s3, 10
	v_lshl_add_u64 v[48:49], s[0:1], 0, v[196:197]
	s_lshl_b64 s[0:1], s[96:97], 2
	s_add_u32 s0, s49, s0
	s_addc_u32 s1, s50, s1
	v_lshl_add_u64 v[52:53], s[0:1], 0, v[196:197]
	global_load_dwordx4 v[80:83], v[48:49], off offset:16
	global_load_dwordx4 v[84:87], v[48:49], off
	global_load_dwordx4 v[72:75], v[52:53], off offset:16
	global_load_dwordx4 v[76:79], v[52:53], off
	global_load_dwordx4 v[60:63], v[48:49], off offset:528
	global_load_dwordx4 v[68:71], v[48:49], off offset:512
	s_nop 0
	global_load_dwordx4 v[48:51], v[52:53], off offset:528
	s_nop 0
	global_load_dwordx4 v[52:55], v[52:53], off offset:512
	v_add_u32_e32 v194, s2, v160
	v_ashrrev_i32_e32 v195, 31, v194
	v_lshlrev_b64 v[160:161], 10, v[194:195]
	v_lshl_add_u64 v[198:199], v[160:161], 0, v[192:193]
	v_cndmask_b32_e64 v160, 0, 1, s[74:75]
	v_cmp_gt_i32_e64 s[0:1], s71, v194
	v_cmp_ne_u32_e64 s[6:7], 1, v160
	s_andn2_b64 vcc, exec, s[74:75]
	s_mov_b64 s[2:3], -1
	s_cbranch_vccnz .LBB0_681
	v_lshl_add_u64 v[160:161], v[198:199], 1, s[14:15]
	v_mov_b32_e32 v222, v160
	v_mov_b32_e32 v223, v161
	global_load_dwordx4 v[210:213], v[222:223], off
	global_load_dwordx4 v[214:217], v[222:223], off offset:256
	s_mov_b64 s[80:81], 0x8000
	v_lshl_add_u64 v[222:223], v[222:223], 0, s[80:81]
	global_load_dwordx4 v[218:221], v[222:223], off
	global_load_dwordx4 v[236:239], v[222:223], off offset:256
	s_mov_b64 s[2:3], 0
	s_waitcnt vmcnt(3)
	v_lshlrev_b32_e32 v164, 16, v210
	v_and_b32_e32 v165, 0xffff0000, v210
	v_lshlrev_b32_e32 v166, 16, v211
	v_and_b32_e32 v167, 0xffff0000, v211
	v_lshlrev_b32_e32 v160, 16, v212
	v_and_b32_e32 v161, 0xffff0000, v212
	v_lshlrev_b32_e32 v162, 16, v213
	v_and_b32_e32 v163, 0xffff0000, v213
	s_mov_b64 s[80:81], 0x8000
	v_lshl_add_u64 v[222:223], v[222:223], 0, s[80:81]
	global_load_dwordx4 v[210:213], v[222:223], off

.LBB0_879:
	s_ashr_i32 s39, s38, 31
	v_cmp_lt_i64_e32 vcc, s[12:13], v[178:179]
	s_lshl_b64 s[12:13], s[38:39], 19
	s_add_u32 s40, s49, s12
	s_addc_u32 s41, s50, s13
	s_lshl_b32 s84, s82, 18
	s_add_u32 s40, s40, s84
	s_addc_u32 s41, s41, 0
	s_and_b64 s[12:13], vcc, exec
	s_cselect_b32 s1, s41, s11
	s_cselect_b32 s9, s40, s10
	s_ashr_i32 s37, s36, 31
	s_lshl_b64 s[12:13], s[36:37], 19
	s_add_u32 s42, s51, s12
	s_addc_u32 s43, s52, s13
	s_and_b64 s[12:13], vcc, exec
	s_cselect_b32 s14, s43, s3
	s_cselect_b32 s15, s42, s2
	s_add_u32 s10, s10, 0x40080
	s_addc_u32 s11, s11, 0
	s_add_u32 s37, s2, 0x100
	s_addc_u32 s39, s3, 0
	s_mov_b32 s67, -2
	s_cmp_lg_u32 s83, 0
	s_cbranch_scc1 .Lup_half_peel
	s_add_u32 s2, s10, 0xfffc0080
	s_addc_u32 s3, s11, -1
	ds_read_b128 v[48:51], v237
	ds_read_b128 v[104:107], v237 offset:2048
	ds_read_b128 v[52:55], v237 offset:1024
	ds_read_b128 v[108:111], v237 offset:3072
	s_cmp_eq_u32 s67, 12
	s_cselect_b32 s13, s1, s3
	s_cselect_b32 s12, s9, s2
	s_cselect_b32 s3, s14, s39
	s_cselect_b32 s2, s15, s37
	s_add_i32 m0, s54, 0xc000
	ds_read_b128 v[112:115], v238
	ds_read_b128 v[120:123], v238 offset:2048
	ds_read_b128 v[160:163], v238 offset:4096
	ds_read_b128 v[190:193], v238 offset:6144
	ds_read_b128 v[116:119], v238 offset:1024
	ds_read_b128 v[156:159], v238 offset:3072
	ds_read_b128 v[164:167], v238 offset:5120
	global_load_lds_dwordx4 v186, s[10:11]
	s_add_i32 m0, s54, 0xe000
	ds_read_b128 v[194:197], v238 offset:7168
	global_load_lds_dwordx4 v188, s[10:11]
	s_waitcnt lgkmcnt(8)
	s_barrier
	s_waitcnt lgkmcnt(4)
	v_mfma_f32_16x16x32_bf16 v[152:155], v[48:51], v[112:115], 0
	v_mfma_f32_16x16x32_bf16 v[68:71], v[104:107], v[112:115], 0
	v_mfma_f32_16x16x32_bf16 v[148:151], v[48:51], v[120:123], 0
	v_mfma_f32_16x16x32_bf16 v[64:67], v[104:107], v[120:123], 0
	v_mfma_f32_16x16x32_bf16 v[136:139], v[48:51], v[160:163], 0
	v_mfma_f32_16x16x32_bf16 v[44:47], v[104:107], v[160:163], 0
	v_mfma_f32_16x16x32_bf16 v[128:131], v[48:51], v[190:193], 0
	v_mfma_f32_16x16x32_bf16 v[40:43], v[104:107], v[190:193], 0
	s_waitcnt lgkmcnt(0)
	v_mfma_f32_16x16x32_bf16 v[152:155], v[52:55], v[116:119], v[152:155]
	v_mfma_f32_16x16x32_bf16 v[68:71], v[108:111], v[116:119], v[68:71]
	v_mfma_f32_16x16x32_bf16 v[148:151], v[52:55], v[156:159], v[148:151]
	v_mfma_f32_16x16x32_bf16 v[64:67], v[108:111], v[156:159], v[64:67]
	v_mfma_f32_16x16x32_bf16 v[136:139], v[52:55], v[164:167], v[136:139]
	v_mfma_f32_16x16x32_bf16 v[44:47], v[108:111], v[164:167], v[44:47]
	v_mfma_f32_16x16x32_bf16 v[128:131], v[52:55], v[194:197], v[128:131]
	v_mfma_f32_16x16x32_bf16 v[40:43], v[108:111], v[194:197], v[40:43]
	s_barrier
	s_add_u32 s98, s2, 0x80
	s_addc_u32 s99, s3, 0
	s_add_i32 m0, s53, 0x10000
	ds_read_b128 v[198:201], v237 offset:16384
	ds_read_b128 v[206:209], v237 offset:18432
	ds_read_b128 v[202:205], v237 offset:17408
	global_load_lds_dwordx4 v168, s[2:3]
	s_add_i32 m0, s53, 0x12000
	ds_read_b128 v[210:213], v237 offset:19456
	global_load_lds_dwordx4 v184, s[2:3]
	s_barrier
	s_waitcnt lgkmcnt(2)
	v_mfma_f32_16x16x32_bf16 v[144:147], v[198:201], v[112:115], 0
	v_mfma_f32_16x16x32_bf16 v[60:63], v[206:209], v[112:115], 0
	v_mfma_f32_16x16x32_bf16 v[56:59], v[206:209], v[120:123], 0
	v_mfma_f32_16x16x32_bf16 v[36:39], v[206:209], v[160:163], 0
	v_mfma_f32_16x16x32_bf16 v[32:35], v[206:209], v[190:193], 0
	s_waitcnt lgkmcnt(0)
	v_mfma_f32_16x16x32_bf16 v[144:147], v[202:205], v[116:119], v[144:147]
	v_mfma_f32_16x16x32_bf16 v[60:63], v[210:213], v[116:119], v[60:63]
	v_mfma_f32_16x16x32_bf16 v[112:115], v[198:201], v[120:123], 0
	v_mfma_f32_16x16x32_bf16 v[56:59], v[210:213], v[156:159], v[56:59]
	v_mfma_f32_16x16x32_bf16 v[116:119], v[198:201], v[160:163], 0
	v_mfma_f32_16x16x32_bf16 v[36:39], v[210:213], v[164:167], v[36:39]
	v_mfma_f32_16x16x32_bf16 v[120:123], v[198:201], v[190:193], 0
	v_mfma_f32_16x16x32_bf16 v[32:35], v[210:213], v[194:197], v[32:35]
	v_mfma_f32_16x16x32_bf16 v[112:115], v[202:205], v[156:159], v[112:115]
	v_mfma_f32_16x16x32_bf16 v[116:119], v[202:205], v[164:167], v[116:119]
	v_mfma_f32_16x16x32_bf16 v[120:123], v[202:205], v[194:197], v[120:123]
	s_mov_b32 m0, s54
	s_add_u32 s100, s12, 0x80
	s_addc_u32 s101, s13, 0
	s_barrier
	ds_read_b128 v[124:127], v238 offset:16384
	ds_read_b128 v[140:143], v238 offset:18432
	ds_read_b128 v[160:163], v238 offset:20480
	ds_read_b128 v[190:193], v238 offset:22528
	ds_read_b128 v[132:135], v238 offset:17408
	ds_read_b128 v[156:159], v238 offset:19456
	ds_read_b128 v[164:167], v238 offset:21504
	global_load_lds_dwordx4 v180, s[12:13]
	s_mov_b32 m0, s55
	ds_read_b128 v[194:197], v238 offset:23552
	global_load_lds_dwordx4 v182, s[12:13]
	s_barrier
	s_waitcnt lgkmcnt(4)
	v_mfma_f32_16x16x32_bf16 v[100:103], v[48:51], v[124:127], 0
	v_mfma_f32_16x16x32_bf16 v[28:31], v[104:107], v[124:127], 0
	v_mfma_f32_16x16x32_bf16 v[96:99], v[48:51], v[140:143], 0
	v_mfma_f32_16x16x32_bf16 v[24:27], v[104:107], v[140:143], 0
	v_mfma_f32_16x16x32_bf16 v[84:87], v[48:51], v[160:163], 0
	v_mfma_f32_16x16x32_bf16 v[12:15], v[104:107], v[160:163], 0
	v_mfma_f32_16x16x32_bf16 v[8:11], v[104:107], v[190:193], 0
	s_waitcnt lgkmcnt(0)
	v_mfma_f32_16x16x32_bf16 v[100:103], v[52:55], v[132:135], v[100:103]
	v_mfma_f32_16x16x32_bf16 v[28:31], v[108:111], v[132:135], v[28:31]
	v_mfma_f32_16x16x32_bf16 v[96:99], v[52:55], v[156:159], v[96:99]
	v_mfma_f32_16x16x32_bf16 v[24:27], v[108:111], v[156:159], v[24:27]
	v_mfma_f32_16x16x32_bf16 v[84:87], v[52:55], v[164:167], v[84:87]
	v_mfma_f32_16x16x32_bf16 v[12:15], v[108:111], v[164:167], v[12:15]
	v_mfma_f32_16x16x32_bf16 v[48:51], v[48:51], v[190:193], 0
	v_mfma_f32_16x16x32_bf16 v[8:11], v[108:111], v[194:197], v[8:11]
	v_mfma_f32_16x16x32_bf16 v[48:51], v[52:55], v[194:197], v[48:51]
	s_barrier
	s_add_i32 m0, s53, 0x14000
	s_add_u32 s68, s2, 0x40000
	s_addc_u32 s69, s3, 0
	global_load_lds_dwordx4 v168, s[68:69]
	s_add_i32 m0, s53, 0x16000
	s_add_u32 s12, s12, 0x40000
	s_addc_u32 s13, s13, 0
	global_load_lds_dwordx4 v184, s[68:69]
	s_waitcnt vmcnt(6)
	s_barrier
	v_mfma_f32_16x16x32_bf16 v[76:79], v[198:201], v[140:143], 0
	v_mfma_f32_16x16x32_bf16 v[20:23], v[206:209], v[124:127], 0
	v_mfma_f32_16x16x32_bf16 v[88:91], v[202:205], v[156:159], v[76:79]
	v_mfma_f32_16x16x32_bf16 v[16:19], v[206:209], v[140:143], 0
	v_mfma_f32_16x16x32_bf16 v[76:79], v[198:201], v[160:163], 0
	v_mfma_f32_16x16x32_bf16 v[4:7], v[206:209], v[160:163], 0
	v_mfma_f32_16x16x32_bf16 v[72:75], v[198:201], v[190:193], 0
	v_mfma_f32_16x16x32_bf16 v[0:3], v[206:209], v[190:193], 0
	v_mfma_f32_16x16x32_bf16 v[52:55], v[198:201], v[124:127], 0
	v_mfma_f32_16x16x32_bf16 v[20:23], v[210:213], v[132:135], v[20:23]
	v_mfma_f32_16x16x32_bf16 v[16:19], v[210:213], v[156:159], v[16:19]
	v_mfma_f32_16x16x32_bf16 v[80:83], v[202:205], v[164:167], v[76:79]
	v_mfma_f32_16x16x32_bf16 v[4:7], v[210:213], v[164:167], v[4:7]
	v_mfma_f32_16x16x32_bf16 v[72:75], v[202:205], v[194:197], v[72:75]
	v_mfma_f32_16x16x32_bf16 v[0:3], v[210:213], v[194:197], v[0:3]
	v_mfma_f32_16x16x32_bf16 v[52:55], v[202:205], v[132:135], v[52:55]
	s_barrier
	ds_read_b128 v[76:79], v237 offset:32768
	ds_read_b128 v[92:95], v237 offset:33792
	ds_read_b128 v[104:107], v237 offset:34816
	ds_read_b128 v[108:111], v237 offset:35840
	s_mov_b32 m0, s56
	ds_read_b128 v[124:127], v238 offset:32768
	ds_read_b128 v[132:135], v238 offset:33792
	ds_read_b128 v[156:159], v238 offset:34816
	ds_read_b128 v[164:167], v238 offset:36864
	ds_read_b128 v[194:197], v238 offset:38912
	ds_read_b128 v[160:163], v238 offset:35840
	ds_read_b128 v[190:193], v238 offset:37888
	global_load_lds_dwordx4 v180, s[12:13]
	s_mov_b32 m0, s57
	ds_read_b128 v[198:201], v238 offset:39936
	global_load_lds_dwordx4 v182, s[12:13]
	s_waitcnt lgkmcnt(8)
	s_barrier
	s_waitcnt lgkmcnt(4)
	v_mfma_f32_16x16x32_bf16 v[140:143], v[76:79], v[124:127], v[152:155]
	v_mfma_f32_16x16x32_bf16 v[152:155], v[92:95], v[132:135], v[140:143]
	v_mfma_f32_16x16x32_bf16 v[68:71], v[104:107], v[124:127], v[68:71]
	v_mfma_f32_16x16x32_bf16 v[140:143], v[76:79], v[156:159], v[148:151]
	v_mfma_f32_16x16x32_bf16 v[64:67], v[104:107], v[156:159], v[64:67]
	v_mfma_f32_16x16x32_bf16 v[136:139], v[76:79], v[164:167], v[136:139]
	v_mfma_f32_16x16x32_bf16 v[44:47], v[104:107], v[164:167], v[44:47]
	s_waitcnt lgkmcnt(0)
	v_mfma_f32_16x16x32_bf16 v[128:131], v[76:79], v[194:197], v[128:131]
	v_mfma_f32_16x16x32_bf16 v[40:43], v[104:107], v[194:197], v[40:43]
	v_mfma_f32_16x16x32_bf16 v[68:71], v[108:111], v[132:135], v[68:71]
	v_mfma_f32_16x16x32_bf16 v[148:151], v[92:95], v[160:163], v[140:143]
	v_mfma_f32_16x16x32_bf16 v[64:67], v[108:111], v[160:163], v[64:67]
	v_mfma_f32_16x16x32_bf16 v[136:139], v[92:95], v[190:193], v[136:139]
	v_mfma_f32_16x16x32_bf16 v[44:47], v[108:111], v[190:193], v[44:47]
	v_mfma_f32_16x16x32_bf16 v[128:131], v[92:95], v[198:201], v[128:131]
	v_mfma_f32_16x16x32_bf16 v[40:43], v[108:111], v[198:201], v[40:43]
	s_barrier
	ds_read_b128 v[202:205], v237 offset:49152
	ds_read_b128 v[206:209], v237 offset:50176
	s_add_i32 m0, s53, 0x18000
	ds_read_b128 v[210:213], v237 offset:51200
	global_load_lds_dwordx4 v168, s[98:99]
	s_add_i32 m0, s53, 0x1a000
	ds_read_b128 v[214:217], v237 offset:52224
	global_load_lds_dwordx4 v184, s[98:99]
	s_barrier
	s_waitcnt lgkmcnt(2)
	v_mfma_f32_16x16x32_bf16 v[140:143], v[202:205], v[124:127], v[144:147]
	v_mfma_f32_16x16x32_bf16 v[112:115], v[202:205], v[156:159], v[112:115]
	v_mfma_f32_16x16x32_bf16 v[144:147], v[206:209], v[132:135], v[140:143]
	s_waitcnt lgkmcnt(0)
	v_mfma_f32_16x16x32_bf16 v[60:63], v[210:213], v[124:127], v[60:63]
	v_mfma_f32_16x16x32_bf16 v[140:143], v[206:209], v[160:163], v[112:115]
	v_mfma_f32_16x16x32_bf16 v[112:115], v[202:205], v[164:167], v[116:119]
	v_mfma_f32_16x16x32_bf16 v[60:63], v[214:217], v[132:135], v[60:63]
	v_mfma_f32_16x16x32_bf16 v[56:59], v[210:213], v[156:159], v[56:59]
	v_mfma_f32_16x16x32_bf16 v[132:135], v[206:209], v[190:193], v[112:115]
	v_mfma_f32_16x16x32_bf16 v[36:39], v[210:213], v[164:167], v[36:39]
	v_mfma_f32_16x16x32_bf16 v[112:115], v[202:205], v[194:197], v[120:123]
	v_mfma_f32_16x16x32_bf16 v[32:35], v[210:213], v[194:197], v[32:35]
	v_mfma_f32_16x16x32_bf16 v[56:59], v[214:217], v[160:163], v[56:59]
	v_mfma_f32_16x16x32_bf16 v[36:39], v[214:217], v[190:193], v[36:39]
	v_mfma_f32_16x16x32_bf16 v[124:127], v[206:209], v[198:201], v[112:115]
	v_mfma_f32_16x16x32_bf16 v[32:35], v[214:217], v[198:201], v[32:35]
	s_mov_b32 m0, s62
	s_barrier
	ds_read_b128 v[112:115], v238 offset:49152
	ds_read_b128 v[120:123], v238 offset:51200
	ds_read_b128 v[160:163], v238 offset:53248
	ds_read_b128 v[190:193], v238 offset:55296
	ds_read_b128 v[116:119], v238 offset:50176
	ds_read_b128 v[156:159], v238 offset:52224
	ds_read_b128 v[164:167], v238 offset:54272
	global_load_lds_dwordx4 v180, s[100:101]
	s_mov_b32 m0, s63
	ds_read_b128 v[194:197], v238 offset:56320
	global_load_lds_dwordx4 v182, s[100:101]
	s_barrier
	s_waitcnt lgkmcnt(4)
	v_mfma_f32_16x16x32_bf16 v[100:103], v[76:79], v[112:115], v[100:103]
	v_mfma_f32_16x16x32_bf16 v[28:31], v[104:107], v[112:115], v[28:31]
	v_mfma_f32_16x16x32_bf16 v[96:99], v[76:79], v[120:123], v[96:99]
	v_mfma_f32_16x16x32_bf16 v[24:27], v[104:107], v[120:123], v[24:27]
	v_mfma_f32_16x16x32_bf16 v[84:87], v[76:79], v[160:163], v[84:87]
	v_mfma_f32_16x16x32_bf16 v[12:15], v[104:107], v[160:163], v[12:15]
	v_mfma_f32_16x16x32_bf16 v[48:51], v[76:79], v[190:193], v[48:51]
	v_mfma_f32_16x16x32_bf16 v[8:11], v[104:107], v[190:193], v[8:11]
	s_waitcnt lgkmcnt(0)
	v_mfma_f32_16x16x32_bf16 v[100:103], v[92:95], v[116:119], v[100:103]
	v_mfma_f32_16x16x32_bf16 v[28:31], v[108:111], v[116:119], v[28:31]
	v_mfma_f32_16x16x32_bf16 v[96:99], v[92:95], v[156:159], v[96:99]
	v_mfma_f32_16x16x32_bf16 v[24:27], v[108:111], v[156:159], v[24:27]
	v_mfma_f32_16x16x32_bf16 v[84:87], v[92:95], v[164:167], v[84:87]
	v_mfma_f32_16x16x32_bf16 v[12:15], v[108:111], v[164:167], v[12:15]
	v_mfma_f32_16x16x32_bf16 v[76:79], v[92:95], v[194:197], v[48:51]
	v_mfma_f32_16x16x32_bf16 v[8:11], v[108:111], v[194:197], v[8:11]
	s_barrier
	s_add_i32 m0, s53, 0x1c000
	s_add_u32 s2, s2, 0x40080
	s_addc_u32 s3, s3, 0
	global_load_lds_dwordx4 v168, s[2:3]
	s_add_i32 m0, s53, 0x1e000
	s_add_i32 s67, s67, 2
	global_load_lds_dwordx4 v184, s[2:3]
	s_waitcnt vmcnt(6)
	s_barrier
	v_mfma_f32_16x16x32_bf16 v[48:51], v[202:205], v[112:115], v[52:55]
	v_mfma_f32_16x16x32_bf16 v[92:95], v[206:209], v[116:119], v[48:51]
	v_mfma_f32_16x16x32_bf16 v[48:51], v[202:205], v[120:123], v[88:91]
	v_mfma_f32_16x16x32_bf16 v[88:91], v[206:209], v[156:159], v[48:51]
	v_mfma_f32_16x16x32_bf16 v[48:51], v[202:205], v[160:163], v[80:83]
	v_mfma_f32_16x16x32_bf16 v[20:23], v[210:213], v[112:115], v[20:23]
	v_mfma_f32_16x16x32_bf16 v[16:19], v[210:213], v[120:123], v[16:19]
	v_mfma_f32_16x16x32_bf16 v[80:83], v[206:209], v[164:167], v[48:51]
	v_mfma_f32_16x16x32_bf16 v[4:7], v[210:213], v[160:163], v[4:7]
	v_mfma_f32_16x16x32_bf16 v[48:51], v[202:205], v[190:193], v[72:75]
	v_mfma_f32_16x16x32_bf16 v[0:3], v[210:213], v[190:193], v[0:3]
	v_mfma_f32_16x16x32_bf16 v[20:23], v[214:217], v[116:119], v[20:23]
	v_mfma_f32_16x16x32_bf16 v[16:19], v[214:217], v[156:159], v[16:19]
	v_mfma_f32_16x16x32_bf16 v[4:7], v[214:217], v[164:167], v[4:7]
	v_mfma_f32_16x16x32_bf16 v[72:75], v[206:209], v[194:197], v[48:51]
	v_mfma_f32_16x16x32_bf16 v[0:3], v[214:217], v[194:197], v[0:3]
	s_add_u32 s10, s10, 0x100
	s_addc_u32 s11, s11, 0
	s_add_u32 s37, s37, 0x100
	s_addc_u32 s39, s39, 0
	s_cmp_gt_u32 s67, 13
	s_barrier
.LBB0_880:
	s_add_u32 s2, s10, 0xfffc0080
	s_addc_u32 s3, s11, -1
	ds_read_b128 v[48:51], v237
	ds_read_b128 v[104:107], v237 offset:2048
	ds_read_b128 v[52:55], v237 offset:1024
	ds_read_b128 v[108:111], v237 offset:3072
	s_cmp_eq_u32 s67, 12
	s_cselect_b32 s13, s1, s3
	s_cselect_b32 s12, s9, s2
	s_cselect_b32 s3, s14, s39
	s_cselect_b32 s2, s15, s37
	s_add_i32 m0, s54, 0xc000
	ds_read_b128 v[112:115], v238
	ds_read_b128 v[120:123], v238 offset:2048
	ds_read_b128 v[160:163], v238 offset:4096
	ds_read_b128 v[190:193], v238 offset:6144
	ds_read_b128 v[116:119], v238 offset:1024
	ds_read_b128 v[156:159], v238 offset:3072
	ds_read_b128 v[164:167], v238 offset:5120
	global_load_lds_dwordx4 v186, s[10:11]
	s_add_i32 m0, s54, 0xe000
	ds_read_b128 v[194:197], v238 offset:7168
	global_load_lds_dwordx4 v188, s[10:11]
	s_waitcnt lgkmcnt(8)
	s_barrier
	s_waitcnt lgkmcnt(4)
	v_mfma_f32_16x16x32_bf16 v[152:155], v[48:51], v[112:115], v[152:155]
	v_mfma_f32_16x16x32_bf16 v[68:71], v[104:107], v[112:115], v[68:71]
	v_mfma_f32_16x16x32_bf16 v[148:151], v[48:51], v[120:123], v[148:151]
	v_mfma_f32_16x16x32_bf16 v[64:67], v[104:107], v[120:123], v[64:67]
	v_mfma_f32_16x16x32_bf16 v[136:139], v[48:51], v[160:163], v[136:139]
	v_mfma_f32_16x16x32_bf16 v[44:47], v[104:107], v[160:163], v[44:47]
	v_mfma_f32_16x16x32_bf16 v[128:131], v[48:51], v[190:193], v[128:131]
	v_mfma_f32_16x16x32_bf16 v[40:43], v[104:107], v[190:193], v[40:43]
	s_waitcnt lgkmcnt(0)
	v_mfma_f32_16x16x32_bf16 v[152:155], v[52:55], v[116:119], v[152:155]
	v_mfma_f32_16x16x32_bf16 v[68:71], v[108:111], v[116:119], v[68:71]
	v_mfma_f32_16x16x32_bf16 v[148:151], v[52:55], v[156:159], v[148:151]
	v_mfma_f32_16x16x32_bf16 v[64:67], v[108:111], v[156:159], v[64:67]
	v_mfma_f32_16x16x32_bf16 v[136:139], v[52:55], v[164:167], v[136:139]
	v_mfma_f32_16x16x32_bf16 v[44:47], v[108:111], v[164:167], v[44:47]
	v_mfma_f32_16x16x32_bf16 v[128:131], v[52:55], v[194:197], v[128:131]
	v_mfma_f32_16x16x32_bf16 v[40:43], v[108:111], v[194:197], v[40:43]
	s_barrier
	s_add_u32 s98, s2, 0x80
	s_addc_u32 s99, s3, 0
	s_add_i32 m0, s53, 0x10000
	ds_read_b128 v[198:201], v237 offset:16384
	ds_read_b128 v[206:209], v237 offset:18432
	ds_read_b128 v[202:205], v237 offset:17408
	global_load_lds_dwordx4 v168, s[2:3]
	s_add_i32 m0, s53, 0x12000
	ds_read_b128 v[210:213], v237 offset:19456
	global_load_lds_dwordx4 v184, s[2:3]
	s_barrier
	s_waitcnt lgkmcnt(2)
	v_mfma_f32_16x16x32_bf16 v[144:147], v[198:201], v[112:115], v[144:147]
	v_mfma_f32_16x16x32_bf16 v[60:63], v[206:209], v[112:115], v[60:63]
	v_mfma_f32_16x16x32_bf16 v[56:59], v[206:209], v[120:123], v[56:59]
	v_mfma_f32_16x16x32_bf16 v[36:39], v[206:209], v[160:163], v[36:39]
	v_mfma_f32_16x16x32_bf16 v[32:35], v[206:209], v[190:193], v[32:35]
	s_waitcnt lgkmcnt(0)
	v_mfma_f32_16x16x32_bf16 v[144:147], v[202:205], v[116:119], v[144:147]
	v_mfma_f32_16x16x32_bf16 v[60:63], v[210:213], v[116:119], v[60:63]
	v_mfma_f32_16x16x32_bf16 v[112:115], v[198:201], v[120:123], v[140:143]
	v_mfma_f32_16x16x32_bf16 v[56:59], v[210:213], v[156:159], v[56:59]
	v_mfma_f32_16x16x32_bf16 v[116:119], v[198:201], v[160:163], v[132:135]
	v_mfma_f32_16x16x32_bf16 v[36:39], v[210:213], v[164:167], v[36:39]
	v_mfma_f32_16x16x32_bf16 v[120:123], v[198:201], v[190:193], v[124:127]
	v_mfma_f32_16x16x32_bf16 v[32:35], v[210:213], v[194:197], v[32:35]
	v_mfma_f32_16x16x32_bf16 v[112:115], v[202:205], v[156:159], v[112:115]
	v_mfma_f32_16x16x32_bf16 v[116:119], v[202:205], v[164:167], v[116:119]
	v_mfma_f32_16x16x32_bf16 v[120:123], v[202:205], v[194:197], v[120:123]
	s_mov_b32 m0, s54
	s_add_u32 s100, s12, 0x80
	s_addc_u32 s101, s13, 0
	s_barrier
	ds_read_b128 v[124:127], v238 offset:16384
	ds_read_b128 v[140:143], v238 offset:18432
	ds_read_b128 v[160:163], v238 offset:20480
	ds_read_b128 v[190:193], v238 offset:22528
	ds_read_b128 v[132:135], v238 offset:17408
	ds_read_b128 v[156:159], v238 offset:19456
	ds_read_b128 v[164:167], v238 offset:21504
	global_load_lds_dwordx4 v180, s[12:13]
	s_mov_b32 m0, s55
	ds_read_b128 v[194:197], v238 offset:23552
	global_load_lds_dwordx4 v182, s[12:13]
	s_barrier
	s_waitcnt lgkmcnt(4)
	v_mfma_f32_16x16x32_bf16 v[100:103], v[48:51], v[124:127], v[100:103]
	v_mfma_f32_16x16x32_bf16 v[28:31], v[104:107], v[124:127], v[28:31]
	v_mfma_f32_16x16x32_bf16 v[96:99], v[48:51], v[140:143], v[96:99]
	v_mfma_f32_16x16x32_bf16 v[24:27], v[104:107], v[140:143], v[24:27]
	v_mfma_f32_16x16x32_bf16 v[84:87], v[48:51], v[160:163], v[84:87]
	v_mfma_f32_16x16x32_bf16 v[12:15], v[104:107], v[160:163], v[12:15]
	v_mfma_f32_16x16x32_bf16 v[8:11], v[104:107], v[190:193], v[8:11]
	s_waitcnt lgkmcnt(0)
	v_mfma_f32_16x16x32_bf16 v[100:103], v[52:55], v[132:135], v[100:103]
	v_mfma_f32_16x16x32_bf16 v[28:31], v[108:111], v[132:135], v[28:31]
	v_mfma_f32_16x16x32_bf16 v[96:99], v[52:55], v[156:159], v[96:99]
	v_mfma_f32_16x16x32_bf16 v[24:27], v[108:111], v[156:159], v[24:27]
	v_mfma_f32_16x16x32_bf16 v[84:87], v[52:55], v[164:167], v[84:87]
	v_mfma_f32_16x16x32_bf16 v[12:15], v[108:111], v[164:167], v[12:15]
	v_mfma_f32_16x16x32_bf16 v[48:51], v[48:51], v[190:193], v[76:79]
	v_mfma_f32_16x16x32_bf16 v[8:11], v[108:111], v[194:197], v[8:11]
	v_mfma_f32_16x16x32_bf16 v[48:51], v[52:55], v[194:197], v[48:51]
	s_barrier
	s_add_i32 m0, s53, 0x14000
	s_add_u32 s68, s2, 0x40000
	s_addc_u32 s69, s3, 0
	global_load_lds_dwordx4 v168, s[68:69]
	s_add_i32 m0, s53, 0x16000
	s_add_u32 s12, s12, 0x40000
	s_addc_u32 s13, s13, 0
	global_load_lds_dwordx4 v184, s[68:69]
	s_waitcnt vmcnt(6)
	s_barrier
	v_mfma_f32_16x16x32_bf16 v[76:79], v[198:201], v[140:143], v[88:91]
	v_mfma_f32_16x16x32_bf16 v[20:23], v[206:209], v[124:127], v[20:23]
	v_mfma_f32_16x16x32_bf16 v[88:91], v[202:205], v[156:159], v[76:79]
	v_mfma_f32_16x16x32_bf16 v[16:19], v[206:209], v[140:143], v[16:19]
	v_mfma_f32_16x16x32_bf16 v[76:79], v[198:201], v[160:163], v[80:83]
	v_mfma_f32_16x16x32_bf16 v[4:7], v[206:209], v[160:163], v[4:7]
	v_mfma_f32_16x16x32_bf16 v[72:75], v[198:201], v[190:193], v[72:75]
	v_mfma_f32_16x16x32_bf16 v[0:3], v[206:209], v[190:193], v[0:3]
	v_mfma_f32_16x16x32_bf16 v[52:55], v[198:201], v[124:127], v[92:95]
	v_mfma_f32_16x16x32_bf16 v[20:23], v[210:213], v[132:135], v[20:23]
	v_mfma_f32_16x16x32_bf16 v[16:19], v[210:213], v[156:159], v[16:19]
	v_mfma_f32_16x16x32_bf16 v[80:83], v[202:205], v[164:167], v[76:79]
	v_mfma_f32_16x16x32_bf16 v[4:7], v[210:213], v[164:167], v[4:7]
	v_mfma_f32_16x16x32_bf16 v[72:75], v[202:205], v[194:197], v[72:75]
	v_mfma_f32_16x16x32_bf16 v[0:3], v[210:213], v[194:197], v[0:3]
	v_mfma_f32_16x16x32_bf16 v[52:55], v[202:205], v[132:135], v[52:55]
	s_barrier
	ds_read_b128 v[76:79], v237 offset:32768
	ds_read_b128 v[92:95], v237 offset:33792
	ds_read_b128 v[104:107], v237 offset:34816
	ds_read_b128 v[108:111], v237 offset:35840
	s_mov_b32 m0, s56
	ds_read_b128 v[124:127], v238 offset:32768
	ds_read_b128 v[132:135], v238 offset:33792
	ds_read_b128 v[156:159], v238 offset:34816
	ds_read_b128 v[164:167], v238 offset:36864
	ds_read_b128 v[194:197], v238 offset:38912
	ds_read_b128 v[160:163], v238 offset:35840
	ds_read_b128 v[190:193], v238 offset:37888
	global_load_lds_dwordx4 v180, s[12:13]
	s_mov_b32 m0, s57
	ds_read_b128 v[198:201], v238 offset:39936
	global_load_lds_dwordx4 v182, s[12:13]
	s_waitcnt lgkmcnt(8)
	s_barrier
	s_waitcnt lgkmcnt(4)
	v_mfma_f32_16x16x32_bf16 v[140:143], v[76:79], v[124:127], v[152:155]
	v_mfma_f32_16x16x32_bf16 v[152:155], v[92:95], v[132:135], v[140:143]
	v_mfma_f32_16x16x32_bf16 v[68:71], v[104:107], v[124:127], v[68:71]
	v_mfma_f32_16x16x32_bf16 v[140:143], v[76:79], v[156:159], v[148:151]
	v_mfma_f32_16x16x32_bf16 v[64:67], v[104:107], v[156:159], v[64:67]
	v_mfma_f32_16x16x32_bf16 v[136:139], v[76:79], v[164:167], v[136:139]
	v_mfma_f32_16x16x32_bf16 v[44:47], v[104:107], v[164:167], v[44:47]
	s_waitcnt lgkmcnt(0)
	v_mfma_f32_16x16x32_bf16 v[128:131], v[76:79], v[194:197], v[128:131]
	v_mfma_f32_16x16x32_bf16 v[40:43], v[104:107], v[194:197], v[40:43]
	v_mfma_f32_16x16x32_bf16 v[68:71], v[108:111], v[132:135], v[68:71]
	v_mfma_f32_16x16x32_bf16 v[148:151], v[92:95], v[160:163], v[140:143]
	v_mfma_f32_16x16x32_bf16 v[64:67], v[108:111], v[160:163], v[64:67]
	v_mfma_f32_16x16x32_bf16 v[136:139], v[92:95], v[190:193], v[136:139]
	v_mfma_f32_16x16x32_bf16 v[44:47], v[108:111], v[190:193], v[44:47]
	v_mfma_f32_16x16x32_bf16 v[128:131], v[92:95], v[198:201], v[128:131]
	v_mfma_f32_16x16x32_bf16 v[40:43], v[108:111], v[198:201], v[40:43]
	s_barrier
	ds_read_b128 v[202:205], v237 offset:49152
	ds_read_b128 v[206:209], v237 offset:50176
	s_add_i32 m0, s53, 0x18000
	ds_read_b128 v[210:213], v237 offset:51200
	global_load_lds_dwordx4 v168, s[98:99]
	s_add_i32 m0, s53, 0x1a000
	ds_read_b128 v[214:217], v237 offset:52224
	global_load_lds_dwordx4 v184, s[98:99]
	s_barrier
	s_waitcnt lgkmcnt(2)
	v_mfma_f32_16x16x32_bf16 v[140:143], v[202:205], v[124:127], v[144:147]
	v_mfma_f32_16x16x32_bf16 v[112:115], v[202:205], v[156:159], v[112:115]
	v_mfma_f32_16x16x32_bf16 v[144:147], v[206:209], v[132:135], v[140:143]
	s_waitcnt lgkmcnt(0)
	v_mfma_f32_16x16x32_bf16 v[60:63], v[210:213], v[124:127], v[60:63]
	v_mfma_f32_16x16x32_bf16 v[140:143], v[206:209], v[160:163], v[112:115]
	v_mfma_f32_16x16x32_bf16 v[112:115], v[202:205], v[164:167], v[116:119]
	v_mfma_f32_16x16x32_bf16 v[60:63], v[214:217], v[132:135], v[60:63]
	v_mfma_f32_16x16x32_bf16 v[56:59], v[210:213], v[156:159], v[56:59]
	v_mfma_f32_16x16x32_bf16 v[132:135], v[206:209], v[190:193], v[112:115]
	v_mfma_f32_16x16x32_bf16 v[36:39], v[210:213], v[164:167], v[36:39]
	v_mfma_f32_16x16x32_bf16 v[112:115], v[202:205], v[194:197], v[120:123]
	v_mfma_f32_16x16x32_bf16 v[32:35], v[210:213], v[194:197], v[32:35]
	v_mfma_f32_16x16x32_bf16 v[56:59], v[214:217], v[160:163], v[56:59]
	v_mfma_f32_16x16x32_bf16 v[36:39], v[214:217], v[190:193], v[36:39]
	v_mfma_f32_16x16x32_bf16 v[124:127], v[206:209], v[198:201], v[112:115]
	v_mfma_f32_16x16x32_bf16 v[32:35], v[214:217], v[198:201], v[32:35]
	s_mov_b32 m0, s62
	s_barrier
	ds_read_b128 v[112:115], v238 offset:49152
	ds_read_b128 v[120:123], v238 offset:51200
	ds_read_b128 v[160:163], v238 offset:53248
	ds_read_b128 v[190:193], v238 offset:55296
	ds_read_b128 v[116:119], v238 offset:50176
	ds_read_b128 v[156:159], v238 offset:52224
	ds_read_b128 v[164:167], v238 offset:54272
	global_load_lds_dwordx4 v180, s[100:101]
	s_mov_b32 m0, s63
	ds_read_b128 v[194:197], v238 offset:56320
	global_load_lds_dwordx4 v182, s[100:101]
	s_barrier
	s_waitcnt lgkmcnt(4)
	v_mfma_f32_16x16x32_bf16 v[100:103], v[76:79], v[112:115], v[100:103]
	v_mfma_f32_16x16x32_bf16 v[28:31], v[104:107], v[112:115], v[28:31]
	v_mfma_f32_16x16x32_bf16 v[96:99], v[76:79], v[120:123], v[96:99]
	v_mfma_f32_16x16x32_bf16 v[24:27], v[104:107], v[120:123], v[24:27]
	v_mfma_f32_16x16x32_bf16 v[84:87], v[76:79], v[160:163], v[84:87]
	v_mfma_f32_16x16x32_bf16 v[12:15], v[104:107], v[160:163], v[12:15]
	v_mfma_f32_16x16x32_bf16 v[48:51], v[76:79], v[190:193], v[48:51]
	v_mfma_f32_16x16x32_bf16 v[8:11], v[104:107], v[190:193], v[8:11]
	s_waitcnt lgkmcnt(0)
	v_mfma_f32_16x16x32_bf16 v[100:103], v[92:95], v[116:119], v[100:103]
	v_mfma_f32_16x16x32_bf16 v[28:31], v[108:111], v[116:119], v[28:31]
	v_mfma_f32_16x16x32_bf16 v[96:99], v[92:95], v[156:159], v[96:99]
	v_mfma_f32_16x16x32_bf16 v[24:27], v[108:111], v[156:159], v[24:27]
	v_mfma_f32_16x16x32_bf16 v[84:87], v[92:95], v[164:167], v[84:87]
	v_mfma_f32_16x16x32_bf16 v[12:15], v[108:111], v[164:167], v[12:15]
	v_mfma_f32_16x16x32_bf16 v[76:79], v[92:95], v[194:197], v[48:51]
	v_mfma_f32_16x16x32_bf16 v[8:11], v[108:111], v[194:197], v[8:11]
	s_barrier
	s_add_i32 m0, s53, 0x1c000
	s_add_u32 s2, s2, 0x40080
	s_addc_u32 s3, s3, 0
	global_load_lds_dwordx4 v168, s[2:3]
	s_add_i32 m0, s53, 0x1e000
	s_add_i32 s67, s67, 2
	global_load_lds_dwordx4 v184, s[2:3]
	s_waitcnt vmcnt(6)
	s_barrier
	v_mfma_f32_16x16x32_bf16 v[48:51], v[202:205], v[112:115], v[52:55]
	v_mfma_f32_16x16x32_bf16 v[92:95], v[206:209], v[116:119], v[48:51]
	v_mfma_f32_16x16x32_bf16 v[48:51], v[202:205], v[120:123], v[88:91]
	v_mfma_f32_16x16x32_bf16 v[88:91], v[206:209], v[156:159], v[48:51]
	v_mfma_f32_16x16x32_bf16 v[48:51], v[202:205], v[160:163], v[80:83]
	v_mfma_f32_16x16x32_bf16 v[20:23], v[210:213], v[112:115], v[20:23]
	v_mfma_f32_16x16x32_bf16 v[16:19], v[210:213], v[120:123], v[16:19]
	v_mfma_f32_16x16x32_bf16 v[80:83], v[206:209], v[164:167], v[48:51]
	v_mfma_f32_16x16x32_bf16 v[4:7], v[210:213], v[160:163], v[4:7]
	v_mfma_f32_16x16x32_bf16 v[48:51], v[202:205], v[190:193], v[72:75]
	v_mfma_f32_16x16x32_bf16 v[0:3], v[210:213], v[190:193], v[0:3]
	v_mfma_f32_16x16x32_bf16 v[20:23], v[214:217], v[116:119], v[20:23]
	v_mfma_f32_16x16x32_bf16 v[16:19], v[214:217], v[156:159], v[16:19]
	v_mfma_f32_16x16x32_bf16 v[4:7], v[214:217], v[164:167], v[4:7]
	v_mfma_f32_16x16x32_bf16 v[72:75], v[206:209], v[194:197], v[48:51]
	v_mfma_f32_16x16x32_bf16 v[0:3], v[214:217], v[194:197], v[0:3]
	s_add_u32 s10, s10, 0x100
	s_addc_u32 s11, s11, 0
	s_add_u32 s37, s37, 0x100
	s_addc_u32 s39, s39, 0
	s_cmp_gt_u32 s67, 13
	s_barrier
	s_cbranch_scc0 .LBB0_880

.LBB0_1048:
	s_add_u32 s56, s2, 0x100
	s_addc_u32 s57, s3, 0
	s_mov_b32 s58, -2
	s_add_u32 s2, s24, 0x100
	s_addc_u32 s3, s25, 0
	ds_read_b128 v[40:43], v194
	ds_read_b128 v[48:51], v194 offset:2048
	ds_read_b128 v[44:47], v194 offset:1024
	ds_read_b128 v[52:55], v194 offset:3072
	s_cmp_eq_u32 s58, 40
	s_cselect_b32 s27, s1, s3
	s_cselect_b32 s26, s0, s2
	s_cselect_b32 s9, s23, s57
	s_cselect_b32 s8, s22, s56
	s_add_i32 m0, s37, 0xc000
	ds_read_b128 v[56:59], v195
	ds_read_b128 v[72:75], v195 offset:2048
	ds_read_b128 v[182:185], v195 offset:4096
	ds_read_b128 v[196:199], v195 offset:6144
	ds_read_b128 v[60:63], v195 offset:1024
	ds_read_b128 v[84:87], v195 offset:3072
	ds_read_b128 v[186:189], v195 offset:5120
	global_load_lds_dwordx4 v166, s[24:25]
	s_add_i32 m0, s37, 0xe000
	ds_read_b128 v[200:203], v195 offset:7168
	global_load_lds_dwordx4 v180, s[24:25]
	s_waitcnt lgkmcnt(8)
	s_barrier
	s_waitcnt lgkmcnt(4)
	v_mfma_f32_16x16x32_bf16 v[156:159], v[40:43], v[56:59], 0
	v_mfma_f32_16x16x32_bf16 v[152:155], v[48:51], v[56:59], 0
	v_mfma_f32_16x16x32_bf16 v[140:143], v[40:43], v[72:75], 0
	v_mfma_f32_16x16x32_bf16 v[136:139], v[48:51], v[72:75], 0
	v_mfma_f32_16x16x32_bf16 v[124:127], v[40:43], v[182:185], 0
	v_mfma_f32_16x16x32_bf16 v[120:123], v[48:51], v[182:185], 0
	v_mfma_f32_16x16x32_bf16 v[108:111], v[40:43], v[196:199], 0
	v_mfma_f32_16x16x32_bf16 v[104:107], v[48:51], v[196:199], 0
	s_waitcnt lgkmcnt(0)
	v_mfma_f32_16x16x32_bf16 v[156:159], v[44:47], v[60:63], v[156:159]
	v_mfma_f32_16x16x32_bf16 v[152:155], v[52:55], v[60:63], v[152:155]
	v_mfma_f32_16x16x32_bf16 v[140:143], v[44:47], v[84:87], v[140:143]
	v_mfma_f32_16x16x32_bf16 v[136:139], v[52:55], v[84:87], v[136:139]
	v_mfma_f32_16x16x32_bf16 v[124:127], v[44:47], v[186:189], v[124:127]
	v_mfma_f32_16x16x32_bf16 v[120:123], v[52:55], v[186:189], v[120:123]
	v_mfma_f32_16x16x32_bf16 v[108:111], v[44:47], v[200:203], v[108:111]
	v_mfma_f32_16x16x32_bf16 v[104:107], v[52:55], v[200:203], v[104:107]
	s_barrier
	ds_read_b128 v[204:207], v194 offset:16384
	ds_read_b128 v[212:215], v194 offset:18432
	ds_read_b128 v[208:211], v194 offset:17408
	s_add_i32 m0, s36, 0x10000
	ds_read_b128 v[216:219], v194 offset:19456
	global_load_lds_dwordx4 v168, s[8:9]
	s_add_i32 m0, s36, 0x12000
	s_add_u32 s98, s8, 0x80
	s_addc_u32 s99, s9, 0
	global_load_lds_dwordx4 v164, s[8:9]
	s_barrier
	s_waitcnt lgkmcnt(2)
	v_mfma_f32_16x16x32_bf16 v[148:151], v[204:207], v[56:59], 0
	v_mfma_f32_16x16x32_bf16 v[56:59], v[212:215], v[56:59], 0
	s_waitcnt lgkmcnt(0)
	v_mfma_f32_16x16x32_bf16 v[148:151], v[208:211], v[60:63], v[148:151]
	v_mfma_f32_16x16x32_bf16 v[56:59], v[216:219], v[60:63], v[56:59]
	v_mfma_f32_16x16x32_bf16 v[60:63], v[204:207], v[72:75], 0
	v_mfma_f32_16x16x32_bf16 v[72:75], v[212:215], v[72:75], 0
	v_mfma_f32_16x16x32_bf16 v[112:115], v[212:215], v[182:185], 0
	v_mfma_f32_16x16x32_bf16 v[100:103], v[204:207], v[196:199], 0
	v_mfma_f32_16x16x32_bf16 v[96:99], v[212:215], v[196:199], 0
	v_mfma_f32_16x16x32_bf16 v[60:63], v[208:211], v[84:87], v[60:63]
	v_mfma_f32_16x16x32_bf16 v[72:75], v[216:219], v[84:87], v[72:75]
	v_mfma_f32_16x16x32_bf16 v[84:87], v[204:207], v[182:185], 0
	v_mfma_f32_16x16x32_bf16 v[112:115], v[216:219], v[186:189], v[112:115]
	v_mfma_f32_16x16x32_bf16 v[100:103], v[208:211], v[200:203], v[100:103]
	v_mfma_f32_16x16x32_bf16 v[96:99], v[216:219], v[200:203], v[96:99]
	v_mfma_f32_16x16x32_bf16 v[84:87], v[208:211], v[186:189], v[84:87]
	s_mov_b32 m0, s37
	s_add_u32 s100, s26, 0x80
	s_addc_u32 s101, s27, 0
	s_barrier
	ds_read_b128 v[116:119], v195 offset:16384
	ds_read_b128 v[132:135], v195 offset:18432
	ds_read_b128 v[182:185], v195 offset:20480
	ds_read_b128 v[196:199], v195 offset:22528
	ds_read_b128 v[128:131], v195 offset:17408
	ds_read_b128 v[144:147], v195 offset:19456
	ds_read_b128 v[186:189], v195 offset:21504
	global_load_lds_dwordx4 v160, s[26:27]
	s_mov_b32 m0, s38
	ds_read_b128 v[200:203], v195 offset:23552
	global_load_lds_dwordx4 v162, s[26:27]
	s_barrier
	s_waitcnt lgkmcnt(4)
	v_mfma_f32_16x16x32_bf16 v[92:95], v[40:43], v[116:119], 0
	v_mfma_f32_16x16x32_bf16 v[88:91], v[48:51], v[116:119], 0
	v_mfma_f32_16x16x32_bf16 v[68:71], v[40:43], v[132:135], 0
	v_mfma_f32_16x16x32_bf16 v[64:67], v[48:51], v[132:135], 0
	v_mfma_f32_16x16x32_bf16 v[28:31], v[40:43], v[182:185], 0
	v_mfma_f32_16x16x32_bf16 v[24:27], v[48:51], v[182:185], 0
	v_mfma_f32_16x16x32_bf16 v[12:15], v[40:43], v[196:199], 0
	v_mfma_f32_16x16x32_bf16 v[8:11], v[48:51], v[196:199], 0
	s_waitcnt lgkmcnt(0)
	v_mfma_f32_16x16x32_bf16 v[92:95], v[44:47], v[128:131], v[92:95]
	v_mfma_f32_16x16x32_bf16 v[88:91], v[52:55], v[128:131], v[88:91]
	v_mfma_f32_16x16x32_bf16 v[68:71], v[44:47], v[144:147], v[68:71]
	v_mfma_f32_16x16x32_bf16 v[64:67], v[52:55], v[144:147], v[64:67]
	v_mfma_f32_16x16x32_bf16 v[28:31], v[44:47], v[186:189], v[28:31]
	v_mfma_f32_16x16x32_bf16 v[24:27], v[52:55], v[186:189], v[24:27]
	v_mfma_f32_16x16x32_bf16 v[12:15], v[44:47], v[200:203], v[12:15]
	v_mfma_f32_16x16x32_bf16 v[8:11], v[52:55], v[200:203], v[8:11]
	s_barrier
	s_add_i32 m0, s36, 0x14000
	s_add_u32 s24, s8, 0xb0000
	s_addc_u32 s25, s9, 0
	global_load_lds_dwordx4 v168, s[24:25]
	s_add_i32 m0, s36, 0x16000
	s_nop 0
	global_load_lds_dwordx4 v164, s[24:25]
	s_waitcnt vmcnt(6)
	s_barrier
	v_mfma_f32_16x16x32_bf16 v[36:39], v[204:207], v[132:135], 0
	v_mfma_f32_16x16x32_bf16 v[32:35], v[212:215], v[132:135], 0
	v_mfma_f32_16x16x32_bf16 v[20:23], v[204:207], v[182:185], 0
	v_mfma_f32_16x16x32_bf16 v[16:19], v[212:215], v[182:185], 0
	v_mfma_f32_16x16x32_bf16 v[4:7], v[204:207], v[196:199], 0
	v_mfma_f32_16x16x32_bf16 v[0:3], v[212:215], v[196:199], 0
	v_mfma_f32_16x16x32_bf16 v[40:43], v[204:207], v[116:119], 0
	v_mfma_f32_16x16x32_bf16 v[44:47], v[212:215], v[116:119], 0
	v_mfma_f32_16x16x32_bf16 v[36:39], v[208:211], v[144:147], v[36:39]
	v_mfma_f32_16x16x32_bf16 v[32:35], v[216:219], v[144:147], v[32:35]
	v_mfma_f32_16x16x32_bf16 v[20:23], v[208:211], v[186:189], v[20:23]
	v_mfma_f32_16x16x32_bf16 v[16:19], v[216:219], v[186:189], v[16:19]
	v_mfma_f32_16x16x32_bf16 v[4:7], v[208:211], v[200:203], v[4:7]
	v_mfma_f32_16x16x32_bf16 v[0:3], v[216:219], v[200:203], v[0:3]
	v_mfma_f32_16x16x32_bf16 v[40:43], v[208:211], v[128:131], v[40:43]
	v_mfma_f32_16x16x32_bf16 v[44:47], v[216:219], v[128:131], v[44:47]
	s_barrier
	ds_read_b128 v[48:51], v194 offset:32768
	ds_read_b128 v[52:55], v194 offset:33792
	ds_read_b128 v[76:79], v194 offset:34816
	ds_read_b128 v[80:83], v194 offset:35840
	s_add_u32 s24, s26, 0xb0000
	s_addc_u32 s25, s27, 0
	s_mov_b32 m0, s39
	ds_read_b128 v[116:119], v195 offset:32768
	ds_read_b128 v[128:131], v195 offset:33792
	ds_read_b128 v[182:185], v195 offset:34816
	ds_read_b128 v[186:189], v195 offset:35840
	ds_read_b128 v[196:199], v195 offset:36864
	ds_read_b128 v[204:207], v195 offset:38912
	ds_read_b128 v[200:203], v195 offset:37888
	global_load_lds_dwordx4 v160, s[24:25]
	s_mov_b32 m0, s40
	ds_read_b128 v[208:211], v195 offset:39936
	global_load_lds_dwordx4 v162, s[24:25]
	s_waitcnt lgkmcnt(8)
	s_barrier
	s_waitcnt lgkmcnt(4)
	v_mfma_f32_16x16x32_bf16 v[132:135], v[48:51], v[116:119], v[156:159]
	v_mfma_f32_16x16x32_bf16 v[156:159], v[52:55], v[128:131], v[132:135]
	v_mfma_f32_16x16x32_bf16 v[132:135], v[76:79], v[116:119], v[152:155]
	v_mfma_f32_16x16x32_bf16 v[152:155], v[80:83], v[128:131], v[132:135]
	v_mfma_f32_16x16x32_bf16 v[132:135], v[48:51], v[182:185], v[140:143]
	v_mfma_f32_16x16x32_bf16 v[140:143], v[52:55], v[186:189], v[132:135]
	v_mfma_f32_16x16x32_bf16 v[132:135], v[76:79], v[182:185], v[136:139]
	s_waitcnt lgkmcnt(0)
	v_mfma_f32_16x16x32_bf16 v[124:127], v[48:51], v[196:199], v[124:127]
	v_mfma_f32_16x16x32_bf16 v[120:123], v[76:79], v[196:199], v[120:123]
	v_mfma_f32_16x16x32_bf16 v[108:111], v[48:51], v[204:207], v[108:111]
	v_mfma_f32_16x16x32_bf16 v[104:107], v[76:79], v[204:207], v[104:107]
	v_mfma_f32_16x16x32_bf16 v[136:139], v[80:83], v[186:189], v[132:135]
	v_mfma_f32_16x16x32_bf16 v[124:127], v[52:55], v[200:203], v[124:127]
	v_mfma_f32_16x16x32_bf16 v[120:123], v[80:83], v[200:203], v[120:123]
	v_mfma_f32_16x16x32_bf16 v[108:111], v[52:55], v[208:211], v[108:111]
	v_mfma_f32_16x16x32_bf16 v[104:107], v[80:83], v[208:211], v[104:107]
	s_barrier
	ds_read_b128 v[220:223], v194 offset:51200
	ds_read_b128 v[212:215], v194 offset:49152
	s_add_i32 m0, s36, 0x18000
	ds_read_b128 v[236:239], v194 offset:52224
	global_load_lds_dwordx4 v168, s[98:99]
	s_add_i32 m0, s36, 0x1a000
	ds_read_b128 v[216:219], v194 offset:50176
	global_load_lds_dwordx4 v164, s[98:99]
	s_barrier
	s_waitcnt lgkmcnt(2)
	v_mfma_f32_16x16x32_bf16 v[56:59], v[220:223], v[116:119], v[56:59]
	v_mfma_f32_16x16x32_bf16 v[132:135], v[212:215], v[116:119], v[148:151]
	s_waitcnt lgkmcnt(0)
	v_mfma_f32_16x16x32_bf16 v[144:147], v[236:239], v[128:131], v[56:59]
	v_mfma_f32_16x16x32_bf16 v[56:59], v[212:215], v[182:185], v[60:63]
	v_mfma_f32_16x16x32_bf16 v[148:151], v[216:219], v[128:131], v[132:135]
	v_mfma_f32_16x16x32_bf16 v[132:135], v[216:219], v[186:189], v[56:59]
	v_mfma_f32_16x16x32_bf16 v[56:59], v[220:223], v[182:185], v[72:75]
	v_mfma_f32_16x16x32_bf16 v[128:131], v[236:239], v[186:189], v[56:59]
	v_mfma_f32_16x16x32_bf16 v[56:59], v[212:215], v[196:199], v[84:87]
	v_mfma_f32_16x16x32_bf16 v[116:119], v[216:219], v[200:203], v[56:59]
	v_mfma_f32_16x16x32_bf16 v[56:59], v[220:223], v[196:199], v[112:115]
	v_mfma_f32_16x16x32_bf16 v[112:115], v[236:239], v[200:203], v[56:59]
	v_mfma_f32_16x16x32_bf16 v[56:59], v[212:215], v[204:207], v[100:103]
	v_mfma_f32_16x16x32_bf16 v[100:103], v[216:219], v[208:211], v[56:59]
	v_mfma_f32_16x16x32_bf16 v[56:59], v[220:223], v[204:207], v[96:99]
	v_mfma_f32_16x16x32_bf16 v[96:99], v[236:239], v[208:211], v[56:59]
	s_mov_b32 m0, s47
	s_barrier
	s_nop 2
	ds_read_b128 v[56:59], v195 offset:49152
	ds_read_b128 v[72:75], v195 offset:51200
	ds_read_b128 v[182:185], v195 offset:53248
	ds_read_b128 v[196:199], v195 offset:55296
	ds_read_b128 v[60:63], v195 offset:50176
	ds_read_b128 v[84:87], v195 offset:52224
	ds_read_b128 v[186:189], v195 offset:54272
	global_load_lds_dwordx4 v160, s[100:101]
	s_mov_b32 m0, s49
	ds_read_b128 v[200:203], v195 offset:56320
	global_load_lds_dwordx4 v162, s[100:101]
	s_barrier
	s_waitcnt lgkmcnt(4)
	v_mfma_f32_16x16x32_bf16 v[92:95], v[48:51], v[56:59], v[92:95]
	v_mfma_f32_16x16x32_bf16 v[88:91], v[76:79], v[56:59], v[88:91]
	v_mfma_f32_16x16x32_bf16 v[68:71], v[48:51], v[72:75], v[68:71]
	v_mfma_f32_16x16x32_bf16 v[64:67], v[76:79], v[72:75], v[64:67]
	v_mfma_f32_16x16x32_bf16 v[28:31], v[48:51], v[182:185], v[28:31]
	v_mfma_f32_16x16x32_bf16 v[24:27], v[76:79], v[182:185], v[24:27]
	v_mfma_f32_16x16x32_bf16 v[12:15], v[48:51], v[196:199], v[12:15]
	v_mfma_f32_16x16x32_bf16 v[8:11], v[76:79], v[196:199], v[8:11]
	s_waitcnt lgkmcnt(0)
	v_mfma_f32_16x16x32_bf16 v[92:95], v[52:55], v[60:63], v[92:95]
	v_mfma_f32_16x16x32_bf16 v[88:91], v[80:83], v[60:63], v[88:91]
	v_mfma_f32_16x16x32_bf16 v[68:71], v[52:55], v[84:87], v[68:71]
	v_mfma_f32_16x16x32_bf16 v[64:67], v[80:83], v[84:87], v[64:67]
	v_mfma_f32_16x16x32_bf16 v[28:31], v[52:55], v[186:189], v[28:31]
	v_mfma_f32_16x16x32_bf16 v[24:27], v[80:83], v[186:189], v[24:27]
	v_mfma_f32_16x16x32_bf16 v[12:15], v[52:55], v[200:203], v[12:15]
	v_mfma_f32_16x16x32_bf16 v[8:11], v[80:83], v[200:203], v[8:11]
	s_barrier
	s_add_i32 m0, s36, 0x1c000
	s_add_u32 s8, s8, 0xb0080
	s_addc_u32 s9, s9, 0
	global_load_lds_dwordx4 v168, s[8:9]
	s_add_i32 m0, s36, 0x1e000
	s_add_i32 s58, s58, 2
	global_load_lds_dwordx4 v164, s[8:9]
	s_waitcnt vmcnt(6)
	s_barrier
	v_mfma_f32_16x16x32_bf16 v[40:43], v[212:215], v[56:59], v[40:43]
	v_mfma_f32_16x16x32_bf16 v[80:83], v[216:219], v[60:63], v[40:43]
	v_mfma_f32_16x16x32_bf16 v[40:43], v[220:223], v[56:59], v[44:47]
	v_mfma_f32_16x16x32_bf16 v[36:39], v[212:215], v[72:75], v[36:39]
	v_mfma_f32_16x16x32_bf16 v[32:35], v[220:223], v[72:75], v[32:35]
	v_mfma_f32_16x16x32_bf16 v[20:23], v[212:215], v[182:185], v[20:23]
	v_mfma_f32_16x16x32_bf16 v[16:19], v[220:223], v[182:185], v[16:19]
	v_mfma_f32_16x16x32_bf16 v[4:7], v[212:215], v[196:199], v[4:7]
	v_mfma_f32_16x16x32_bf16 v[0:3], v[220:223], v[196:199], v[0:3]
	v_mfma_f32_16x16x32_bf16 v[76:79], v[236:239], v[60:63], v[40:43]
	v_mfma_f32_16x16x32_bf16 v[36:39], v[216:219], v[84:87], v[36:39]
	v_mfma_f32_16x16x32_bf16 v[32:35], v[236:239], v[84:87], v[32:35]
	v_mfma_f32_16x16x32_bf16 v[20:23], v[216:219], v[186:189], v[20:23]
	v_mfma_f32_16x16x32_bf16 v[16:19], v[236:239], v[186:189], v[16:19]
	v_mfma_f32_16x16x32_bf16 v[4:7], v[216:219], v[200:203], v[4:7]
	v_mfma_f32_16x16x32_bf16 v[0:3], v[236:239], v[200:203], v[0:3]
	s_add_u32 s56, s56, 0x100
	s_addc_u32 s57, s57, 0
	s_cmp_gt_u32 s58, 41
	s_mov_b64 s[24:25], s[2:3]
	s_barrier
.LBB0_1049:
	s_add_u32 s2, s24, 0x100
	s_addc_u32 s3, s25, 0
	ds_read_b128 v[40:43], v194
	ds_read_b128 v[48:51], v194 offset:2048
	ds_read_b128 v[44:47], v194 offset:1024
	ds_read_b128 v[52:55], v194 offset:3072
	s_cmp_eq_u32 s58, 40
	s_cselect_b32 s27, s1, s3
	s_cselect_b32 s26, s0, s2
	s_cselect_b32 s9, s23, s57
	s_cselect_b32 s8, s22, s56
	s_add_i32 m0, s37, 0xc000
	ds_read_b128 v[56:59], v195
	ds_read_b128 v[72:75], v195 offset:2048
	ds_read_b128 v[182:185], v195 offset:4096
	ds_read_b128 v[196:199], v195 offset:6144
	ds_read_b128 v[60:63], v195 offset:1024
	ds_read_b128 v[84:87], v195 offset:3072
	ds_read_b128 v[186:189], v195 offset:5120
	global_load_lds_dwordx4 v166, s[24:25]
	s_add_i32 m0, s37, 0xe000
	ds_read_b128 v[200:203], v195 offset:7168
	global_load_lds_dwordx4 v180, s[24:25]
	s_waitcnt lgkmcnt(8)
	s_barrier
	s_waitcnt lgkmcnt(4)
	v_mfma_f32_16x16x32_bf16 v[156:159], v[40:43], v[56:59], v[156:159]
	v_mfma_f32_16x16x32_bf16 v[152:155], v[48:51], v[56:59], v[152:155]
	v_mfma_f32_16x16x32_bf16 v[140:143], v[40:43], v[72:75], v[140:143]
	v_mfma_f32_16x16x32_bf16 v[136:139], v[48:51], v[72:75], v[136:139]
	v_mfma_f32_16x16x32_bf16 v[124:127], v[40:43], v[182:185], v[124:127]
	v_mfma_f32_16x16x32_bf16 v[120:123], v[48:51], v[182:185], v[120:123]
	v_mfma_f32_16x16x32_bf16 v[108:111], v[40:43], v[196:199], v[108:111]
	v_mfma_f32_16x16x32_bf16 v[104:107], v[48:51], v[196:199], v[104:107]
	s_waitcnt lgkmcnt(0)
	v_mfma_f32_16x16x32_bf16 v[156:159], v[44:47], v[60:63], v[156:159]
	v_mfma_f32_16x16x32_bf16 v[152:155], v[52:55], v[60:63], v[152:155]
	v_mfma_f32_16x16x32_bf16 v[140:143], v[44:47], v[84:87], v[140:143]
	v_mfma_f32_16x16x32_bf16 v[136:139], v[52:55], v[84:87], v[136:139]
	v_mfma_f32_16x16x32_bf16 v[124:127], v[44:47], v[186:189], v[124:127]
	v_mfma_f32_16x16x32_bf16 v[120:123], v[52:55], v[186:189], v[120:123]
	v_mfma_f32_16x16x32_bf16 v[108:111], v[44:47], v[200:203], v[108:111]
	v_mfma_f32_16x16x32_bf16 v[104:107], v[52:55], v[200:203], v[104:107]
	s_barrier
	ds_read_b128 v[204:207], v194 offset:16384
	ds_read_b128 v[212:215], v194 offset:18432
	ds_read_b128 v[208:211], v194 offset:17408
	s_add_i32 m0, s36, 0x10000
	ds_read_b128 v[216:219], v194 offset:19456
	global_load_lds_dwordx4 v168, s[8:9]
	s_add_i32 m0, s36, 0x12000
	s_add_u32 s98, s8, 0x80
	s_addc_u32 s99, s9, 0
	global_load_lds_dwordx4 v164, s[8:9]
	s_barrier
	s_waitcnt lgkmcnt(2)
	v_mfma_f32_16x16x32_bf16 v[148:151], v[204:207], v[56:59], v[148:151]
	v_mfma_f32_16x16x32_bf16 v[56:59], v[212:215], v[56:59], v[144:147]
	s_waitcnt lgkmcnt(0)
	v_mfma_f32_16x16x32_bf16 v[148:151], v[208:211], v[60:63], v[148:151]
	v_mfma_f32_16x16x32_bf16 v[56:59], v[216:219], v[60:63], v[56:59]
	v_mfma_f32_16x16x32_bf16 v[60:63], v[204:207], v[72:75], v[132:135]
	v_mfma_f32_16x16x32_bf16 v[72:75], v[212:215], v[72:75], v[128:131]
	v_mfma_f32_16x16x32_bf16 v[112:115], v[212:215], v[182:185], v[112:115]
	v_mfma_f32_16x16x32_bf16 v[100:103], v[204:207], v[196:199], v[100:103]
	v_mfma_f32_16x16x32_bf16 v[96:99], v[212:215], v[196:199], v[96:99]
	v_mfma_f32_16x16x32_bf16 v[60:63], v[208:211], v[84:87], v[60:63]
	v_mfma_f32_16x16x32_bf16 v[72:75], v[216:219], v[84:87], v[72:75]
	v_mfma_f32_16x16x32_bf16 v[84:87], v[204:207], v[182:185], v[116:119]
	v_mfma_f32_16x16x32_bf16 v[112:115], v[216:219], v[186:189], v[112:115]
	v_mfma_f32_16x16x32_bf16 v[100:103], v[208:211], v[200:203], v[100:103]
	v_mfma_f32_16x16x32_bf16 v[96:99], v[216:219], v[200:203], v[96:99]
	v_mfma_f32_16x16x32_bf16 v[84:87], v[208:211], v[186:189], v[84:87]
	s_mov_b32 m0, s37
	s_add_u32 s100, s26, 0x80
	s_addc_u32 s101, s27, 0
	s_barrier
	ds_read_b128 v[116:119], v195 offset:16384
	ds_read_b128 v[132:135], v195 offset:18432
	ds_read_b128 v[182:185], v195 offset:20480
	ds_read_b128 v[196:199], v195 offset:22528
	ds_read_b128 v[128:131], v195 offset:17408
	ds_read_b128 v[144:147], v195 offset:19456
	ds_read_b128 v[186:189], v195 offset:21504
	global_load_lds_dwordx4 v160, s[26:27]
	s_mov_b32 m0, s38
	ds_read_b128 v[200:203], v195 offset:23552
	global_load_lds_dwordx4 v162, s[26:27]
	s_barrier
	s_waitcnt lgkmcnt(4)
	v_mfma_f32_16x16x32_bf16 v[92:95], v[40:43], v[116:119], v[92:95]
	v_mfma_f32_16x16x32_bf16 v[88:91], v[48:51], v[116:119], v[88:91]
	v_mfma_f32_16x16x32_bf16 v[68:71], v[40:43], v[132:135], v[68:71]
	v_mfma_f32_16x16x32_bf16 v[64:67], v[48:51], v[132:135], v[64:67]
	v_mfma_f32_16x16x32_bf16 v[28:31], v[40:43], v[182:185], v[28:31]
	v_mfma_f32_16x16x32_bf16 v[24:27], v[48:51], v[182:185], v[24:27]
	v_mfma_f32_16x16x32_bf16 v[12:15], v[40:43], v[196:199], v[12:15]
	v_mfma_f32_16x16x32_bf16 v[8:11], v[48:51], v[196:199], v[8:11]
	s_waitcnt lgkmcnt(0)
	v_mfma_f32_16x16x32_bf16 v[92:95], v[44:47], v[128:131], v[92:95]
	v_mfma_f32_16x16x32_bf16 v[88:91], v[52:55], v[128:131], v[88:91]
	v_mfma_f32_16x16x32_bf16 v[68:71], v[44:47], v[144:147], v[68:71]
	v_mfma_f32_16x16x32_bf16 v[64:67], v[52:55], v[144:147], v[64:67]
	v_mfma_f32_16x16x32_bf16 v[28:31], v[44:47], v[186:189], v[28:31]
	v_mfma_f32_16x16x32_bf16 v[24:27], v[52:55], v[186:189], v[24:27]
	v_mfma_f32_16x16x32_bf16 v[12:15], v[44:47], v[200:203], v[12:15]
	v_mfma_f32_16x16x32_bf16 v[8:11], v[52:55], v[200:203], v[8:11]
	s_barrier
	s_add_i32 m0, s36, 0x14000
	s_add_u32 s24, s8, 0xb0000
	s_addc_u32 s25, s9, 0
	global_load_lds_dwordx4 v168, s[24:25]
	s_add_i32 m0, s36, 0x16000
	s_nop 0
	global_load_lds_dwordx4 v164, s[24:25]
	s_waitcnt vmcnt(6)
	s_barrier
	v_mfma_f32_16x16x32_bf16 v[36:39], v[204:207], v[132:135], v[36:39]
	v_mfma_f32_16x16x32_bf16 v[32:35], v[212:215], v[132:135], v[32:35]
	v_mfma_f32_16x16x32_bf16 v[20:23], v[204:207], v[182:185], v[20:23]
	v_mfma_f32_16x16x32_bf16 v[16:19], v[212:215], v[182:185], v[16:19]
	v_mfma_f32_16x16x32_bf16 v[4:7], v[204:207], v[196:199], v[4:7]
	v_mfma_f32_16x16x32_bf16 v[0:3], v[212:215], v[196:199], v[0:3]
	v_mfma_f32_16x16x32_bf16 v[40:43], v[204:207], v[116:119], v[80:83]
	v_mfma_f32_16x16x32_bf16 v[44:47], v[212:215], v[116:119], v[76:79]
	v_mfma_f32_16x16x32_bf16 v[36:39], v[208:211], v[144:147], v[36:39]
	v_mfma_f32_16x16x32_bf16 v[32:35], v[216:219], v[144:147], v[32:35]
	v_mfma_f32_16x16x32_bf16 v[20:23], v[208:211], v[186:189], v[20:23]
	v_mfma_f32_16x16x32_bf16 v[16:19], v[216:219], v[186:189], v[16:19]
	v_mfma_f32_16x16x32_bf16 v[4:7], v[208:211], v[200:203], v[4:7]
	v_mfma_f32_16x16x32_bf16 v[0:3], v[216:219], v[200:203], v[0:3]
	v_mfma_f32_16x16x32_bf16 v[40:43], v[208:211], v[128:131], v[40:43]
	v_mfma_f32_16x16x32_bf16 v[44:47], v[216:219], v[128:131], v[44:47]
	s_barrier
	ds_read_b128 v[48:51], v194 offset:32768
	ds_read_b128 v[52:55], v194 offset:33792
	ds_read_b128 v[76:79], v194 offset:34816
	ds_read_b128 v[80:83], v194 offset:35840
	s_add_u32 s24, s26, 0xb0000
	s_addc_u32 s25, s27, 0
	s_mov_b32 m0, s39
	ds_read_b128 v[116:119], v195 offset:32768
	ds_read_b128 v[128:131], v195 offset:33792
	ds_read_b128 v[182:185], v195 offset:34816
	ds_read_b128 v[186:189], v195 offset:35840
	ds_read_b128 v[196:199], v195 offset:36864
	ds_read_b128 v[204:207], v195 offset:38912
	ds_read_b128 v[200:203], v195 offset:37888
	global_load_lds_dwordx4 v160, s[24:25]
	s_mov_b32 m0, s40
	ds_read_b128 v[208:211], v195 offset:39936
	global_load_lds_dwordx4 v162, s[24:25]
	s_waitcnt lgkmcnt(8)
	s_barrier
	s_waitcnt lgkmcnt(4)
	v_mfma_f32_16x16x32_bf16 v[132:135], v[48:51], v[116:119], v[156:159]
	v_mfma_f32_16x16x32_bf16 v[156:159], v[52:55], v[128:131], v[132:135]
	v_mfma_f32_16x16x32_bf16 v[132:135], v[76:79], v[116:119], v[152:155]
	v_mfma_f32_16x16x32_bf16 v[152:155], v[80:83], v[128:131], v[132:135]
	v_mfma_f32_16x16x32_bf16 v[132:135], v[48:51], v[182:185], v[140:143]
	v_mfma_f32_16x16x32_bf16 v[140:143], v[52:55], v[186:189], v[132:135]
	v_mfma_f32_16x16x32_bf16 v[132:135], v[76:79], v[182:185], v[136:139]
	s_waitcnt lgkmcnt(0)
	v_mfma_f32_16x16x32_bf16 v[124:127], v[48:51], v[196:199], v[124:127]
	v_mfma_f32_16x16x32_bf16 v[120:123], v[76:79], v[196:199], v[120:123]
	v_mfma_f32_16x16x32_bf16 v[108:111], v[48:51], v[204:207], v[108:111]
	v_mfma_f32_16x16x32_bf16 v[104:107], v[76:79], v[204:207], v[104:107]
	v_mfma_f32_16x16x32_bf16 v[136:139], v[80:83], v[186:189], v[132:135]
	v_mfma_f32_16x16x32_bf16 v[124:127], v[52:55], v[200:203], v[124:127]
	v_mfma_f32_16x16x32_bf16 v[120:123], v[80:83], v[200:203], v[120:123]
	v_mfma_f32_16x16x32_bf16 v[108:111], v[52:55], v[208:211], v[108:111]
	v_mfma_f32_16x16x32_bf16 v[104:107], v[80:83], v[208:211], v[104:107]
	s_barrier
	ds_read_b128 v[220:223], v194 offset:51200
	ds_read_b128 v[212:215], v194 offset:49152
	s_add_i32 m0, s36, 0x18000
	ds_read_b128 v[236:239], v194 offset:52224
	global_load_lds_dwordx4 v168, s[98:99]
	s_add_i32 m0, s36, 0x1a000
	ds_read_b128 v[216:219], v194 offset:50176
	global_load_lds_dwordx4 v164, s[98:99]
	s_barrier
	s_waitcnt lgkmcnt(2)
	v_mfma_f32_16x16x32_bf16 v[56:59], v[220:223], v[116:119], v[56:59]
	v_mfma_f32_16x16x32_bf16 v[132:135], v[212:215], v[116:119], v[148:151]
	s_waitcnt lgkmcnt(0)
	v_mfma_f32_16x16x32_bf16 v[144:147], v[236:239], v[128:131], v[56:59]
	v_mfma_f32_16x16x32_bf16 v[56:59], v[212:215], v[182:185], v[60:63]
	v_mfma_f32_16x16x32_bf16 v[148:151], v[216:219], v[128:131], v[132:135]
	v_mfma_f32_16x16x32_bf16 v[132:135], v[216:219], v[186:189], v[56:59]
	v_mfma_f32_16x16x32_bf16 v[56:59], v[220:223], v[182:185], v[72:75]
	v_mfma_f32_16x16x32_bf16 v[128:131], v[236:239], v[186:189], v[56:59]
	v_mfma_f32_16x16x32_bf16 v[56:59], v[212:215], v[196:199], v[84:87]
	v_mfma_f32_16x16x32_bf16 v[116:119], v[216:219], v[200:203], v[56:59]
	v_mfma_f32_16x16x32_bf16 v[56:59], v[220:223], v[196:199], v[112:115]
	v_mfma_f32_16x16x32_bf16 v[112:115], v[236:239], v[200:203], v[56:59]
	v_mfma_f32_16x16x32_bf16 v[56:59], v[212:215], v[204:207], v[100:103]
	v_mfma_f32_16x16x32_bf16 v[100:103], v[216:219], v[208:211], v[56:59]
	v_mfma_f32_16x16x32_bf16 v[56:59], v[220:223], v[204:207], v[96:99]
	v_mfma_f32_16x16x32_bf16 v[96:99], v[236:239], v[208:211], v[56:59]
	s_mov_b32 m0, s47
	s_barrier
	s_nop 2
	ds_read_b128 v[56:59], v195 offset:49152
	ds_read_b128 v[72:75], v195 offset:51200
	ds_read_b128 v[182:185], v195 offset:53248
	ds_read_b128 v[196:199], v195 offset:55296
	ds_read_b128 v[60:63], v195 offset:50176
	ds_read_b128 v[84:87], v195 offset:52224
	ds_read_b128 v[186:189], v195 offset:54272
	global_load_lds_dwordx4 v160, s[100:101]
	s_mov_b32 m0, s49
	ds_read_b128 v[200:203], v195 offset:56320
	global_load_lds_dwordx4 v162, s[100:101]
	s_barrier
	s_waitcnt lgkmcnt(4)
	v_mfma_f32_16x16x32_bf16 v[92:95], v[48:51], v[56:59], v[92:95]
	v_mfma_f32_16x16x32_bf16 v[88:91], v[76:79], v[56:59], v[88:91]
	v_mfma_f32_16x16x32_bf16 v[68:71], v[48:51], v[72:75], v[68:71]
	v_mfma_f32_16x16x32_bf16 v[64:67], v[76:79], v[72:75], v[64:67]
	v_mfma_f32_16x16x32_bf16 v[28:31], v[48:51], v[182:185], v[28:31]
	v_mfma_f32_16x16x32_bf16 v[24:27], v[76:79], v[182:185], v[24:27]
	v_mfma_f32_16x16x32_bf16 v[12:15], v[48:51], v[196:199], v[12:15]
	v_mfma_f32_16x16x32_bf16 v[8:11], v[76:79], v[196:199], v[8:11]
	s_waitcnt lgkmcnt(0)
	v_mfma_f32_16x16x32_bf16 v[92:95], v[52:55], v[60:63], v[92:95]
	v_mfma_f32_16x16x32_bf16 v[88:91], v[80:83], v[60:63], v[88:91]
	v_mfma_f32_16x16x32_bf16 v[68:71], v[52:55], v[84:87], v[68:71]
	v_mfma_f32_16x16x32_bf16 v[64:67], v[80:83], v[84:87], v[64:67]
	v_mfma_f32_16x16x32_bf16 v[28:31], v[52:55], v[186:189], v[28:31]
	v_mfma_f32_16x16x32_bf16 v[24:27], v[80:83], v[186:189], v[24:27]
	v_mfma_f32_16x16x32_bf16 v[12:15], v[52:55], v[200:203], v[12:15]
	v_mfma_f32_16x16x32_bf16 v[8:11], v[80:83], v[200:203], v[8:11]
	s_barrier
	s_add_i32 m0, s36, 0x1c000
	s_add_u32 s8, s8, 0xb0080
	s_addc_u32 s9, s9, 0
	global_load_lds_dwordx4 v168, s[8:9]
	s_add_i32 m0, s36, 0x1e000
	s_add_i32 s58, s58, 2
	global_load_lds_dwordx4 v164, s[8:9]
	s_waitcnt vmcnt(6)
	s_barrier
	v_mfma_f32_16x16x32_bf16 v[40:43], v[212:215], v[56:59], v[40:43]
	v_mfma_f32_16x16x32_bf16 v[80:83], v[216:219], v[60:63], v[40:43]
	v_mfma_f32_16x16x32_bf16 v[40:43], v[220:223], v[56:59], v[44:47]
	v_mfma_f32_16x16x32_bf16 v[36:39], v[212:215], v[72:75], v[36:39]
	v_mfma_f32_16x16x32_bf16 v[32:35], v[220:223], v[72:75], v[32:35]
	v_mfma_f32_16x16x32_bf16 v[20:23], v[212:215], v[182:185], v[20:23]
	v_mfma_f32_16x16x32_bf16 v[16:19], v[220:223], v[182:185], v[16:19]
	v_mfma_f32_16x16x32_bf16 v[4:7], v[212:215], v[196:199], v[4:7]
	v_mfma_f32_16x16x32_bf16 v[0:3], v[220:223], v[196:199], v[0:3]
	v_mfma_f32_16x16x32_bf16 v[76:79], v[236:239], v[60:63], v[40:43]
	v_mfma_f32_16x16x32_bf16 v[36:39], v[216:219], v[84:87], v[36:39]
	v_mfma_f32_16x16x32_bf16 v[32:35], v[236:239], v[84:87], v[32:35]
	v_mfma_f32_16x16x32_bf16 v[20:23], v[216:219], v[186:189], v[20:23]
	v_mfma_f32_16x16x32_bf16 v[16:19], v[236:239], v[186:189], v[16:19]
	v_mfma_f32_16x16x32_bf16 v[4:7], v[216:219], v[200:203], v[4:7]
	v_mfma_f32_16x16x32_bf16 v[0:3], v[236:239], v[200:203], v[0:3]
	s_add_u32 s56, s56, 0x100
	s_addc_u32 s57, s57, 0
	s_cmp_gt_u32 s58, 41
	s_mov_b64 s[24:25], s[2:3]
	s_barrier
	s_cbranch_scc0 .LBB0_1049
	s_lshl_b32 s2, s55, 8
	v_mov_b32_e32 v186, v193
	v_mov_b32_e32 v196, v192
	s_or_b32 s2, s2, s46
	v_mov_b32_e32 v52, 0
	v_lshl_add_u32 v182, v196, 3, s2
	s_add_i32 s2, s54, -16
	s_lshr_b32 s2, s2, 3
	s_add_i32 s2, s2, 1
	s_cmp_gt_i32 s54, 15
	s_cselect_b32 s8, s2, 0
	s_mul_i32 s96, s8, 0x1800
	s_lshl_b64 s[2:3], s[96:97], 2
	s_add_u32 s2, s41, s2
	v_ashrrev_i32_e32 v183, 31, v182
	s_addc_u32 s3, s42, s3
	v_lshlrev_b64 v[40:41], 2, v[182:183]
	v_lshl_add_u64 v[42:43], s[2:3], 0, v[40:41]
	global_load_dwordx4 v[72:75], v[42:43], off
	s_lshl_b32 s96, s8, 10
	s_lshl_b64 s[2:3], s[96:97], 2
	s_add_u32 s2, s43, s2
	s_addc_u32 s3, s44, s3
	v_lshl_add_u64 v[184:185], s[2:3], 0, v[40:41]
	s_and_b64 vcc, exec, s[4:5]
	v_mov_b32_e32 v60, 0
	v_mov_b32_e32 v61, v52
	v_mov_b32_e32 v62, 0
	v_mov_b32_e32 v63, 0
	s_cbranch_vccnz .LBB0_1052
	global_load_dwordx4 v[60:63], v[184:185], off
